# accumulate pairs of the two 16-MFMA blocks of a super-phase interleaved (consecutive pairs share the A fragment)
# speedup vs baseline: 1.0138x; 1.0055x over previous
.LBB0_296:
	s_ashr_i32 s23, s22, 31
	s_lshl_b64 s[56:57], s[22:23], 21
	s_add_u32 s72, s2, s56
	s_addc_u32 s73, s3, s57
	s_and_b64 s[56:57], s[4:5], exec
	s_cselect_b32 s23, s73, s81
	s_cselect_b32 s56, s72, s80
	s_ashr_i32 s21, s20, 31
	s_lshl_b64 s[60:61], s[20:21], 20
	s_add_u32 s74, s14, s60
	s_addc_u32 s75, s15, s61
	s_and_b64 s[60:61], s[4:5], exec
	s_cselect_b32 s21, s75, s83
	s_cselect_b32 s57, s74, s82
	s_add_u32 s80, s80, 0x100080
	s_addc_u32 s81, s81, 0
	s_add_u32 s60, s82, 0x100
	s_addc_u32 s61, s83, 0
	s_mov_b32 s68, -2
	s_add_u32 s67, s80, 0xfff00080
	s_addc_u32 s69, s81, -1
	s_add_i32 s70, 0, 0x10000
	s_cmp_eq_u32 s68, 28
	s_cselect_b32 s85, s23, s69
	s_cselect_b32 s84, s56, s67
	s_cselect_b32 s83, s21, s61
	s_cselect_b32 s82, s57, s60
	s_add_i32 s67, 0, 0x14000
	v_add_u32_e32 v140, s70, v168
	v_add_u32_e32 v166, s67, v168
	ds_read_b128 v[80:83], v140
	ds_read_b128 v[116:119], v140 offset:1024
	ds_read_b128 v[136:139], v140 offset:2048
	ds_read_b128 v[140:143], v140 offset:3072
	ds_read_b128 v[158:161], v166
	ds_read_b128 v[162:165], v166 offset:1024
	ds_read_b128 v[170:173], v166 offset:2048
	ds_read_b128 v[174:177], v166 offset:3072
	v_lshl_add_u64 v[166:167], s[80:81], 0, v[154:155]
	s_add_i32 m0, s26, 0xc000
	ds_read_b128 v[178:181], v169
	ds_read_b128 v[182:185], v169 offset:1024
	ds_read_b128 v[186:189], v169 offset:2048
	ds_read_b128 v[190:193], v169 offset:3072
	ds_read_b128 v[194:197], v169 offset:4096
	ds_read_b128 v[198:201], v169 offset:5120
	ds_read_b128 v[202:205], v169 offset:6144
	ds_read_b128 v[206:209], v169 offset:7168
	global_load_lds_dwordx4 v[166:167], off
	v_lshl_add_u64 v[166:167], s[80:81], 0, v[156:157]
	s_add_i32 m0, s26, 0xe000
	s_nop 0
	global_load_lds_dwordx4 v[166:167], off
	s_waitcnt vmcnt(8)
	s_waitcnt lgkmcnt(0)
	s_barrier
	s_waitcnt lgkmcnt(0)
	v_mfma_f32_16x16x32_bf16 v[132:135], v[80:83], v[178:181], 0
	v_mfma_f32_16x16x32_bf16 v[132:135], v[116:119], v[182:185], v[132:135]
	v_mfma_f32_16x16x32_bf16 v[124:127], v[158:161], v[178:181], 0
	v_mfma_f32_16x16x32_bf16 v[124:127], v[162:165], v[182:185], v[124:127]
	v_mfma_f32_16x16x32_bf16 v[128:131], v[136:139], v[178:181], 0
	v_mfma_f32_16x16x32_bf16 v[128:131], v[140:143], v[182:185], v[128:131]
	v_mfma_f32_16x16x32_bf16 v[120:123], v[170:173], v[178:181], 0
	v_mfma_f32_16x16x32_bf16 v[120:123], v[174:177], v[182:185], v[120:123]
	v_mfma_f32_16x16x32_bf16 v[112:115], v[80:83], v[186:189], 0
	v_mfma_f32_16x16x32_bf16 v[112:115], v[116:119], v[190:193], v[112:115]
	v_mfma_f32_16x16x32_bf16 v[104:107], v[158:161], v[186:189], 0
	v_mfma_f32_16x16x32_bf16 v[104:107], v[162:165], v[190:193], v[104:107]
	v_mfma_f32_16x16x32_bf16 v[108:111], v[136:139], v[186:189], 0
	v_mfma_f32_16x16x32_bf16 v[108:111], v[140:143], v[190:193], v[108:111]
	v_mfma_f32_16x16x32_bf16 v[100:103], v[170:173], v[186:189], 0
	v_mfma_f32_16x16x32_bf16 v[100:103], v[174:177], v[190:193], v[100:103]
	v_mfma_f32_16x16x32_bf16 v[96:99], v[80:83], v[194:197], 0
	v_mfma_f32_16x16x32_bf16 v[96:99], v[116:119], v[198:201], v[96:99]
	v_mfma_f32_16x16x32_bf16 v[88:91], v[158:161], v[194:197], 0
	v_mfma_f32_16x16x32_bf16 v[88:91], v[162:165], v[198:201], v[88:91]
	v_mfma_f32_16x16x32_bf16 v[92:95], v[136:139], v[194:197], 0
	v_mfma_f32_16x16x32_bf16 v[92:95], v[140:143], v[198:201], v[92:95]
	v_mfma_f32_16x16x32_bf16 v[84:87], v[170:173], v[194:197], 0
	v_mfma_f32_16x16x32_bf16 v[84:87], v[174:177], v[198:201], v[84:87]
	v_mfma_f32_16x16x32_bf16 v[76:79], v[80:83], v[202:205], 0
	v_mfma_f32_16x16x32_bf16 v[76:79], v[116:119], v[206:209], v[76:79]
	v_mfma_f32_16x16x32_bf16 v[68:71], v[158:161], v[202:205], 0
	v_mfma_f32_16x16x32_bf16 v[68:71], v[162:165], v[206:209], v[68:71]
	v_mfma_f32_16x16x32_bf16 v[72:75], v[136:139], v[202:205], 0
	v_mfma_f32_16x16x32_bf16 v[72:75], v[140:143], v[206:209], v[72:75]
	v_mfma_f32_16x16x32_bf16 v[64:67], v[170:173], v[202:205], 0
	v_mfma_f32_16x16x32_bf16 v[64:67], v[174:177], v[206:209], v[64:67]
	s_barrier
	s_add_i32 s69, s70, s24
	v_lshl_add_u64 v[166:167], s[82:83], 0, v[146:147]
	s_mov_b32 m0, s69
	ds_read_b128 v[178:181], v169 offset:16384
	ds_read_b128 v[182:185], v169 offset:17408
	ds_read_b128 v[186:189], v169 offset:18432
	ds_read_b128 v[190:193], v169 offset:19456
	ds_read_b128 v[194:197], v169 offset:20480
	ds_read_b128 v[198:201], v169 offset:21504
	ds_read_b128 v[202:205], v169 offset:22528
	ds_read_b128 v[206:209], v169 offset:23552
	global_load_lds_dwordx4 v[166:167], off
	s_add_i32 m0, s69, 0x2000
	s_add_u32 s70, s82, 0x80000
	v_lshl_add_u64 v[210:211], s[82:83], 0, v[150:151]
	s_addc_u32 s71, s83, 0
	s_add_i32 s67, s67, s24
	global_load_lds_dwordx4 v[210:211], off
	v_lshl_add_u64 v[212:213], s[70:71], 0, v[146:147]
	s_mov_b32 m0, s67
	v_lshl_add_u64 v[214:215], s[84:85], 0, v[148:149]
	global_load_lds_dwordx4 v[212:213], off
	v_lshl_add_u64 v[212:213], s[70:71], 0, v[150:151]
	s_add_i32 m0, s67, 0x2000
	s_nop 0
	global_load_lds_dwordx4 v[212:213], off
	v_lshl_add_u64 v[212:213], s[84:85], 0, v[144:145]
	s_mov_b32 m0, s26
	s_nop 0
	global_load_lds_dwordx4 v[212:213], off
	s_mov_b32 m0, s28
	s_nop 0
	global_load_lds_dwordx4 v[214:215], off
	s_waitcnt vmcnt(8)
	s_waitcnt lgkmcnt(0)
	s_barrier
	s_waitcnt lgkmcnt(0)
	v_mfma_f32_16x16x32_bf16 v[60:63], v[80:83], v[178:181], 0
	v_mfma_f32_16x16x32_bf16 v[60:63], v[116:119], v[182:185], v[60:63]
	v_mfma_f32_16x16x32_bf16 v[52:55], v[158:161], v[178:181], 0
	v_mfma_f32_16x16x32_bf16 v[52:55], v[162:165], v[182:185], v[52:55]
	v_mfma_f32_16x16x32_bf16 v[56:59], v[136:139], v[178:181], 0
	v_mfma_f32_16x16x32_bf16 v[56:59], v[140:143], v[182:185], v[56:59]
	v_mfma_f32_16x16x32_bf16 v[48:51], v[170:173], v[178:181], 0
	v_mfma_f32_16x16x32_bf16 v[48:51], v[174:177], v[182:185], v[48:51]
	v_mfma_f32_16x16x32_bf16 v[44:47], v[80:83], v[186:189], 0
	v_mfma_f32_16x16x32_bf16 v[44:47], v[116:119], v[190:193], v[44:47]
	v_mfma_f32_16x16x32_bf16 v[36:39], v[158:161], v[186:189], 0
	v_mfma_f32_16x16x32_bf16 v[36:39], v[162:165], v[190:193], v[36:39]
	v_mfma_f32_16x16x32_bf16 v[40:43], v[136:139], v[186:189], 0
	v_mfma_f32_16x16x32_bf16 v[40:43], v[140:143], v[190:193], v[40:43]
	v_mfma_f32_16x16x32_bf16 v[32:35], v[170:173], v[186:189], 0
	v_mfma_f32_16x16x32_bf16 v[32:35], v[174:177], v[190:193], v[32:35]
	v_mfma_f32_16x16x32_bf16 v[28:31], v[80:83], v[194:197], 0
	v_mfma_f32_16x16x32_bf16 v[28:31], v[116:119], v[198:201], v[28:31]
	v_mfma_f32_16x16x32_bf16 v[20:23], v[158:161], v[194:197], 0
	v_mfma_f32_16x16x32_bf16 v[20:23], v[162:165], v[198:201], v[20:23]
	v_mfma_f32_16x16x32_bf16 v[24:27], v[136:139], v[194:197], 0
	v_mfma_f32_16x16x32_bf16 v[24:27], v[140:143], v[198:201], v[24:27]
	v_mfma_f32_16x16x32_bf16 v[16:19], v[170:173], v[194:197], 0
	v_mfma_f32_16x16x32_bf16 v[16:19], v[174:177], v[198:201], v[16:19]
	v_mfma_f32_16x16x32_bf16 v[12:15], v[80:83], v[202:205], 0
	v_mfma_f32_16x16x32_bf16 v[12:15], v[116:119], v[206:209], v[12:15]
	v_mfma_f32_16x16x32_bf16 v[4:7], v[158:161], v[202:205], 0
	v_mfma_f32_16x16x32_bf16 v[4:7], v[162:165], v[206:209], v[4:7]
	v_mfma_f32_16x16x32_bf16 v[8:11], v[136:139], v[202:205], 0
	v_mfma_f32_16x16x32_bf16 v[8:11], v[140:143], v[206:209], v[8:11]
	v_mfma_f32_16x16x32_bf16 v[0:3], v[170:173], v[202:205], 0
	v_mfma_f32_16x16x32_bf16 v[0:3], v[174:177], v[206:209], v[0:3]
	s_barrier
	s_add_i32 s67, 0, 0x18000
	s_add_i32 s69, 0, 0x1c000
	v_add_u32_e32 v140, s67, v168
	v_add_u32_e32 v174, s69, v168
	ds_read_b128 v[80:83], v140
	ds_read_b128 v[116:119], v140 offset:1024
	ds_read_b128 v[136:139], v140 offset:2048
	ds_read_b128 v[140:143], v140 offset:3072
	ds_read_b128 v[158:161], v174
	ds_read_b128 v[162:165], v174 offset:1024
	ds_read_b128 v[170:173], v174 offset:2048
	ds_read_b128 v[174:177], v174 offset:3072
	s_add_u32 s70, s84, 0x100000
	s_addc_u32 s71, s85, 0
	s_mov_b32 m0, s29
	v_lshl_add_u64 v[218:219], s[70:71], 0, v[144:145]
	ds_read_b128 v[178:181], v169 offset:32768
	ds_read_b128 v[182:185], v169 offset:33792
	ds_read_b128 v[186:189], v169 offset:34816
	ds_read_b128 v[190:193], v169 offset:35840
	ds_read_b128 v[194:197], v169 offset:36864
	ds_read_b128 v[198:201], v169 offset:37888
	ds_read_b128 v[202:205], v169 offset:38912
	ds_read_b128 v[206:209], v169 offset:39936
	global_load_lds_dwordx4 v[218:219], off
	v_lshl_add_u64 v[218:219], s[70:71], 0, v[148:149]
	s_mov_b32 m0, s34
	s_nop 0
	global_load_lds_dwordx4 v[218:219], off
	s_waitcnt vmcnt(8)
	s_waitcnt lgkmcnt(0)
	s_barrier
	s_waitcnt lgkmcnt(0)
	v_mfma_f32_16x16x32_bf16 v[132:135], v[80:83], v[178:181], v[132:135]
	v_mfma_f32_16x16x32_bf16 v[132:135], v[116:119], v[182:185], v[132:135]
	v_mfma_f32_16x16x32_bf16 v[124:127], v[158:161], v[178:181], v[124:127]
	v_mfma_f32_16x16x32_bf16 v[124:127], v[162:165], v[182:185], v[124:127]
	v_mfma_f32_16x16x32_bf16 v[128:131], v[136:139], v[178:181], v[128:131]
	v_mfma_f32_16x16x32_bf16 v[128:131], v[140:143], v[182:185], v[128:131]
	v_mfma_f32_16x16x32_bf16 v[120:123], v[170:173], v[178:181], v[120:123]
	v_mfma_f32_16x16x32_bf16 v[120:123], v[174:177], v[182:185], v[120:123]
	v_mfma_f32_16x16x32_bf16 v[112:115], v[80:83], v[186:189], v[112:115]
	v_mfma_f32_16x16x32_bf16 v[112:115], v[116:119], v[190:193], v[112:115]
	v_mfma_f32_16x16x32_bf16 v[104:107], v[158:161], v[186:189], v[104:107]
	v_mfma_f32_16x16x32_bf16 v[104:107], v[162:165], v[190:193], v[104:107]
	v_mfma_f32_16x16x32_bf16 v[108:111], v[136:139], v[186:189], v[108:111]
	v_mfma_f32_16x16x32_bf16 v[108:111], v[140:143], v[190:193], v[108:111]
	v_mfma_f32_16x16x32_bf16 v[100:103], v[170:173], v[186:189], v[100:103]
	v_mfma_f32_16x16x32_bf16 v[100:103], v[174:177], v[190:193], v[100:103]
	v_mfma_f32_16x16x32_bf16 v[96:99], v[80:83], v[194:197], v[96:99]
	v_mfma_f32_16x16x32_bf16 v[96:99], v[116:119], v[198:201], v[96:99]
	v_mfma_f32_16x16x32_bf16 v[88:91], v[158:161], v[194:197], v[88:91]
	v_mfma_f32_16x16x32_bf16 v[88:91], v[162:165], v[198:201], v[88:91]
	v_mfma_f32_16x16x32_bf16 v[92:95], v[136:139], v[194:197], v[92:95]
	v_mfma_f32_16x16x32_bf16 v[92:95], v[140:143], v[198:201], v[92:95]
	v_mfma_f32_16x16x32_bf16 v[84:87], v[170:173], v[194:197], v[84:87]
	v_mfma_f32_16x16x32_bf16 v[84:87], v[174:177], v[198:201], v[84:87]
	v_mfma_f32_16x16x32_bf16 v[76:79], v[80:83], v[202:205], v[76:79]
	v_mfma_f32_16x16x32_bf16 v[76:79], v[116:119], v[206:209], v[76:79]
	v_mfma_f32_16x16x32_bf16 v[68:71], v[158:161], v[202:205], v[68:71]
	v_mfma_f32_16x16x32_bf16 v[68:71], v[162:165], v[206:209], v[68:71]
	v_mfma_f32_16x16x32_bf16 v[72:75], v[136:139], v[202:205], v[72:75]
	v_mfma_f32_16x16x32_bf16 v[72:75], v[140:143], v[206:209], v[72:75]
	v_mfma_f32_16x16x32_bf16 v[64:67], v[170:173], v[202:205], v[64:67]
	v_mfma_f32_16x16x32_bf16 v[64:67], v[174:177], v[206:209], v[64:67]
	s_barrier
	s_add_i32 s67, s67, s24
	v_lshl_add_u64 v[166:167], v[166:167], 0, s[30:31]
	s_mov_b32 m0, s67
	ds_read_b128 v[178:181], v169 offset:49152
	ds_read_b128 v[182:185], v169 offset:50176
	ds_read_b128 v[186:189], v169 offset:51200
	ds_read_b128 v[190:193], v169 offset:52224
	ds_read_b128 v[194:197], v169 offset:53248
	ds_read_b128 v[198:201], v169 offset:54272
	ds_read_b128 v[202:205], v169 offset:55296
	ds_read_b128 v[206:209], v169 offset:56320
	global_load_lds_dwordx4 v[166:167], off
	s_add_i32 m0, s67, 0x2000
	s_add_u32 s70, s82, 0x80080
	v_lshl_add_u64 v[166:167], v[210:211], 0, s[30:31]
	s_addc_u32 s71, s83, 0
	s_add_i32 s67, s69, s24
	global_load_lds_dwordx4 v[166:167], off
	v_lshl_add_u64 v[166:167], s[70:71], 0, v[146:147]
	s_mov_b32 m0, s67
	s_nop 0
	global_load_lds_dwordx4 v[166:167], off
	v_lshl_add_u64 v[166:167], s[70:71], 0, v[150:151]
	s_add_i32 m0, s67, 0x2000
	s_nop 0
	global_load_lds_dwordx4 v[166:167], off
	v_lshl_add_u64 v[166:167], v[212:213], 0, s[30:31]
	s_mov_b32 m0, s39
	s_nop 0
	global_load_lds_dwordx4 v[166:167], off
	v_lshl_add_u64 v[166:167], v[214:215], 0, s[30:31]
	s_mov_b32 m0, s40
	s_nop 0
	global_load_lds_dwordx4 v[166:167], off
	s_waitcnt vmcnt(8)
	s_waitcnt lgkmcnt(0)
	s_barrier
	s_waitcnt lgkmcnt(0)
	v_mfma_f32_16x16x32_bf16 v[60:63], v[80:83], v[178:181], v[60:63]
	v_mfma_f32_16x16x32_bf16 v[60:63], v[116:119], v[182:185], v[60:63]
	v_mfma_f32_16x16x32_bf16 v[52:55], v[158:161], v[178:181], v[52:55]
	v_mfma_f32_16x16x32_bf16 v[52:55], v[162:165], v[182:185], v[52:55]
	v_mfma_f32_16x16x32_bf16 v[56:59], v[136:139], v[178:181], v[56:59]
	v_mfma_f32_16x16x32_bf16 v[56:59], v[140:143], v[182:185], v[56:59]
	v_mfma_f32_16x16x32_bf16 v[48:51], v[170:173], v[178:181], v[48:51]
	v_mfma_f32_16x16x32_bf16 v[48:51], v[174:177], v[182:185], v[48:51]
	v_mfma_f32_16x16x32_bf16 v[44:47], v[80:83], v[186:189], v[44:47]
	v_mfma_f32_16x16x32_bf16 v[44:47], v[116:119], v[190:193], v[44:47]
	v_mfma_f32_16x16x32_bf16 v[36:39], v[158:161], v[186:189], v[36:39]
	v_mfma_f32_16x16x32_bf16 v[36:39], v[162:165], v[190:193], v[36:39]
	v_mfma_f32_16x16x32_bf16 v[40:43], v[136:139], v[186:189], v[40:43]
	v_mfma_f32_16x16x32_bf16 v[40:43], v[140:143], v[190:193], v[40:43]
	v_mfma_f32_16x16x32_bf16 v[32:35], v[170:173], v[186:189], v[32:35]
	v_mfma_f32_16x16x32_bf16 v[32:35], v[174:177], v[190:193], v[32:35]
	v_mfma_f32_16x16x32_bf16 v[28:31], v[80:83], v[194:197], v[28:31]
	v_mfma_f32_16x16x32_bf16 v[28:31], v[116:119], v[198:201], v[28:31]
	v_mfma_f32_16x16x32_bf16 v[20:23], v[158:161], v[194:197], v[20:23]
	v_mfma_f32_16x16x32_bf16 v[20:23], v[162:165], v[198:201], v[20:23]
	v_mfma_f32_16x16x32_bf16 v[24:27], v[136:139], v[194:197], v[24:27]
	v_mfma_f32_16x16x32_bf16 v[24:27], v[140:143], v[198:201], v[24:27]
	v_mfma_f32_16x16x32_bf16 v[16:19], v[170:173], v[194:197], v[16:19]
	v_mfma_f32_16x16x32_bf16 v[16:19], v[174:177], v[198:201], v[16:19]
	v_mfma_f32_16x16x32_bf16 v[12:15], v[80:83], v[202:205], v[12:15]
	v_mfma_f32_16x16x32_bf16 v[12:15], v[116:119], v[206:209], v[12:15]
	v_mfma_f32_16x16x32_bf16 v[4:7], v[158:161], v[202:205], v[4:7]
	v_mfma_f32_16x16x32_bf16 v[4:7], v[162:165], v[206:209], v[4:7]
	v_mfma_f32_16x16x32_bf16 v[8:11], v[136:139], v[202:205], v[8:11]
	v_mfma_f32_16x16x32_bf16 v[8:11], v[140:143], v[206:209], v[8:11]
	v_mfma_f32_16x16x32_bf16 v[0:3], v[170:173], v[202:205], v[0:3]
	v_mfma_f32_16x16x32_bf16 v[0:3], v[174:177], v[206:209], v[0:3]
	s_barrier
	s_add_i32 s68, s68, 2
	s_add_u32 s80, s80, 0x100
	s_addc_u32 s81, s81, 0
	s_add_u32 s60, s60, 0x100
	s_addc_u32 s61, s61, 0
.LBB0_297:
	s_add_u32 s67, s80, 0xfff00080
	s_addc_u32 s69, s81, -1
	s_add_i32 s70, 0, 0x10000
	s_cmp_eq_u32 s68, 28
	s_cselect_b32 s85, s23, s69
	s_cselect_b32 s84, s56, s67
	s_cselect_b32 s83, s21, s61
	s_cselect_b32 s82, s57, s60
	s_add_i32 s67, 0, 0x14000
	v_add_u32_e32 v140, s70, v168
	v_add_u32_e32 v166, s67, v168
	ds_read_b128 v[80:83], v140
	ds_read_b128 v[116:119], v140 offset:1024
	ds_read_b128 v[136:139], v140 offset:2048
	ds_read_b128 v[140:143], v140 offset:3072
	ds_read_b128 v[158:161], v166
	ds_read_b128 v[162:165], v166 offset:1024
	ds_read_b128 v[170:173], v166 offset:2048
	ds_read_b128 v[174:177], v166 offset:3072
	v_lshl_add_u64 v[166:167], s[80:81], 0, v[154:155]
	s_add_i32 m0, s26, 0xc000
	ds_read_b128 v[178:181], v169
	ds_read_b128 v[182:185], v169 offset:1024
	ds_read_b128 v[186:189], v169 offset:2048
	ds_read_b128 v[190:193], v169 offset:3072
	ds_read_b128 v[194:197], v169 offset:4096
	ds_read_b128 v[198:201], v169 offset:5120
	ds_read_b128 v[202:205], v169 offset:6144
	ds_read_b128 v[206:209], v169 offset:7168
	global_load_lds_dwordx4 v[166:167], off
	v_lshl_add_u64 v[166:167], s[80:81], 0, v[156:157]
	s_add_i32 m0, s26, 0xe000
	s_nop 0
	global_load_lds_dwordx4 v[166:167], off
	s_waitcnt vmcnt(8)
	s_waitcnt lgkmcnt(0)
	s_barrier
	s_waitcnt lgkmcnt(0)
	v_mfma_f32_16x16x32_bf16 v[132:135], v[80:83], v[178:181], v[132:135]
	v_mfma_f32_16x16x32_bf16 v[132:135], v[116:119], v[182:185], v[132:135]
	v_mfma_f32_16x16x32_bf16 v[124:127], v[158:161], v[178:181], v[124:127]
	v_mfma_f32_16x16x32_bf16 v[124:127], v[162:165], v[182:185], v[124:127]
	v_mfma_f32_16x16x32_bf16 v[128:131], v[136:139], v[178:181], v[128:131]
	v_mfma_f32_16x16x32_bf16 v[128:131], v[140:143], v[182:185], v[128:131]
	v_mfma_f32_16x16x32_bf16 v[120:123], v[170:173], v[178:181], v[120:123]
	v_mfma_f32_16x16x32_bf16 v[120:123], v[174:177], v[182:185], v[120:123]
	v_mfma_f32_16x16x32_bf16 v[112:115], v[80:83], v[186:189], v[112:115]
	v_mfma_f32_16x16x32_bf16 v[112:115], v[116:119], v[190:193], v[112:115]
	v_mfma_f32_16x16x32_bf16 v[104:107], v[158:161], v[186:189], v[104:107]
	v_mfma_f32_16x16x32_bf16 v[104:107], v[162:165], v[190:193], v[104:107]
	v_mfma_f32_16x16x32_bf16 v[108:111], v[136:139], v[186:189], v[108:111]
	v_mfma_f32_16x16x32_bf16 v[108:111], v[140:143], v[190:193], v[108:111]
	v_mfma_f32_16x16x32_bf16 v[100:103], v[170:173], v[186:189], v[100:103]
	v_mfma_f32_16x16x32_bf16 v[100:103], v[174:177], v[190:193], v[100:103]
	v_mfma_f32_16x16x32_bf16 v[96:99], v[80:83], v[194:197], v[96:99]
	v_mfma_f32_16x16x32_bf16 v[96:99], v[116:119], v[198:201], v[96:99]
	v_mfma_f32_16x16x32_bf16 v[88:91], v[158:161], v[194:197], v[88:91]
	v_mfma_f32_16x16x32_bf16 v[88:91], v[162:165], v[198:201], v[88:91]
	v_mfma_f32_16x16x32_bf16 v[92:95], v[136:139], v[194:197], v[92:95]
	v_mfma_f32_16x16x32_bf16 v[92:95], v[140:143], v[198:201], v[92:95]
	v_mfma_f32_16x16x32_bf16 v[84:87], v[170:173], v[194:197], v[84:87]
	v_mfma_f32_16x16x32_bf16 v[84:87], v[174:177], v[198:201], v[84:87]
	v_mfma_f32_16x16x32_bf16 v[76:79], v[80:83], v[202:205], v[76:79]
	v_mfma_f32_16x16x32_bf16 v[76:79], v[116:119], v[206:209], v[76:79]
	v_mfma_f32_16x16x32_bf16 v[68:71], v[158:161], v[202:205], v[68:71]
	v_mfma_f32_16x16x32_bf16 v[68:71], v[162:165], v[206:209], v[68:71]
	v_mfma_f32_16x16x32_bf16 v[72:75], v[136:139], v[202:205], v[72:75]
	v_mfma_f32_16x16x32_bf16 v[72:75], v[140:143], v[206:209], v[72:75]
	v_mfma_f32_16x16x32_bf16 v[64:67], v[170:173], v[202:205], v[64:67]
	v_mfma_f32_16x16x32_bf16 v[64:67], v[174:177], v[206:209], v[64:67]
	s_barrier
	s_add_i32 s69, s70, s24
	v_lshl_add_u64 v[166:167], s[82:83], 0, v[146:147]
	s_mov_b32 m0, s69
	ds_read_b128 v[178:181], v169 offset:16384
	ds_read_b128 v[182:185], v169 offset:17408
	ds_read_b128 v[186:189], v169 offset:18432
	ds_read_b128 v[190:193], v169 offset:19456
	ds_read_b128 v[194:197], v169 offset:20480
	ds_read_b128 v[198:201], v169 offset:21504
	ds_read_b128 v[202:205], v169 offset:22528
	ds_read_b128 v[206:209], v169 offset:23552
	global_load_lds_dwordx4 v[166:167], off
	s_add_i32 m0, s69, 0x2000
	s_add_u32 s70, s82, 0x80000
	v_lshl_add_u64 v[210:211], s[82:83], 0, v[150:151]
	s_addc_u32 s71, s83, 0
	s_add_i32 s67, s67, s24
	global_load_lds_dwordx4 v[210:211], off
	v_lshl_add_u64 v[212:213], s[70:71], 0, v[146:147]
	s_mov_b32 m0, s67
	v_lshl_add_u64 v[214:215], s[84:85], 0, v[148:149]
	global_load_lds_dwordx4 v[212:213], off
	v_lshl_add_u64 v[212:213], s[70:71], 0, v[150:151]
	s_add_i32 m0, s67, 0x2000
	s_nop 0
	global_load_lds_dwordx4 v[212:213], off
	v_lshl_add_u64 v[212:213], s[84:85], 0, v[144:145]
	s_mov_b32 m0, s26
	s_nop 0
	global_load_lds_dwordx4 v[212:213], off
	s_mov_b32 m0, s28
	s_nop 0
	global_load_lds_dwordx4 v[214:215], off
	s_waitcnt vmcnt(8)
	s_waitcnt lgkmcnt(0)
	s_barrier
	s_waitcnt lgkmcnt(0)
	v_mfma_f32_16x16x32_bf16 v[60:63], v[80:83], v[178:181], v[60:63]
	v_mfma_f32_16x16x32_bf16 v[60:63], v[116:119], v[182:185], v[60:63]
	v_mfma_f32_16x16x32_bf16 v[52:55], v[158:161], v[178:181], v[52:55]
	v_mfma_f32_16x16x32_bf16 v[52:55], v[162:165], v[182:185], v[52:55]
	v_mfma_f32_16x16x32_bf16 v[56:59], v[136:139], v[178:181], v[56:59]
	v_mfma_f32_16x16x32_bf16 v[56:59], v[140:143], v[182:185], v[56:59]
	v_mfma_f32_16x16x32_bf16 v[48:51], v[170:173], v[178:181], v[48:51]
	v_mfma_f32_16x16x32_bf16 v[48:51], v[174:177], v[182:185], v[48:51]
	v_mfma_f32_16x16x32_bf16 v[44:47], v[80:83], v[186:189], v[44:47]
	v_mfma_f32_16x16x32_bf16 v[44:47], v[116:119], v[190:193], v[44:47]
	v_mfma_f32_16x16x32_bf16 v[36:39], v[158:161], v[186:189], v[36:39]
	v_mfma_f32_16x16x32_bf16 v[36:39], v[162:165], v[190:193], v[36:39]
	v_mfma_f32_16x16x32_bf16 v[40:43], v[136:139], v[186:189], v[40:43]
	v_mfma_f32_16x16x32_bf16 v[40:43], v[140:143], v[190:193], v[40:43]
	v_mfma_f32_16x16x32_bf16 v[32:35], v[170:173], v[186:189], v[32:35]
	v_mfma_f32_16x16x32_bf16 v[32:35], v[174:177], v[190:193], v[32:35]
	v_mfma_f32_16x16x32_bf16 v[28:31], v[80:83], v[194:197], v[28:31]
	v_mfma_f32_16x16x32_bf16 v[28:31], v[116:119], v[198:201], v[28:31]
	v_mfma_f32_16x16x32_bf16 v[20:23], v[158:161], v[194:197], v[20:23]
	v_mfma_f32_16x16x32_bf16 v[20:23], v[162:165], v[198:201], v[20:23]
	v_mfma_f32_16x16x32_bf16 v[24:27], v[136:139], v[194:197], v[24:27]
	v_mfma_f32_16x16x32_bf16 v[24:27], v[140:143], v[198:201], v[24:27]
	v_mfma_f32_16x16x32_bf16 v[16:19], v[170:173], v[194:197], v[16:19]
	v_mfma_f32_16x16x32_bf16 v[16:19], v[174:177], v[198:201], v[16:19]
	v_mfma_f32_16x16x32_bf16 v[12:15], v[80:83], v[202:205], v[12:15]
	v_mfma_f32_16x16x32_bf16 v[12:15], v[116:119], v[206:209], v[12:15]
	v_mfma_f32_16x16x32_bf16 v[4:7], v[158:161], v[202:205], v[4:7]
	v_mfma_f32_16x16x32_bf16 v[4:7], v[162:165], v[206:209], v[4:7]
	v_mfma_f32_16x16x32_bf16 v[8:11], v[136:139], v[202:205], v[8:11]
	v_mfma_f32_16x16x32_bf16 v[8:11], v[140:143], v[206:209], v[8:11]
	v_mfma_f32_16x16x32_bf16 v[0:3], v[170:173], v[202:205], v[0:3]
	v_mfma_f32_16x16x32_bf16 v[0:3], v[174:177], v[206:209], v[0:3]
	s_barrier
	s_add_i32 s67, 0, 0x18000
	s_add_i32 s69, 0, 0x1c000
	v_add_u32_e32 v140, s67, v168
	v_add_u32_e32 v174, s69, v168
	ds_read_b128 v[80:83], v140
	ds_read_b128 v[116:119], v140 offset:1024
	ds_read_b128 v[136:139], v140 offset:2048
	ds_read_b128 v[140:143], v140 offset:3072
	ds_read_b128 v[158:161], v174
	ds_read_b128 v[162:165], v174 offset:1024
	ds_read_b128 v[170:173], v174 offset:2048
	ds_read_b128 v[174:177], v174 offset:3072
	s_add_u32 s70, s84, 0x100000
	s_addc_u32 s71, s85, 0
	s_mov_b32 m0, s29
	v_lshl_add_u64 v[218:219], s[70:71], 0, v[144:145]
	ds_read_b128 v[178:181], v169 offset:32768
	ds_read_b128 v[182:185], v169 offset:33792
	ds_read_b128 v[186:189], v169 offset:34816
	ds_read_b128 v[190:193], v169 offset:35840
	ds_read_b128 v[194:197], v169 offset:36864
	ds_read_b128 v[198:201], v169 offset:37888
	ds_read_b128 v[202:205], v169 offset:38912
	ds_read_b128 v[206:209], v169 offset:39936
	global_load_lds_dwordx4 v[218:219], off
	v_lshl_add_u64 v[218:219], s[70:71], 0, v[148:149]
	s_mov_b32 m0, s34
	s_nop 0
	global_load_lds_dwordx4 v[218:219], off
	s_waitcnt vmcnt(8)
	s_waitcnt lgkmcnt(0)
	s_barrier
	s_waitcnt lgkmcnt(0)
	v_mfma_f32_16x16x32_bf16 v[132:135], v[80:83], v[178:181], v[132:135]
	v_mfma_f32_16x16x32_bf16 v[132:135], v[116:119], v[182:185], v[132:135]
	v_mfma_f32_16x16x32_bf16 v[124:127], v[158:161], v[178:181], v[124:127]
	v_mfma_f32_16x16x32_bf16 v[124:127], v[162:165], v[182:185], v[124:127]
	v_mfma_f32_16x16x32_bf16 v[128:131], v[136:139], v[178:181], v[128:131]
	v_mfma_f32_16x16x32_bf16 v[128:131], v[140:143], v[182:185], v[128:131]
	v_mfma_f32_16x16x32_bf16 v[120:123], v[170:173], v[178:181], v[120:123]
	v_mfma_f32_16x16x32_bf16 v[120:123], v[174:177], v[182:185], v[120:123]
	v_mfma_f32_16x16x32_bf16 v[112:115], v[80:83], v[186:189], v[112:115]
	v_mfma_f32_16x16x32_bf16 v[112:115], v[116:119], v[190:193], v[112:115]
	v_mfma_f32_16x16x32_bf16 v[104:107], v[158:161], v[186:189], v[104:107]
	v_mfma_f32_16x16x32_bf16 v[104:107], v[162:165], v[190:193], v[104:107]
	v_mfma_f32_16x16x32_bf16 v[108:111], v[136:139], v[186:189], v[108:111]
	v_mfma_f32_16x16x32_bf16 v[108:111], v[140:143], v[190:193], v[108:111]
	v_mfma_f32_16x16x32_bf16 v[100:103], v[170:173], v[186:189], v[100:103]
	v_mfma_f32_16x16x32_bf16 v[100:103], v[174:177], v[190:193], v[100:103]
	v_mfma_f32_16x16x32_bf16 v[96:99], v[80:83], v[194:197], v[96:99]
	v_mfma_f32_16x16x32_bf16 v[96:99], v[116:119], v[198:201], v[96:99]
	v_mfma_f32_16x16x32_bf16 v[88:91], v[158:161], v[194:197], v[88:91]
	v_mfma_f32_16x16x32_bf16 v[88:91], v[162:165], v[198:201], v[88:91]
	v_mfma_f32_16x16x32_bf16 v[92:95], v[136:139], v[194:197], v[92:95]
	v_mfma_f32_16x16x32_bf16 v[92:95], v[140:143], v[198:201], v[92:95]
	v_mfma_f32_16x16x32_bf16 v[84:87], v[170:173], v[194:197], v[84:87]
	v_mfma_f32_16x16x32_bf16 v[84:87], v[174:177], v[198:201], v[84:87]
	v_mfma_f32_16x16x32_bf16 v[76:79], v[80:83], v[202:205], v[76:79]
	v_mfma_f32_16x16x32_bf16 v[76:79], v[116:119], v[206:209], v[76:79]
	v_mfma_f32_16x16x32_bf16 v[68:71], v[158:161], v[202:205], v[68:71]
	v_mfma_f32_16x16x32_bf16 v[68:71], v[162:165], v[206:209], v[68:71]
	v_mfma_f32_16x16x32_bf16 v[72:75], v[136:139], v[202:205], v[72:75]
	v_mfma_f32_16x16x32_bf16 v[72:75], v[140:143], v[206:209], v[72:75]
	v_mfma_f32_16x16x32_bf16 v[64:67], v[170:173], v[202:205], v[64:67]
	v_mfma_f32_16x16x32_bf16 v[64:67], v[174:177], v[206:209], v[64:67]
	s_barrier
	s_add_i32 s67, s67, s24
	v_lshl_add_u64 v[166:167], v[166:167], 0, s[30:31]
	s_mov_b32 m0, s67
	ds_read_b128 v[178:181], v169 offset:49152
	ds_read_b128 v[182:185], v169 offset:50176
	ds_read_b128 v[186:189], v169 offset:51200
	ds_read_b128 v[190:193], v169 offset:52224
	ds_read_b128 v[194:197], v169 offset:53248
	ds_read_b128 v[198:201], v169 offset:54272
	ds_read_b128 v[202:205], v169 offset:55296
	ds_read_b128 v[206:209], v169 offset:56320
	global_load_lds_dwordx4 v[166:167], off
	s_add_i32 m0, s67, 0x2000
	s_add_u32 s70, s82, 0x80080
	v_lshl_add_u64 v[166:167], v[210:211], 0, s[30:31]
	s_addc_u32 s71, s83, 0
	s_add_i32 s67, s69, s24
	global_load_lds_dwordx4 v[166:167], off
	v_lshl_add_u64 v[166:167], s[70:71], 0, v[146:147]
	s_mov_b32 m0, s67
	s_nop 0
	global_load_lds_dwordx4 v[166:167], off
	v_lshl_add_u64 v[166:167], s[70:71], 0, v[150:151]
	s_add_i32 m0, s67, 0x2000
	s_nop 0
	global_load_lds_dwordx4 v[166:167], off
	v_lshl_add_u64 v[166:167], v[212:213], 0, s[30:31]
	s_mov_b32 m0, s39
	s_nop 0
	global_load_lds_dwordx4 v[166:167], off
	v_lshl_add_u64 v[166:167], v[214:215], 0, s[30:31]
	s_mov_b32 m0, s40
	s_nop 0
	global_load_lds_dwordx4 v[166:167], off
	s_waitcnt vmcnt(8)
	s_waitcnt lgkmcnt(0)
	s_barrier
	s_waitcnt lgkmcnt(0)
	v_mfma_f32_16x16x32_bf16 v[60:63], v[80:83], v[178:181], v[60:63]
	v_mfma_f32_16x16x32_bf16 v[60:63], v[116:119], v[182:185], v[60:63]
	v_mfma_f32_16x16x32_bf16 v[52:55], v[158:161], v[178:181], v[52:55]
	v_mfma_f32_16x16x32_bf16 v[52:55], v[162:165], v[182:185], v[52:55]
	v_mfma_f32_16x16x32_bf16 v[56:59], v[136:139], v[178:181], v[56:59]
	v_mfma_f32_16x16x32_bf16 v[56:59], v[140:143], v[182:185], v[56:59]
	v_mfma_f32_16x16x32_bf16 v[48:51], v[170:173], v[178:181], v[48:51]
	v_mfma_f32_16x16x32_bf16 v[48:51], v[174:177], v[182:185], v[48:51]
	v_mfma_f32_16x16x32_bf16 v[44:47], v[80:83], v[186:189], v[44:47]
	v_mfma_f32_16x16x32_bf16 v[44:47], v[116:119], v[190:193], v[44:47]
	v_mfma_f32_16x16x32_bf16 v[36:39], v[158:161], v[186:189], v[36:39]
	v_mfma_f32_16x16x32_bf16 v[36:39], v[162:165], v[190:193], v[36:39]
	v_mfma_f32_16x16x32_bf16 v[40:43], v[136:139], v[186:189], v[40:43]
	v_mfma_f32_16x16x32_bf16 v[40:43], v[140:143], v[190:193], v[40:43]
	v_mfma_f32_16x16x32_bf16 v[32:35], v[170:173], v[186:189], v[32:35]
	v_mfma_f32_16x16x32_bf16 v[32:35], v[174:177], v[190:193], v[32:35]
	v_mfma_f32_16x16x32_bf16 v[28:31], v[80:83], v[194:197], v[28:31]
	v_mfma_f32_16x16x32_bf16 v[28:31], v[116:119], v[198:201], v[28:31]
	v_mfma_f32_16x16x32_bf16 v[20:23], v[158:161], v[194:197], v[20:23]
	v_mfma_f32_16x16x32_bf16 v[20:23], v[162:165], v[198:201], v[20:23]
	v_mfma_f32_16x16x32_bf16 v[24:27], v[136:139], v[194:197], v[24:27]
	v_mfma_f32_16x16x32_bf16 v[24:27], v[140:143], v[198:201], v[24:27]
	v_mfma_f32_16x16x32_bf16 v[16:19], v[170:173], v[194:197], v[16:19]
	v_mfma_f32_16x16x32_bf16 v[16:19], v[174:177], v[198:201], v[16:19]
	v_mfma_f32_16x16x32_bf16 v[12:15], v[80:83], v[202:205], v[12:15]
	v_mfma_f32_16x16x32_bf16 v[12:15], v[116:119], v[206:209], v[12:15]
	v_mfma_f32_16x16x32_bf16 v[4:7], v[158:161], v[202:205], v[4:7]
	v_mfma_f32_16x16x32_bf16 v[4:7], v[162:165], v[206:209], v[4:7]
	v_mfma_f32_16x16x32_bf16 v[8:11], v[136:139], v[202:205], v[8:11]
	v_mfma_f32_16x16x32_bf16 v[8:11], v[140:143], v[206:209], v[8:11]
	v_mfma_f32_16x16x32_bf16 v[0:3], v[170:173], v[202:205], v[0:3]
	v_mfma_f32_16x16x32_bf16 v[0:3], v[174:177], v[206:209], v[0:3]
	s_barrier
	s_add_i32 s68, s68, 2
	s_add_u32 s80, s80, 0x100
	s_addc_u32 s81, s81, 0
	s_add_u32 s60, s60, 0x100
	s_addc_u32 s61, s61, 0
	s_cmp_gt_u32 s68, 29
	s_cbranch_scc0 .LBB0_297
	s_and_b64 vcc, exec, s[18:19]
	s_cbranch_vccz .LBB0_300
	s_barrier

.LBB0_384:
	s_ashr_i32 s73, s72, 31
	s_lshl_b64 s[74:75], s[72:73], 20
	s_add_u32 s74, s2, s74
	s_addc_u32 s75, s3, s75
	s_and_b64 s[76:77], s[4:5], exec
	s_cselect_b32 s73, s75, s81
	s_cselect_b32 s79, s74, s80
	s_ashr_i32 s23, s22, 31
	s_lshl_b64 s[76:77], s[22:23], 20
	s_add_u32 s76, s14, s76
	s_addc_u32 s77, s15, s77
	s_and_b64 s[84:85], s[4:5], exec
	s_cselect_b32 s23, s77, s83
	s_cselect_b32 s86, s76, s82
	s_add_u32 s80, s80, 0x80080
	s_addc_u32 s81, s81, 0
	s_add_u32 s87, s82, 0x100
	s_addc_u32 s88, s83, 0
	s_mov_b32 s89, -2
	s_add_u32 s67, s80, 0xfff80080
	s_addc_u32 s82, s81, -1
	s_add_i32 s90, 0, 0x10000
	s_cmp_eq_u32 s89, 28
	s_cselect_b32 s85, s73, s82
	s_cselect_b32 s84, s79, s67
	s_cselect_b32 s83, s23, s88
	s_cselect_b32 s82, s86, s87
	s_add_i32 s67, 0, 0x14000
	v_add_u32_e32 v140, s90, v186
	v_add_u32_e32 v156, s67, v186
	ds_read_b128 v[128:131], v140
	ds_read_b128 v[132:135], v140 offset:1024
	ds_read_b128 v[136:139], v140 offset:2048
	ds_read_b128 v[140:143], v140 offset:3072
	ds_read_b128 v[144:147], v156
	ds_read_b128 v[148:151], v156 offset:1024
	ds_read_b128 v[152:155], v156 offset:2048
	ds_read_b128 v[156:159], v156 offset:3072
	v_lshl_add_u64 v[208:209], s[80:81], 0, v[178:179]
	s_add_i32 m0, s29, 0xc000
	ds_read_b128 v[160:163], v187
	ds_read_b128 v[164:167], v187 offset:1024
	ds_read_b128 v[182:185], v187 offset:2048
	ds_read_b128 v[188:191], v187 offset:3072
	ds_read_b128 v[192:195], v187 offset:4096
	ds_read_b128 v[196:199], v187 offset:5120
	ds_read_b128 v[200:203], v187 offset:6144
	ds_read_b128 v[204:207], v187 offset:7168
	global_load_lds_dwordx4 v[208:209], off
	v_lshl_add_u64 v[208:209], s[80:81], 0, v[180:181]
	s_add_i32 m0, s29, 0xe000
	s_nop 0
	global_load_lds_dwordx4 v[208:209], off
	s_waitcnt vmcnt(8)
	s_waitcnt lgkmcnt(0)
	s_barrier
	s_waitcnt lgkmcnt(0)
	v_mfma_f32_16x16x32_bf16 v[124:127], v[128:131], v[160:163], 0
	v_mfma_f32_16x16x32_bf16 v[124:127], v[132:135], v[164:167], v[124:127]
	v_mfma_f32_16x16x32_bf16 v[116:119], v[144:147], v[160:163], 0
	v_mfma_f32_16x16x32_bf16 v[116:119], v[148:151], v[164:167], v[116:119]
	v_mfma_f32_16x16x32_bf16 v[120:123], v[136:139], v[160:163], 0
	v_mfma_f32_16x16x32_bf16 v[120:123], v[140:143], v[164:167], v[120:123]
	v_mfma_f32_16x16x32_bf16 v[112:115], v[152:155], v[160:163], 0
	v_mfma_f32_16x16x32_bf16 v[112:115], v[156:159], v[164:167], v[112:115]
	v_mfma_f32_16x16x32_bf16 v[108:111], v[128:131], v[182:185], 0
	v_mfma_f32_16x16x32_bf16 v[108:111], v[132:135], v[188:191], v[108:111]
	v_mfma_f32_16x16x32_bf16 v[100:103], v[144:147], v[182:185], 0
	v_mfma_f32_16x16x32_bf16 v[100:103], v[148:151], v[188:191], v[100:103]
	v_mfma_f32_16x16x32_bf16 v[104:107], v[136:139], v[182:185], 0
	v_mfma_f32_16x16x32_bf16 v[104:107], v[140:143], v[188:191], v[104:107]
	v_mfma_f32_16x16x32_bf16 v[96:99], v[152:155], v[182:185], 0
	v_mfma_f32_16x16x32_bf16 v[96:99], v[156:159], v[188:191], v[96:99]
	v_mfma_f32_16x16x32_bf16 v[92:95], v[128:131], v[192:195], 0
	v_mfma_f32_16x16x32_bf16 v[92:95], v[132:135], v[196:199], v[92:95]
	v_mfma_f32_16x16x32_bf16 v[84:87], v[144:147], v[192:195], 0
	v_mfma_f32_16x16x32_bf16 v[84:87], v[148:151], v[196:199], v[84:87]
	v_mfma_f32_16x16x32_bf16 v[88:91], v[136:139], v[192:195], 0
	v_mfma_f32_16x16x32_bf16 v[88:91], v[140:143], v[196:199], v[88:91]
	v_mfma_f32_16x16x32_bf16 v[80:83], v[152:155], v[192:195], 0
	v_mfma_f32_16x16x32_bf16 v[80:83], v[156:159], v[196:199], v[80:83]
	v_mfma_f32_16x16x32_bf16 v[76:79], v[128:131], v[200:203], 0
	v_mfma_f32_16x16x32_bf16 v[76:79], v[132:135], v[204:207], v[76:79]
	v_mfma_f32_16x16x32_bf16 v[68:71], v[144:147], v[200:203], 0
	v_mfma_f32_16x16x32_bf16 v[68:71], v[148:151], v[204:207], v[68:71]
	v_mfma_f32_16x16x32_bf16 v[72:75], v[136:139], v[200:203], 0
	v_mfma_f32_16x16x32_bf16 v[72:75], v[140:143], v[204:207], v[72:75]
	v_mfma_f32_16x16x32_bf16 v[64:67], v[152:155], v[200:203], 0
	v_mfma_f32_16x16x32_bf16 v[64:67], v[156:159], v[204:207], v[64:67]
	s_barrier
	s_add_i32 s90, s90, s24
	v_lshl_add_u64 v[208:209], s[82:83], 0, v[172:173]
	s_mov_b32 m0, s90
	ds_read_b128 v[160:163], v187 offset:16384
	ds_read_b128 v[164:167], v187 offset:17408
	ds_read_b128 v[182:185], v187 offset:18432
	ds_read_b128 v[188:191], v187 offset:19456
	ds_read_b128 v[192:195], v187 offset:20480
	ds_read_b128 v[196:199], v187 offset:21504
	ds_read_b128 v[200:203], v187 offset:22528
	ds_read_b128 v[204:207], v187 offset:23552
	global_load_lds_dwordx4 v[208:209], off
	s_add_i32 m0, s90, 0x2000
	s_add_u32 s90, s82, 0x80000
	v_lshl_add_u64 v[210:211], s[82:83], 0, v[168:169]
	s_addc_u32 s91, s83, 0
	s_add_i32 s67, s67, s24
	global_load_lds_dwordx4 v[210:211], off
	v_lshl_add_u64 v[212:213], s[90:91], 0, v[172:173]
	s_mov_b32 m0, s67
	v_lshl_add_u64 v[214:215], s[84:85], 0, v[170:171]
	global_load_lds_dwordx4 v[212:213], off
	v_lshl_add_u64 v[212:213], s[90:91], 0, v[168:169]
	s_add_i32 m0, s67, 0x2000
	s_nop 0
	global_load_lds_dwordx4 v[212:213], off
	v_lshl_add_u64 v[212:213], s[84:85], 0, v[174:175]
	s_mov_b32 m0, s29
	s_nop 0
	global_load_lds_dwordx4 v[212:213], off
	s_mov_b32 m0, s34
	s_nop 0
	global_load_lds_dwordx4 v[214:215], off
	s_waitcnt vmcnt(8)
	s_waitcnt lgkmcnt(0)
	s_barrier
	s_waitcnt lgkmcnt(0)
	v_mfma_f32_16x16x32_bf16 v[60:63], v[128:131], v[160:163], 0
	v_mfma_f32_16x16x32_bf16 v[60:63], v[132:135], v[164:167], v[60:63]
	v_mfma_f32_16x16x32_bf16 v[52:55], v[144:147], v[160:163], 0
	v_mfma_f32_16x16x32_bf16 v[52:55], v[148:151], v[164:167], v[52:55]
	v_mfma_f32_16x16x32_bf16 v[56:59], v[136:139], v[160:163], 0
	v_mfma_f32_16x16x32_bf16 v[56:59], v[140:143], v[164:167], v[56:59]
	v_mfma_f32_16x16x32_bf16 v[48:51], v[152:155], v[160:163], 0
	v_mfma_f32_16x16x32_bf16 v[48:51], v[156:159], v[164:167], v[48:51]
	v_mfma_f32_16x16x32_bf16 v[44:47], v[128:131], v[182:185], 0
	v_mfma_f32_16x16x32_bf16 v[44:47], v[132:135], v[188:191], v[44:47]
	v_mfma_f32_16x16x32_bf16 v[36:39], v[144:147], v[182:185], 0
	v_mfma_f32_16x16x32_bf16 v[36:39], v[148:151], v[188:191], v[36:39]
	v_mfma_f32_16x16x32_bf16 v[40:43], v[136:139], v[182:185], 0
	v_mfma_f32_16x16x32_bf16 v[40:43], v[140:143], v[188:191], v[40:43]
	v_mfma_f32_16x16x32_bf16 v[32:35], v[152:155], v[182:185], 0
	v_mfma_f32_16x16x32_bf16 v[32:35], v[156:159], v[188:191], v[32:35]
	v_mfma_f32_16x16x32_bf16 v[28:31], v[128:131], v[192:195], 0
	v_mfma_f32_16x16x32_bf16 v[28:31], v[132:135], v[196:199], v[28:31]
	v_mfma_f32_16x16x32_bf16 v[20:23], v[144:147], v[192:195], 0
	v_mfma_f32_16x16x32_bf16 v[20:23], v[148:151], v[196:199], v[20:23]
	v_mfma_f32_16x16x32_bf16 v[24:27], v[136:139], v[192:195], 0
	v_mfma_f32_16x16x32_bf16 v[24:27], v[140:143], v[196:199], v[24:27]
	v_mfma_f32_16x16x32_bf16 v[16:19], v[152:155], v[192:195], 0
	v_mfma_f32_16x16x32_bf16 v[16:19], v[156:159], v[196:199], v[16:19]
	v_mfma_f32_16x16x32_bf16 v[12:15], v[128:131], v[200:203], 0
	v_mfma_f32_16x16x32_bf16 v[12:15], v[132:135], v[204:207], v[12:15]
	v_mfma_f32_16x16x32_bf16 v[4:7], v[144:147], v[200:203], 0
	v_mfma_f32_16x16x32_bf16 v[4:7], v[148:151], v[204:207], v[4:7]
	v_mfma_f32_16x16x32_bf16 v[8:11], v[136:139], v[200:203], 0
	v_mfma_f32_16x16x32_bf16 v[8:11], v[140:143], v[204:207], v[8:11]
	v_mfma_f32_16x16x32_bf16 v[0:3], v[152:155], v[200:203], 0
	v_mfma_f32_16x16x32_bf16 v[0:3], v[156:159], v[204:207], v[0:3]
	s_barrier
	s_add_i32 s67, 0, 0x18000
	s_add_i32 s90, 0, 0x1c000
	v_add_u32_e32 v140, s67, v186
	v_add_u32_e32 v156, s90, v186
	ds_read_b128 v[128:131], v140
	ds_read_b128 v[132:135], v140 offset:1024
	ds_read_b128 v[136:139], v140 offset:2048
	ds_read_b128 v[140:143], v140 offset:3072
	ds_read_b128 v[144:147], v156
	ds_read_b128 v[148:151], v156 offset:1024
	ds_read_b128 v[152:155], v156 offset:2048
	ds_read_b128 v[156:159], v156 offset:3072
	s_add_u32 s84, s84, 0x80000
	s_addc_u32 s85, s85, 0
	s_mov_b32 m0, s35
	v_lshl_add_u64 v[218:219], s[84:85], 0, v[174:175]
	ds_read_b128 v[160:163], v187 offset:32768
	ds_read_b128 v[164:167], v187 offset:33792
	ds_read_b128 v[182:185], v187 offset:34816
	ds_read_b128 v[188:191], v187 offset:35840
	ds_read_b128 v[192:195], v187 offset:36864
	ds_read_b128 v[196:199], v187 offset:37888
	ds_read_b128 v[200:203], v187 offset:38912
	ds_read_b128 v[204:207], v187 offset:39936
	global_load_lds_dwordx4 v[218:219], off
	v_lshl_add_u64 v[218:219], s[84:85], 0, v[170:171]
	s_mov_b32 m0, s38
	s_nop 0
	global_load_lds_dwordx4 v[218:219], off
	s_waitcnt vmcnt(8)
	s_waitcnt lgkmcnt(0)
	s_barrier
	s_waitcnt lgkmcnt(0)
	v_mfma_f32_16x16x32_bf16 v[124:127], v[128:131], v[160:163], v[124:127]
	v_mfma_f32_16x16x32_bf16 v[124:127], v[132:135], v[164:167], v[124:127]
	v_mfma_f32_16x16x32_bf16 v[116:119], v[144:147], v[160:163], v[116:119]
	v_mfma_f32_16x16x32_bf16 v[116:119], v[148:151], v[164:167], v[116:119]
	v_mfma_f32_16x16x32_bf16 v[120:123], v[136:139], v[160:163], v[120:123]
	v_mfma_f32_16x16x32_bf16 v[120:123], v[140:143], v[164:167], v[120:123]
	v_mfma_f32_16x16x32_bf16 v[112:115], v[152:155], v[160:163], v[112:115]
	v_mfma_f32_16x16x32_bf16 v[112:115], v[156:159], v[164:167], v[112:115]
	v_mfma_f32_16x16x32_bf16 v[108:111], v[128:131], v[182:185], v[108:111]
	v_mfma_f32_16x16x32_bf16 v[108:111], v[132:135], v[188:191], v[108:111]
	v_mfma_f32_16x16x32_bf16 v[100:103], v[144:147], v[182:185], v[100:103]
	v_mfma_f32_16x16x32_bf16 v[100:103], v[148:151], v[188:191], v[100:103]
	v_mfma_f32_16x16x32_bf16 v[104:107], v[136:139], v[182:185], v[104:107]
	v_mfma_f32_16x16x32_bf16 v[104:107], v[140:143], v[188:191], v[104:107]
	v_mfma_f32_16x16x32_bf16 v[96:99], v[152:155], v[182:185], v[96:99]
	v_mfma_f32_16x16x32_bf16 v[96:99], v[156:159], v[188:191], v[96:99]
	v_mfma_f32_16x16x32_bf16 v[92:95], v[128:131], v[192:195], v[92:95]
	v_mfma_f32_16x16x32_bf16 v[92:95], v[132:135], v[196:199], v[92:95]
	v_mfma_f32_16x16x32_bf16 v[84:87], v[144:147], v[192:195], v[84:87]
	v_mfma_f32_16x16x32_bf16 v[84:87], v[148:151], v[196:199], v[84:87]
	v_mfma_f32_16x16x32_bf16 v[88:91], v[136:139], v[192:195], v[88:91]
	v_mfma_f32_16x16x32_bf16 v[88:91], v[140:143], v[196:199], v[88:91]
	v_mfma_f32_16x16x32_bf16 v[80:83], v[152:155], v[192:195], v[80:83]
	v_mfma_f32_16x16x32_bf16 v[80:83], v[156:159], v[196:199], v[80:83]
	v_mfma_f32_16x16x32_bf16 v[76:79], v[128:131], v[200:203], v[76:79]
	v_mfma_f32_16x16x32_bf16 v[76:79], v[132:135], v[204:207], v[76:79]
	v_mfma_f32_16x16x32_bf16 v[68:71], v[144:147], v[200:203], v[68:71]
	v_mfma_f32_16x16x32_bf16 v[68:71], v[148:151], v[204:207], v[68:71]
	v_mfma_f32_16x16x32_bf16 v[72:75], v[136:139], v[200:203], v[72:75]
	v_mfma_f32_16x16x32_bf16 v[72:75], v[140:143], v[204:207], v[72:75]
	v_mfma_f32_16x16x32_bf16 v[64:67], v[152:155], v[200:203], v[64:67]
	v_mfma_f32_16x16x32_bf16 v[64:67], v[156:159], v[204:207], v[64:67]
	s_barrier
	s_add_i32 s67, s67, s24
	v_lshl_add_u64 v[208:209], v[208:209], 0, s[30:31]
	s_mov_b32 m0, s67
	ds_read_b128 v[160:163], v187 offset:49152
	ds_read_b128 v[164:167], v187 offset:50176
	ds_read_b128 v[182:185], v187 offset:51200
	ds_read_b128 v[188:191], v187 offset:52224
	ds_read_b128 v[192:195], v187 offset:53248
	ds_read_b128 v[196:199], v187 offset:54272
	ds_read_b128 v[200:203], v187 offset:55296
	ds_read_b128 v[204:207], v187 offset:56320
	global_load_lds_dwordx4 v[208:209], off
	s_add_i32 m0, s67, 0x2000
	s_add_u32 s82, s82, 0x80080
	v_lshl_add_u64 v[208:209], v[210:211], 0, s[30:31]
	s_addc_u32 s83, s83, 0
	s_add_i32 s67, s90, s24
	global_load_lds_dwordx4 v[208:209], off
	v_lshl_add_u64 v[208:209], s[82:83], 0, v[172:173]
	s_mov_b32 m0, s67
	s_nop 0
	global_load_lds_dwordx4 v[208:209], off
	v_lshl_add_u64 v[208:209], s[82:83], 0, v[168:169]
	s_add_i32 m0, s67, 0x2000
	s_nop 0
	global_load_lds_dwordx4 v[208:209], off
	v_lshl_add_u64 v[208:209], v[212:213], 0, s[30:31]
	s_mov_b32 m0, s54
	s_nop 0
	global_load_lds_dwordx4 v[208:209], off
	v_lshl_add_u64 v[208:209], v[214:215], 0, s[30:31]
	s_mov_b32 m0, s55
	s_nop 0
	global_load_lds_dwordx4 v[208:209], off
	s_waitcnt vmcnt(8)
	s_waitcnt lgkmcnt(0)
	s_barrier
	s_waitcnt lgkmcnt(0)
	v_mfma_f32_16x16x32_bf16 v[60:63], v[128:131], v[160:163], v[60:63]
	v_mfma_f32_16x16x32_bf16 v[60:63], v[132:135], v[164:167], v[60:63]
	v_mfma_f32_16x16x32_bf16 v[52:55], v[144:147], v[160:163], v[52:55]
	v_mfma_f32_16x16x32_bf16 v[52:55], v[148:151], v[164:167], v[52:55]
	v_mfma_f32_16x16x32_bf16 v[56:59], v[136:139], v[160:163], v[56:59]
	v_mfma_f32_16x16x32_bf16 v[56:59], v[140:143], v[164:167], v[56:59]
	v_mfma_f32_16x16x32_bf16 v[48:51], v[152:155], v[160:163], v[48:51]
	v_mfma_f32_16x16x32_bf16 v[48:51], v[156:159], v[164:167], v[48:51]
	v_mfma_f32_16x16x32_bf16 v[44:47], v[128:131], v[182:185], v[44:47]
	v_mfma_f32_16x16x32_bf16 v[44:47], v[132:135], v[188:191], v[44:47]
	v_mfma_f32_16x16x32_bf16 v[36:39], v[144:147], v[182:185], v[36:39]
	v_mfma_f32_16x16x32_bf16 v[36:39], v[148:151], v[188:191], v[36:39]
	v_mfma_f32_16x16x32_bf16 v[40:43], v[136:139], v[182:185], v[40:43]
	v_mfma_f32_16x16x32_bf16 v[40:43], v[140:143], v[188:191], v[40:43]
	v_mfma_f32_16x16x32_bf16 v[32:35], v[152:155], v[182:185], v[32:35]
	v_mfma_f32_16x16x32_bf16 v[32:35], v[156:159], v[188:191], v[32:35]
	v_mfma_f32_16x16x32_bf16 v[28:31], v[128:131], v[192:195], v[28:31]
	v_mfma_f32_16x16x32_bf16 v[28:31], v[132:135], v[196:199], v[28:31]
	v_mfma_f32_16x16x32_bf16 v[20:23], v[144:147], v[192:195], v[20:23]
	v_mfma_f32_16x16x32_bf16 v[20:23], v[148:151], v[196:199], v[20:23]
	v_mfma_f32_16x16x32_bf16 v[24:27], v[136:139], v[192:195], v[24:27]
	v_mfma_f32_16x16x32_bf16 v[24:27], v[140:143], v[196:199], v[24:27]
	v_mfma_f32_16x16x32_bf16 v[16:19], v[152:155], v[192:195], v[16:19]
	v_mfma_f32_16x16x32_bf16 v[16:19], v[156:159], v[196:199], v[16:19]
	v_mfma_f32_16x16x32_bf16 v[12:15], v[128:131], v[200:203], v[12:15]
	v_mfma_f32_16x16x32_bf16 v[12:15], v[132:135], v[204:207], v[12:15]
	v_mfma_f32_16x16x32_bf16 v[4:7], v[144:147], v[200:203], v[4:7]
	v_mfma_f32_16x16x32_bf16 v[4:7], v[148:151], v[204:207], v[4:7]
	v_mfma_f32_16x16x32_bf16 v[8:11], v[136:139], v[200:203], v[8:11]
	v_mfma_f32_16x16x32_bf16 v[8:11], v[140:143], v[204:207], v[8:11]
	v_mfma_f32_16x16x32_bf16 v[0:3], v[152:155], v[200:203], v[0:3]
	v_mfma_f32_16x16x32_bf16 v[0:3], v[156:159], v[204:207], v[0:3]
	s_barrier
	s_add_i32 s89, s89, 2
	s_add_u32 s80, s80, 0x100
	s_addc_u32 s81, s81, 0
	s_add_u32 s87, s87, 0x100
	s_addc_u32 s88, s88, 0
.LBB0_385:
	s_add_u32 s67, s80, 0xfff80080
	s_addc_u32 s82, s81, -1
	s_add_i32 s90, 0, 0x10000
	s_cmp_eq_u32 s89, 28
	s_cselect_b32 s85, s73, s82
	s_cselect_b32 s84, s79, s67
	s_cselect_b32 s83, s23, s88
	s_cselect_b32 s82, s86, s87
	s_add_i32 s67, 0, 0x14000
	v_add_u32_e32 v140, s90, v186
	v_add_u32_e32 v156, s67, v186
	ds_read_b128 v[128:131], v140
	ds_read_b128 v[132:135], v140 offset:1024
	ds_read_b128 v[136:139], v140 offset:2048
	ds_read_b128 v[140:143], v140 offset:3072
	ds_read_b128 v[144:147], v156
	ds_read_b128 v[148:151], v156 offset:1024
	ds_read_b128 v[152:155], v156 offset:2048
	ds_read_b128 v[156:159], v156 offset:3072
	v_lshl_add_u64 v[208:209], s[80:81], 0, v[178:179]
	s_add_i32 m0, s29, 0xc000
	ds_read_b128 v[160:163], v187
	ds_read_b128 v[164:167], v187 offset:1024
	ds_read_b128 v[182:185], v187 offset:2048
	ds_read_b128 v[188:191], v187 offset:3072
	ds_read_b128 v[192:195], v187 offset:4096
	ds_read_b128 v[196:199], v187 offset:5120
	ds_read_b128 v[200:203], v187 offset:6144
	ds_read_b128 v[204:207], v187 offset:7168
	global_load_lds_dwordx4 v[208:209], off
	v_lshl_add_u64 v[208:209], s[80:81], 0, v[180:181]
	s_add_i32 m0, s29, 0xe000
	s_nop 0
	global_load_lds_dwordx4 v[208:209], off
	s_waitcnt vmcnt(8)
	s_waitcnt lgkmcnt(0)
	s_barrier
	s_waitcnt lgkmcnt(0)
	v_mfma_f32_16x16x32_bf16 v[124:127], v[128:131], v[160:163], v[124:127]
	v_mfma_f32_16x16x32_bf16 v[124:127], v[132:135], v[164:167], v[124:127]
	v_mfma_f32_16x16x32_bf16 v[116:119], v[144:147], v[160:163], v[116:119]
	v_mfma_f32_16x16x32_bf16 v[116:119], v[148:151], v[164:167], v[116:119]
	v_mfma_f32_16x16x32_bf16 v[120:123], v[136:139], v[160:163], v[120:123]
	v_mfma_f32_16x16x32_bf16 v[120:123], v[140:143], v[164:167], v[120:123]
	v_mfma_f32_16x16x32_bf16 v[112:115], v[152:155], v[160:163], v[112:115]
	v_mfma_f32_16x16x32_bf16 v[112:115], v[156:159], v[164:167], v[112:115]
	v_mfma_f32_16x16x32_bf16 v[108:111], v[128:131], v[182:185], v[108:111]
	v_mfma_f32_16x16x32_bf16 v[108:111], v[132:135], v[188:191], v[108:111]
	v_mfma_f32_16x16x32_bf16 v[100:103], v[144:147], v[182:185], v[100:103]
	v_mfma_f32_16x16x32_bf16 v[100:103], v[148:151], v[188:191], v[100:103]
	v_mfma_f32_16x16x32_bf16 v[104:107], v[136:139], v[182:185], v[104:107]
	v_mfma_f32_16x16x32_bf16 v[104:107], v[140:143], v[188:191], v[104:107]
	v_mfma_f32_16x16x32_bf16 v[96:99], v[152:155], v[182:185], v[96:99]
	v_mfma_f32_16x16x32_bf16 v[96:99], v[156:159], v[188:191], v[96:99]
	v_mfma_f32_16x16x32_bf16 v[92:95], v[128:131], v[192:195], v[92:95]
	v_mfma_f32_16x16x32_bf16 v[92:95], v[132:135], v[196:199], v[92:95]
	v_mfma_f32_16x16x32_bf16 v[84:87], v[144:147], v[192:195], v[84:87]
	v_mfma_f32_16x16x32_bf16 v[84:87], v[148:151], v[196:199], v[84:87]
	v_mfma_f32_16x16x32_bf16 v[88:91], v[136:139], v[192:195], v[88:91]
	v_mfma_f32_16x16x32_bf16 v[88:91], v[140:143], v[196:199], v[88:91]
	v_mfma_f32_16x16x32_bf16 v[80:83], v[152:155], v[192:195], v[80:83]
	v_mfma_f32_16x16x32_bf16 v[80:83], v[156:159], v[196:199], v[80:83]
	v_mfma_f32_16x16x32_bf16 v[76:79], v[128:131], v[200:203], v[76:79]
	v_mfma_f32_16x16x32_bf16 v[76:79], v[132:135], v[204:207], v[76:79]
	v_mfma_f32_16x16x32_bf16 v[68:71], v[144:147], v[200:203], v[68:71]
	v_mfma_f32_16x16x32_bf16 v[68:71], v[148:151], v[204:207], v[68:71]
	v_mfma_f32_16x16x32_bf16 v[72:75], v[136:139], v[200:203], v[72:75]
	v_mfma_f32_16x16x32_bf16 v[72:75], v[140:143], v[204:207], v[72:75]
	v_mfma_f32_16x16x32_bf16 v[64:67], v[152:155], v[200:203], v[64:67]
	v_mfma_f32_16x16x32_bf16 v[64:67], v[156:159], v[204:207], v[64:67]
	s_barrier
	s_add_i32 s90, s90, s24
	v_lshl_add_u64 v[208:209], s[82:83], 0, v[172:173]
	s_mov_b32 m0, s90
	ds_read_b128 v[160:163], v187 offset:16384
	ds_read_b128 v[164:167], v187 offset:17408
	ds_read_b128 v[182:185], v187 offset:18432
	ds_read_b128 v[188:191], v187 offset:19456
	ds_read_b128 v[192:195], v187 offset:20480
	ds_read_b128 v[196:199], v187 offset:21504
	ds_read_b128 v[200:203], v187 offset:22528
	ds_read_b128 v[204:207], v187 offset:23552
	global_load_lds_dwordx4 v[208:209], off
	s_add_i32 m0, s90, 0x2000
	s_add_u32 s90, s82, 0x80000
	v_lshl_add_u64 v[210:211], s[82:83], 0, v[168:169]
	s_addc_u32 s91, s83, 0
	s_add_i32 s67, s67, s24
	global_load_lds_dwordx4 v[210:211], off
	v_lshl_add_u64 v[212:213], s[90:91], 0, v[172:173]
	s_mov_b32 m0, s67
	v_lshl_add_u64 v[214:215], s[84:85], 0, v[170:171]
	global_load_lds_dwordx4 v[212:213], off
	v_lshl_add_u64 v[212:213], s[90:91], 0, v[168:169]
	s_add_i32 m0, s67, 0x2000
	s_nop 0
	global_load_lds_dwordx4 v[212:213], off
	v_lshl_add_u64 v[212:213], s[84:85], 0, v[174:175]
	s_mov_b32 m0, s29
	s_nop 0
	global_load_lds_dwordx4 v[212:213], off
	s_mov_b32 m0, s34
	s_nop 0
	global_load_lds_dwordx4 v[214:215], off
	s_waitcnt vmcnt(8)
	s_waitcnt lgkmcnt(0)
	s_barrier
	s_waitcnt lgkmcnt(0)
	v_mfma_f32_16x16x32_bf16 v[60:63], v[128:131], v[160:163], v[60:63]
	v_mfma_f32_16x16x32_bf16 v[60:63], v[132:135], v[164:167], v[60:63]
	v_mfma_f32_16x16x32_bf16 v[52:55], v[144:147], v[160:163], v[52:55]
	v_mfma_f32_16x16x32_bf16 v[52:55], v[148:151], v[164:167], v[52:55]
	v_mfma_f32_16x16x32_bf16 v[56:59], v[136:139], v[160:163], v[56:59]
	v_mfma_f32_16x16x32_bf16 v[56:59], v[140:143], v[164:167], v[56:59]
	v_mfma_f32_16x16x32_bf16 v[48:51], v[152:155], v[160:163], v[48:51]
	v_mfma_f32_16x16x32_bf16 v[48:51], v[156:159], v[164:167], v[48:51]
	v_mfma_f32_16x16x32_bf16 v[44:47], v[128:131], v[182:185], v[44:47]
	v_mfma_f32_16x16x32_bf16 v[44:47], v[132:135], v[188:191], v[44:47]
	v_mfma_f32_16x16x32_bf16 v[36:39], v[144:147], v[182:185], v[36:39]
	v_mfma_f32_16x16x32_bf16 v[36:39], v[148:151], v[188:191], v[36:39]
	v_mfma_f32_16x16x32_bf16 v[40:43], v[136:139], v[182:185], v[40:43]
	v_mfma_f32_16x16x32_bf16 v[40:43], v[140:143], v[188:191], v[40:43]
	v_mfma_f32_16x16x32_bf16 v[32:35], v[152:155], v[182:185], v[32:35]
	v_mfma_f32_16x16x32_bf16 v[32:35], v[156:159], v[188:191], v[32:35]
	v_mfma_f32_16x16x32_bf16 v[28:31], v[128:131], v[192:195], v[28:31]
	v_mfma_f32_16x16x32_bf16 v[28:31], v[132:135], v[196:199], v[28:31]
	v_mfma_f32_16x16x32_bf16 v[20:23], v[144:147], v[192:195], v[20:23]
	v_mfma_f32_16x16x32_bf16 v[20:23], v[148:151], v[196:199], v[20:23]
	v_mfma_f32_16x16x32_bf16 v[24:27], v[136:139], v[192:195], v[24:27]
	v_mfma_f32_16x16x32_bf16 v[24:27], v[140:143], v[196:199], v[24:27]
	v_mfma_f32_16x16x32_bf16 v[16:19], v[152:155], v[192:195], v[16:19]
	v_mfma_f32_16x16x32_bf16 v[16:19], v[156:159], v[196:199], v[16:19]
	v_mfma_f32_16x16x32_bf16 v[12:15], v[128:131], v[200:203], v[12:15]
	v_mfma_f32_16x16x32_bf16 v[12:15], v[132:135], v[204:207], v[12:15]
	v_mfma_f32_16x16x32_bf16 v[4:7], v[144:147], v[200:203], v[4:7]
	v_mfma_f32_16x16x32_bf16 v[4:7], v[148:151], v[204:207], v[4:7]
	v_mfma_f32_16x16x32_bf16 v[8:11], v[136:139], v[200:203], v[8:11]
	v_mfma_f32_16x16x32_bf16 v[8:11], v[140:143], v[204:207], v[8:11]
	v_mfma_f32_16x16x32_bf16 v[0:3], v[152:155], v[200:203], v[0:3]
	v_mfma_f32_16x16x32_bf16 v[0:3], v[156:159], v[204:207], v[0:3]
	s_barrier
	s_add_i32 s67, 0, 0x18000
	s_add_i32 s90, 0, 0x1c000
	v_add_u32_e32 v140, s67, v186
	v_add_u32_e32 v156, s90, v186
	ds_read_b128 v[128:131], v140
	ds_read_b128 v[132:135], v140 offset:1024
	ds_read_b128 v[136:139], v140 offset:2048
	ds_read_b128 v[140:143], v140 offset:3072
	ds_read_b128 v[144:147], v156
	ds_read_b128 v[148:151], v156 offset:1024
	ds_read_b128 v[152:155], v156 offset:2048
	ds_read_b128 v[156:159], v156 offset:3072
	s_add_u32 s84, s84, 0x80000
	s_addc_u32 s85, s85, 0
	s_mov_b32 m0, s35
	v_lshl_add_u64 v[218:219], s[84:85], 0, v[174:175]
	ds_read_b128 v[160:163], v187 offset:32768
	ds_read_b128 v[164:167], v187 offset:33792
	ds_read_b128 v[182:185], v187 offset:34816
	ds_read_b128 v[188:191], v187 offset:35840
	ds_read_b128 v[192:195], v187 offset:36864
	ds_read_b128 v[196:199], v187 offset:37888
	ds_read_b128 v[200:203], v187 offset:38912
	ds_read_b128 v[204:207], v187 offset:39936
	global_load_lds_dwordx4 v[218:219], off
	v_lshl_add_u64 v[218:219], s[84:85], 0, v[170:171]
	s_mov_b32 m0, s38
	s_nop 0
	global_load_lds_dwordx4 v[218:219], off
	s_waitcnt vmcnt(8)
	s_waitcnt lgkmcnt(0)
	s_barrier
	s_waitcnt lgkmcnt(0)
	v_mfma_f32_16x16x32_bf16 v[124:127], v[128:131], v[160:163], v[124:127]
	v_mfma_f32_16x16x32_bf16 v[124:127], v[132:135], v[164:167], v[124:127]
	v_mfma_f32_16x16x32_bf16 v[116:119], v[144:147], v[160:163], v[116:119]
	v_mfma_f32_16x16x32_bf16 v[116:119], v[148:151], v[164:167], v[116:119]
	v_mfma_f32_16x16x32_bf16 v[120:123], v[136:139], v[160:163], v[120:123]
	v_mfma_f32_16x16x32_bf16 v[120:123], v[140:143], v[164:167], v[120:123]
	v_mfma_f32_16x16x32_bf16 v[112:115], v[152:155], v[160:163], v[112:115]
	v_mfma_f32_16x16x32_bf16 v[112:115], v[156:159], v[164:167], v[112:115]
	v_mfma_f32_16x16x32_bf16 v[108:111], v[128:131], v[182:185], v[108:111]
	v_mfma_f32_16x16x32_bf16 v[108:111], v[132:135], v[188:191], v[108:111]
	v_mfma_f32_16x16x32_bf16 v[100:103], v[144:147], v[182:185], v[100:103]
	v_mfma_f32_16x16x32_bf16 v[100:103], v[148:151], v[188:191], v[100:103]
	v_mfma_f32_16x16x32_bf16 v[104:107], v[136:139], v[182:185], v[104:107]
	v_mfma_f32_16x16x32_bf16 v[104:107], v[140:143], v[188:191], v[104:107]
	v_mfma_f32_16x16x32_bf16 v[96:99], v[152:155], v[182:185], v[96:99]
	v_mfma_f32_16x16x32_bf16 v[96:99], v[156:159], v[188:191], v[96:99]
	v_mfma_f32_16x16x32_bf16 v[92:95], v[128:131], v[192:195], v[92:95]
	v_mfma_f32_16x16x32_bf16 v[92:95], v[132:135], v[196:199], v[92:95]
	v_mfma_f32_16x16x32_bf16 v[84:87], v[144:147], v[192:195], v[84:87]
	v_mfma_f32_16x16x32_bf16 v[84:87], v[148:151], v[196:199], v[84:87]
	v_mfma_f32_16x16x32_bf16 v[88:91], v[136:139], v[192:195], v[88:91]
	v_mfma_f32_16x16x32_bf16 v[88:91], v[140:143], v[196:199], v[88:91]
	v_mfma_f32_16x16x32_bf16 v[80:83], v[152:155], v[192:195], v[80:83]
	v_mfma_f32_16x16x32_bf16 v[80:83], v[156:159], v[196:199], v[80:83]
	v_mfma_f32_16x16x32_bf16 v[76:79], v[128:131], v[200:203], v[76:79]
	v_mfma_f32_16x16x32_bf16 v[76:79], v[132:135], v[204:207], v[76:79]
	v_mfma_f32_16x16x32_bf16 v[68:71], v[144:147], v[200:203], v[68:71]
	v_mfma_f32_16x16x32_bf16 v[68:71], v[148:151], v[204:207], v[68:71]
	v_mfma_f32_16x16x32_bf16 v[72:75], v[136:139], v[200:203], v[72:75]
	v_mfma_f32_16x16x32_bf16 v[72:75], v[140:143], v[204:207], v[72:75]
	v_mfma_f32_16x16x32_bf16 v[64:67], v[152:155], v[200:203], v[64:67]
	v_mfma_f32_16x16x32_bf16 v[64:67], v[156:159], v[204:207], v[64:67]
	s_barrier
	s_add_i32 s67, s67, s24
	v_lshl_add_u64 v[208:209], v[208:209], 0, s[30:31]
	s_mov_b32 m0, s67
	ds_read_b128 v[160:163], v187 offset:49152
	ds_read_b128 v[164:167], v187 offset:50176
	ds_read_b128 v[182:185], v187 offset:51200
	ds_read_b128 v[188:191], v187 offset:52224
	ds_read_b128 v[192:195], v187 offset:53248
	ds_read_b128 v[196:199], v187 offset:54272
	ds_read_b128 v[200:203], v187 offset:55296
	ds_read_b128 v[204:207], v187 offset:56320
	global_load_lds_dwordx4 v[208:209], off
	s_add_i32 m0, s67, 0x2000
	s_add_u32 s82, s82, 0x80080
	v_lshl_add_u64 v[208:209], v[210:211], 0, s[30:31]
	s_addc_u32 s83, s83, 0
	s_add_i32 s67, s90, s24
	global_load_lds_dwordx4 v[208:209], off
	v_lshl_add_u64 v[208:209], s[82:83], 0, v[172:173]
	s_mov_b32 m0, s67
	s_nop 0
	global_load_lds_dwordx4 v[208:209], off
	v_lshl_add_u64 v[208:209], s[82:83], 0, v[168:169]
	s_add_i32 m0, s67, 0x2000
	s_nop 0
	global_load_lds_dwordx4 v[208:209], off
	v_lshl_add_u64 v[208:209], v[212:213], 0, s[30:31]
	s_mov_b32 m0, s54
	s_nop 0
	global_load_lds_dwordx4 v[208:209], off
	v_lshl_add_u64 v[208:209], v[214:215], 0, s[30:31]
	s_mov_b32 m0, s55
	s_nop 0
	global_load_lds_dwordx4 v[208:209], off
	s_waitcnt vmcnt(8)
	s_waitcnt lgkmcnt(0)
	s_barrier
	s_waitcnt lgkmcnt(0)
	v_mfma_f32_16x16x32_bf16 v[60:63], v[128:131], v[160:163], v[60:63]
	v_mfma_f32_16x16x32_bf16 v[60:63], v[132:135], v[164:167], v[60:63]
	v_mfma_f32_16x16x32_bf16 v[52:55], v[144:147], v[160:163], v[52:55]
	v_mfma_f32_16x16x32_bf16 v[52:55], v[148:151], v[164:167], v[52:55]
	v_mfma_f32_16x16x32_bf16 v[56:59], v[136:139], v[160:163], v[56:59]
	v_mfma_f32_16x16x32_bf16 v[56:59], v[140:143], v[164:167], v[56:59]
	v_mfma_f32_16x16x32_bf16 v[48:51], v[152:155], v[160:163], v[48:51]
	v_mfma_f32_16x16x32_bf16 v[48:51], v[156:159], v[164:167], v[48:51]
	v_mfma_f32_16x16x32_bf16 v[44:47], v[128:131], v[182:185], v[44:47]
	v_mfma_f32_16x16x32_bf16 v[44:47], v[132:135], v[188:191], v[44:47]
	v_mfma_f32_16x16x32_bf16 v[36:39], v[144:147], v[182:185], v[36:39]
	v_mfma_f32_16x16x32_bf16 v[36:39], v[148:151], v[188:191], v[36:39]
	v_mfma_f32_16x16x32_bf16 v[40:43], v[136:139], v[182:185], v[40:43]
	v_mfma_f32_16x16x32_bf16 v[40:43], v[140:143], v[188:191], v[40:43]
	v_mfma_f32_16x16x32_bf16 v[32:35], v[152:155], v[182:185], v[32:35]
	v_mfma_f32_16x16x32_bf16 v[32:35], v[156:159], v[188:191], v[32:35]
	v_mfma_f32_16x16x32_bf16 v[28:31], v[128:131], v[192:195], v[28:31]
	v_mfma_f32_16x16x32_bf16 v[28:31], v[132:135], v[196:199], v[28:31]
	v_mfma_f32_16x16x32_bf16 v[20:23], v[144:147], v[192:195], v[20:23]
	v_mfma_f32_16x16x32_bf16 v[20:23], v[148:151], v[196:199], v[20:23]
	v_mfma_f32_16x16x32_bf16 v[24:27], v[136:139], v[192:195], v[24:27]
	v_mfma_f32_16x16x32_bf16 v[24:27], v[140:143], v[196:199], v[24:27]
	v_mfma_f32_16x16x32_bf16 v[16:19], v[152:155], v[192:195], v[16:19]
	v_mfma_f32_16x16x32_bf16 v[16:19], v[156:159], v[196:199], v[16:19]
	v_mfma_f32_16x16x32_bf16 v[12:15], v[128:131], v[200:203], v[12:15]
	v_mfma_f32_16x16x32_bf16 v[12:15], v[132:135], v[204:207], v[12:15]
	v_mfma_f32_16x16x32_bf16 v[4:7], v[144:147], v[200:203], v[4:7]
	v_mfma_f32_16x16x32_bf16 v[4:7], v[148:151], v[204:207], v[4:7]
	v_mfma_f32_16x16x32_bf16 v[8:11], v[136:139], v[200:203], v[8:11]
	v_mfma_f32_16x16x32_bf16 v[8:11], v[140:143], v[204:207], v[8:11]
	v_mfma_f32_16x16x32_bf16 v[0:3], v[152:155], v[200:203], v[0:3]
	v_mfma_f32_16x16x32_bf16 v[0:3], v[156:159], v[204:207], v[0:3]
	s_barrier
	s_add_i32 s89, s89, 2
	s_add_u32 s80, s80, 0x100
	s_addc_u32 s81, s81, 0
	s_add_u32 s87, s87, 0x100
	s_addc_u32 s88, s88, 0
	s_cmp_gt_u32 s89, 29
	s_cbranch_scc0 .LBB0_385
	s_and_b64 vcc, exec, s[18:19]
	s_cbranch_vccz .LBB0_388
	s_barrier

.LBB0_594:
	s_ashr_i32 s81, s80, 31
	s_lshl_b64 s[84:85], s[80:81], 20
	s_add_u32 s84, s29, s84
	s_addc_u32 s85, s34, s85
	s_and_b64 s[86:87], s[82:83], exec
	s_cselect_b32 s81, s85, s95
	s_cselect_b32 vcc_lo, s84, s94
	s_ashr_i32 s79, s78, 31
	s_lshl_b64 s[86:87], s[78:79], 20
	s_add_u32 s86, s35, s86
	s_addc_u32 s87, s38, s87
	s_and_b64 s[2:3], s[82:83], exec
	s_cselect_b32 s79, s87, s93
	s_cselect_b32 vcc_hi, s86, s92
	s_lshl_b32 s88, s88, 8
	s_ashr_i32 s89, s88, 31
	s_lshl_b64 s[2:3], s[88:89], 2
	s_add_u32 s2, s90, s2
	s_addc_u32 s3, s91, s3
	s_add_i32 m0, s14, s41
	s_add_u32 s90, s94, 0x80080
	global_load_lds_dwordx4 v239, s[2:3]
	s_addc_u32 s91, s95, 0
	s_add_u32 s89, s92, 0x100
	s_addc_u32 s14, s93, 0
	s_mov_b32 s20, -2
	s_waitcnt vmcnt(0)
	s_add_u32 s2, s90, 0xfff80080
	s_addc_u32 s3, s91, -1
	s_add_i32 s67, 0, 0x10000
	s_cmp_eq_u32 s20, 28
	s_cselect_b32 s95, s81, s3
	s_cselect_b32 s94, vcc_lo, s2
	s_cselect_b32 s93, s79, s14
	s_cselect_b32 s92, vcc_hi, s89
	s_add_i32 s76, 0, 0x14000
	v_add_u32_e32 v96, s67, v238
	v_add_u32_e32 v140, s76, v238
	ds_read_b128 v[64:67], v96
	ds_read_b128 v[72:75], v96 offset:1024
	ds_read_b128 v[88:91], v96 offset:2048
	ds_read_b128 v[96:99], v96 offset:3072
	ds_read_b128 v[108:111], v140
	ds_read_b128 v[116:119], v140 offset:1024
	ds_read_b128 v[128:131], v140 offset:2048
	ds_read_b128 v[140:143], v140 offset:3072
	v_lshl_add_u64 v[192:193], s[90:91], 0, v[230:231]
	s_add_i32 m0, s39, 0xc000
	ds_read_b128 v[152:155], v240
	ds_read_b128 v[156:159], v240 offset:1024
	ds_read_b128 v[160:163], v240 offset:2048
	ds_read_b128 v[164:167], v240 offset:3072
	ds_read_b128 v[168:171], v240 offset:4096
	ds_read_b128 v[180:183], v240 offset:5120
	ds_read_b128 v[184:187], v240 offset:6144
	ds_read_b128 v[188:191], v240 offset:7168
	global_load_lds_dwordx4 v[192:193], off
	v_lshl_add_u64 v[192:193], s[90:91], 0, v[232:233]
	s_add_i32 m0, s39, 0xe000
	s_nop 0
	global_load_lds_dwordx4 v[192:193], off
	s_waitcnt vmcnt(8)
	s_waitcnt lgkmcnt(0)
	s_barrier
	s_waitcnt lgkmcnt(0)
	v_mfma_f32_16x16x32_bf16 v[176:179], v[64:67], v[152:155], 0
	v_mfma_f32_16x16x32_bf16 v[176:179], v[72:75], v[156:159], v[176:179]
	v_mfma_f32_16x16x32_bf16 v[148:151], v[108:111], v[152:155], 0
	v_mfma_f32_16x16x32_bf16 v[148:151], v[116:119], v[156:159], v[148:151]
	v_mfma_f32_16x16x32_bf16 v[172:175], v[88:91], v[152:155], 0
	v_mfma_f32_16x16x32_bf16 v[172:175], v[96:99], v[156:159], v[172:175]
	v_mfma_f32_16x16x32_bf16 v[144:147], v[128:131], v[152:155], 0
	v_mfma_f32_16x16x32_bf16 v[144:147], v[140:143], v[156:159], v[144:147]
	v_mfma_f32_16x16x32_bf16 v[136:139], v[64:67], v[160:163], 0
	v_mfma_f32_16x16x32_bf16 v[136:139], v[72:75], v[164:167], v[136:139]
	v_mfma_f32_16x16x32_bf16 v[124:127], v[108:111], v[160:163], 0
	v_mfma_f32_16x16x32_bf16 v[124:127], v[116:119], v[164:167], v[124:127]
	v_mfma_f32_16x16x32_bf16 v[132:135], v[88:91], v[160:163], 0
	v_mfma_f32_16x16x32_bf16 v[132:135], v[96:99], v[164:167], v[132:135]
	v_mfma_f32_16x16x32_bf16 v[120:123], v[128:131], v[160:163], 0
	v_mfma_f32_16x16x32_bf16 v[120:123], v[140:143], v[164:167], v[120:123]
	v_mfma_f32_16x16x32_bf16 v[112:115], v[64:67], v[168:171], 0
	v_mfma_f32_16x16x32_bf16 v[112:115], v[72:75], v[180:183], v[112:115]
	v_mfma_f32_16x16x32_bf16 v[100:103], v[108:111], v[168:171], 0
	v_mfma_f32_16x16x32_bf16 v[100:103], v[116:119], v[180:183], v[100:103]
	v_mfma_f32_16x16x32_bf16 v[104:107], v[88:91], v[168:171], 0
	v_mfma_f32_16x16x32_bf16 v[104:107], v[96:99], v[180:183], v[104:107]
	v_mfma_f32_16x16x32_bf16 v[92:95], v[128:131], v[168:171], 0
	v_mfma_f32_16x16x32_bf16 v[92:95], v[140:143], v[180:183], v[92:95]
	v_mfma_f32_16x16x32_bf16 v[84:87], v[64:67], v[184:187], 0
	v_mfma_f32_16x16x32_bf16 v[84:87], v[72:75], v[188:191], v[84:87]
	v_mfma_f32_16x16x32_bf16 v[76:79], v[108:111], v[184:187], 0
	v_mfma_f32_16x16x32_bf16 v[76:79], v[116:119], v[188:191], v[76:79]
	v_mfma_f32_16x16x32_bf16 v[80:83], v[88:91], v[184:187], 0
	v_mfma_f32_16x16x32_bf16 v[80:83], v[96:99], v[188:191], v[80:83]
	v_mfma_f32_16x16x32_bf16 v[68:71], v[128:131], v[184:187], 0
	v_mfma_f32_16x16x32_bf16 v[68:71], v[140:143], v[188:191], v[68:71]
	s_barrier
	s_add_i32 s2, s67, s28
	v_lshl_add_u64 v[192:193], s[92:93], 0, v[216:217]
	s_mov_b32 m0, s2
	ds_read_b128 v[152:155], v240 offset:16384
	ds_read_b128 v[156:159], v240 offset:17408
	ds_read_b128 v[160:163], v240 offset:18432
	ds_read_b128 v[164:167], v240 offset:19456
	ds_read_b128 v[168:171], v240 offset:20480
	ds_read_b128 v[180:183], v240 offset:21504
	ds_read_b128 v[184:187], v240 offset:22528
	ds_read_b128 v[188:191], v240 offset:23552
	global_load_lds_dwordx4 v[192:193], off
	s_add_i32 m0, s2, 0x2000
	s_add_u32 s2, s92, 0x80000
	v_lshl_add_u64 v[194:195], s[92:93], 0, v[228:229]
	s_addc_u32 s3, s93, 0
	s_add_i32 s67, s76, s28
	global_load_lds_dwordx4 v[194:195], off
	v_lshl_add_u64 v[196:197], s[2:3], 0, v[216:217]
	s_mov_b32 m0, s67
	v_lshl_add_u64 v[198:199], s[94:95], 0, v[226:227]
	global_load_lds_dwordx4 v[196:197], off
	v_lshl_add_u64 v[196:197], s[2:3], 0, v[228:229]
	s_add_i32 m0, s67, 0x2000
	s_nop 0
	global_load_lds_dwordx4 v[196:197], off
	v_lshl_add_u64 v[196:197], s[94:95], 0, v[224:225]
	s_mov_b32 m0, s39
	s_nop 0
	global_load_lds_dwordx4 v[196:197], off
	s_mov_b32 m0, s53
	s_nop 0
	global_load_lds_dwordx4 v[198:199], off
	s_waitcnt vmcnt(8)
	s_waitcnt lgkmcnt(0)
	s_barrier
	s_waitcnt lgkmcnt(0)
	v_mfma_f32_16x16x32_bf16 v[60:63], v[64:67], v[152:155], 0
	v_mfma_f32_16x16x32_bf16 v[60:63], v[72:75], v[156:159], v[60:63]
	v_mfma_f32_16x16x32_bf16 v[52:55], v[108:111], v[152:155], 0
	v_mfma_f32_16x16x32_bf16 v[52:55], v[116:119], v[156:159], v[52:55]
	v_mfma_f32_16x16x32_bf16 v[56:59], v[88:91], v[152:155], 0
	v_mfma_f32_16x16x32_bf16 v[56:59], v[96:99], v[156:159], v[56:59]
	v_mfma_f32_16x16x32_bf16 v[48:51], v[128:131], v[152:155], 0
	v_mfma_f32_16x16x32_bf16 v[48:51], v[140:143], v[156:159], v[48:51]
	v_mfma_f32_16x16x32_bf16 v[44:47], v[64:67], v[160:163], 0
	v_mfma_f32_16x16x32_bf16 v[44:47], v[72:75], v[164:167], v[44:47]
	v_mfma_f32_16x16x32_bf16 v[36:39], v[108:111], v[160:163], 0
	v_mfma_f32_16x16x32_bf16 v[36:39], v[116:119], v[164:167], v[36:39]
	v_mfma_f32_16x16x32_bf16 v[40:43], v[88:91], v[160:163], 0
	v_mfma_f32_16x16x32_bf16 v[40:43], v[96:99], v[164:167], v[40:43]
	v_mfma_f32_16x16x32_bf16 v[32:35], v[128:131], v[160:163], 0
	v_mfma_f32_16x16x32_bf16 v[32:35], v[140:143], v[164:167], v[32:35]
	v_mfma_f32_16x16x32_bf16 v[28:31], v[64:67], v[168:171], 0
	v_mfma_f32_16x16x32_bf16 v[28:31], v[72:75], v[180:183], v[28:31]
	v_mfma_f32_16x16x32_bf16 v[20:23], v[108:111], v[168:171], 0
	v_mfma_f32_16x16x32_bf16 v[20:23], v[116:119], v[180:183], v[20:23]
	v_mfma_f32_16x16x32_bf16 v[24:27], v[88:91], v[168:171], 0
	v_mfma_f32_16x16x32_bf16 v[24:27], v[96:99], v[180:183], v[24:27]
	v_mfma_f32_16x16x32_bf16 v[16:19], v[128:131], v[168:171], 0
	v_mfma_f32_16x16x32_bf16 v[16:19], v[140:143], v[180:183], v[16:19]
	v_mfma_f32_16x16x32_bf16 v[12:15], v[64:67], v[184:187], 0
	v_mfma_f32_16x16x32_bf16 v[12:15], v[72:75], v[188:191], v[12:15]
	v_mfma_f32_16x16x32_bf16 v[4:7], v[108:111], v[184:187], 0
	v_mfma_f32_16x16x32_bf16 v[4:7], v[116:119], v[188:191], v[4:7]
	v_mfma_f32_16x16x32_bf16 v[8:11], v[88:91], v[184:187], 0
	v_mfma_f32_16x16x32_bf16 v[8:11], v[96:99], v[188:191], v[8:11]
	v_mfma_f32_16x16x32_bf16 v[0:3], v[128:131], v[184:187], 0
	v_mfma_f32_16x16x32_bf16 v[0:3], v[140:143], v[188:191], v[0:3]
	s_barrier
	s_add_i32 s67, 0, 0x18000
	s_add_i32 s76, 0, 0x1c000
	v_add_u32_e32 v96, s67, v238
	v_add_u32_e32 v140, s76, v238
	ds_read_b128 v[64:67], v96
	ds_read_b128 v[72:75], v96 offset:1024
	ds_read_b128 v[88:91], v96 offset:2048
	ds_read_b128 v[96:99], v96 offset:3072
	ds_read_b128 v[108:111], v140
	ds_read_b128 v[116:119], v140 offset:1024
	ds_read_b128 v[128:131], v140 offset:2048
	ds_read_b128 v[140:143], v140 offset:3072
	s_add_u32 s2, s94, 0x80000
	s_addc_u32 s3, s95, 0
	s_mov_b32 m0, s55
	v_lshl_add_u64 v[200:201], s[2:3], 0, v[224:225]
	ds_read_b128 v[152:155], v240 offset:32768
	ds_read_b128 v[156:159], v240 offset:33792
	ds_read_b128 v[160:163], v240 offset:34816
	ds_read_b128 v[164:167], v240 offset:35840
	ds_read_b128 v[168:171], v240 offset:36864
	ds_read_b128 v[180:183], v240 offset:37888
	ds_read_b128 v[184:187], v240 offset:38912
	ds_read_b128 v[188:191], v240 offset:39936
	global_load_lds_dwordx4 v[200:201], off
	v_lshl_add_u64 v[200:201], s[2:3], 0, v[226:227]
	s_mov_b32 m0, s56
	s_nop 0
	global_load_lds_dwordx4 v[200:201], off
	s_waitcnt vmcnt(8)
	s_waitcnt lgkmcnt(0)
	s_barrier
	s_waitcnt lgkmcnt(0)
	v_mfma_f32_16x16x32_bf16 v[176:179], v[64:67], v[152:155], v[176:179]
	v_mfma_f32_16x16x32_bf16 v[176:179], v[72:75], v[156:159], v[176:179]
	v_mfma_f32_16x16x32_bf16 v[148:151], v[108:111], v[152:155], v[148:151]
	v_mfma_f32_16x16x32_bf16 v[148:151], v[116:119], v[156:159], v[148:151]
	v_mfma_f32_16x16x32_bf16 v[172:175], v[88:91], v[152:155], v[172:175]
	v_mfma_f32_16x16x32_bf16 v[172:175], v[96:99], v[156:159], v[172:175]
	v_mfma_f32_16x16x32_bf16 v[144:147], v[128:131], v[152:155], v[144:147]
	v_mfma_f32_16x16x32_bf16 v[144:147], v[140:143], v[156:159], v[144:147]
	v_mfma_f32_16x16x32_bf16 v[136:139], v[64:67], v[160:163], v[136:139]
	v_mfma_f32_16x16x32_bf16 v[136:139], v[72:75], v[164:167], v[136:139]
	v_mfma_f32_16x16x32_bf16 v[124:127], v[108:111], v[160:163], v[124:127]
	v_mfma_f32_16x16x32_bf16 v[124:127], v[116:119], v[164:167], v[124:127]
	v_mfma_f32_16x16x32_bf16 v[132:135], v[88:91], v[160:163], v[132:135]
	v_mfma_f32_16x16x32_bf16 v[132:135], v[96:99], v[164:167], v[132:135]
	v_mfma_f32_16x16x32_bf16 v[120:123], v[128:131], v[160:163], v[120:123]
	v_mfma_f32_16x16x32_bf16 v[120:123], v[140:143], v[164:167], v[120:123]
	v_mfma_f32_16x16x32_bf16 v[112:115], v[64:67], v[168:171], v[112:115]
	v_mfma_f32_16x16x32_bf16 v[112:115], v[72:75], v[180:183], v[112:115]
	v_mfma_f32_16x16x32_bf16 v[100:103], v[108:111], v[168:171], v[100:103]
	v_mfma_f32_16x16x32_bf16 v[100:103], v[116:119], v[180:183], v[100:103]
	v_mfma_f32_16x16x32_bf16 v[104:107], v[88:91], v[168:171], v[104:107]
	v_mfma_f32_16x16x32_bf16 v[104:107], v[96:99], v[180:183], v[104:107]
	v_mfma_f32_16x16x32_bf16 v[92:95], v[128:131], v[168:171], v[92:95]
	v_mfma_f32_16x16x32_bf16 v[92:95], v[140:143], v[180:183], v[92:95]
	v_mfma_f32_16x16x32_bf16 v[84:87], v[64:67], v[184:187], v[84:87]
	v_mfma_f32_16x16x32_bf16 v[84:87], v[72:75], v[188:191], v[84:87]
	v_mfma_f32_16x16x32_bf16 v[76:79], v[108:111], v[184:187], v[76:79]
	v_mfma_f32_16x16x32_bf16 v[76:79], v[116:119], v[188:191], v[76:79]
	v_mfma_f32_16x16x32_bf16 v[80:83], v[88:91], v[184:187], v[80:83]
	v_mfma_f32_16x16x32_bf16 v[80:83], v[96:99], v[188:191], v[80:83]
	v_mfma_f32_16x16x32_bf16 v[68:71], v[128:131], v[184:187], v[68:71]
	v_mfma_f32_16x16x32_bf16 v[68:71], v[140:143], v[188:191], v[68:71]
	s_barrier
	s_add_i32 s2, s67, s28
	v_lshl_add_u64 v[192:193], v[192:193], 0, s[30:31]
	s_mov_b32 m0, s2
	ds_read_b128 v[152:155], v240 offset:49152
	ds_read_b128 v[156:159], v240 offset:50176
	ds_read_b128 v[160:163], v240 offset:51200
	ds_read_b128 v[164:167], v240 offset:52224
	ds_read_b128 v[168:171], v240 offset:53248
	ds_read_b128 v[180:183], v240 offset:54272
	ds_read_b128 v[184:187], v240 offset:55296
	ds_read_b128 v[188:191], v240 offset:56320
	global_load_lds_dwordx4 v[192:193], off
	s_add_i32 m0, s2, 0x2000
	s_add_u32 s2, s92, 0x80080
	v_lshl_add_u64 v[192:193], v[194:195], 0, s[30:31]
	s_addc_u32 s3, s93, 0
	s_add_i32 s67, s76, s28
	global_load_lds_dwordx4 v[192:193], off
	v_lshl_add_u64 v[192:193], s[2:3], 0, v[216:217]
	s_mov_b32 m0, s67
	s_nop 0
	global_load_lds_dwordx4 v[192:193], off
	v_lshl_add_u64 v[192:193], s[2:3], 0, v[228:229]
	s_add_i32 m0, s67, 0x2000
	s_nop 0
	global_load_lds_dwordx4 v[192:193], off
	v_lshl_add_u64 v[192:193], v[196:197], 0, s[30:31]
	s_mov_b32 m0, s70
	s_nop 0
	global_load_lds_dwordx4 v[192:193], off
	v_lshl_add_u64 v[192:193], v[198:199], 0, s[30:31]
	s_mov_b32 m0, s71
	s_nop 0
	global_load_lds_dwordx4 v[192:193], off
	s_waitcnt vmcnt(8)
	s_waitcnt lgkmcnt(0)
	s_barrier
	s_waitcnt lgkmcnt(0)
	v_mfma_f32_16x16x32_bf16 v[60:63], v[64:67], v[152:155], v[60:63]
	v_mfma_f32_16x16x32_bf16 v[60:63], v[72:75], v[156:159], v[60:63]
	v_mfma_f32_16x16x32_bf16 v[52:55], v[108:111], v[152:155], v[52:55]
	v_mfma_f32_16x16x32_bf16 v[52:55], v[116:119], v[156:159], v[52:55]
	v_mfma_f32_16x16x32_bf16 v[56:59], v[88:91], v[152:155], v[56:59]
	v_mfma_f32_16x16x32_bf16 v[56:59], v[96:99], v[156:159], v[56:59]
	v_mfma_f32_16x16x32_bf16 v[48:51], v[128:131], v[152:155], v[48:51]
	v_mfma_f32_16x16x32_bf16 v[48:51], v[140:143], v[156:159], v[48:51]
	v_mfma_f32_16x16x32_bf16 v[44:47], v[64:67], v[160:163], v[44:47]
	v_mfma_f32_16x16x32_bf16 v[44:47], v[72:75], v[164:167], v[44:47]
	v_mfma_f32_16x16x32_bf16 v[36:39], v[108:111], v[160:163], v[36:39]
	v_mfma_f32_16x16x32_bf16 v[36:39], v[116:119], v[164:167], v[36:39]
	v_mfma_f32_16x16x32_bf16 v[40:43], v[88:91], v[160:163], v[40:43]
	v_mfma_f32_16x16x32_bf16 v[40:43], v[96:99], v[164:167], v[40:43]
	v_mfma_f32_16x16x32_bf16 v[32:35], v[128:131], v[160:163], v[32:35]
	v_mfma_f32_16x16x32_bf16 v[32:35], v[140:143], v[164:167], v[32:35]
	v_mfma_f32_16x16x32_bf16 v[28:31], v[64:67], v[168:171], v[28:31]
	v_mfma_f32_16x16x32_bf16 v[28:31], v[72:75], v[180:183], v[28:31]
	v_mfma_f32_16x16x32_bf16 v[20:23], v[108:111], v[168:171], v[20:23]
	v_mfma_f32_16x16x32_bf16 v[20:23], v[116:119], v[180:183], v[20:23]
	v_mfma_f32_16x16x32_bf16 v[24:27], v[88:91], v[168:171], v[24:27]
	v_mfma_f32_16x16x32_bf16 v[24:27], v[96:99], v[180:183], v[24:27]
	v_mfma_f32_16x16x32_bf16 v[16:19], v[128:131], v[168:171], v[16:19]
	v_mfma_f32_16x16x32_bf16 v[16:19], v[140:143], v[180:183], v[16:19]
	v_mfma_f32_16x16x32_bf16 v[12:15], v[64:67], v[184:187], v[12:15]
	v_mfma_f32_16x16x32_bf16 v[12:15], v[72:75], v[188:191], v[12:15]
	v_mfma_f32_16x16x32_bf16 v[4:7], v[108:111], v[184:187], v[4:7]
	v_mfma_f32_16x16x32_bf16 v[4:7], v[116:119], v[188:191], v[4:7]
	v_mfma_f32_16x16x32_bf16 v[8:11], v[88:91], v[184:187], v[8:11]
	v_mfma_f32_16x16x32_bf16 v[8:11], v[96:99], v[188:191], v[8:11]
	v_mfma_f32_16x16x32_bf16 v[0:3], v[128:131], v[184:187], v[0:3]
	v_mfma_f32_16x16x32_bf16 v[0:3], v[140:143], v[188:191], v[0:3]
	s_barrier
	s_add_i32 s20, s20, 2
	s_add_u32 s90, s90, 0x100
	s_addc_u32 s91, s91, 0
	s_add_u32 s89, s89, 0x100
	s_addc_u32 s14, s14, 0
.LBB0_595:
	s_add_u32 s2, s90, 0xfff80080
	s_addc_u32 s3, s91, -1
	s_add_i32 s67, 0, 0x10000
	s_cmp_eq_u32 s20, 28
	s_cselect_b32 s95, s81, s3
	s_cselect_b32 s94, vcc_lo, s2
	s_cselect_b32 s93, s79, s14
	s_cselect_b32 s92, vcc_hi, s89
	s_add_i32 s76, 0, 0x14000
	v_add_u32_e32 v96, s67, v238
	v_add_u32_e32 v140, s76, v238
	ds_read_b128 v[64:67], v96
	ds_read_b128 v[72:75], v96 offset:1024
	ds_read_b128 v[88:91], v96 offset:2048
	ds_read_b128 v[96:99], v96 offset:3072
	ds_read_b128 v[108:111], v140
	ds_read_b128 v[116:119], v140 offset:1024
	ds_read_b128 v[128:131], v140 offset:2048
	ds_read_b128 v[140:143], v140 offset:3072
	v_lshl_add_u64 v[192:193], s[90:91], 0, v[230:231]
	s_add_i32 m0, s39, 0xc000
	ds_read_b128 v[152:155], v240
	ds_read_b128 v[156:159], v240 offset:1024
	ds_read_b128 v[160:163], v240 offset:2048
	ds_read_b128 v[164:167], v240 offset:3072
	ds_read_b128 v[168:171], v240 offset:4096
	ds_read_b128 v[180:183], v240 offset:5120
	ds_read_b128 v[184:187], v240 offset:6144
	ds_read_b128 v[188:191], v240 offset:7168
	global_load_lds_dwordx4 v[192:193], off
	v_lshl_add_u64 v[192:193], s[90:91], 0, v[232:233]
	s_add_i32 m0, s39, 0xe000
	s_nop 0
	global_load_lds_dwordx4 v[192:193], off
	s_waitcnt vmcnt(8)
	s_waitcnt lgkmcnt(0)
	s_barrier
	s_waitcnt lgkmcnt(0)
	v_mfma_f32_16x16x32_bf16 v[176:179], v[64:67], v[152:155], v[176:179]
	v_mfma_f32_16x16x32_bf16 v[176:179], v[72:75], v[156:159], v[176:179]
	v_mfma_f32_16x16x32_bf16 v[148:151], v[108:111], v[152:155], v[148:151]
	v_mfma_f32_16x16x32_bf16 v[148:151], v[116:119], v[156:159], v[148:151]
	v_mfma_f32_16x16x32_bf16 v[172:175], v[88:91], v[152:155], v[172:175]
	v_mfma_f32_16x16x32_bf16 v[172:175], v[96:99], v[156:159], v[172:175]
	v_mfma_f32_16x16x32_bf16 v[144:147], v[128:131], v[152:155], v[144:147]
	v_mfma_f32_16x16x32_bf16 v[144:147], v[140:143], v[156:159], v[144:147]
	v_mfma_f32_16x16x32_bf16 v[136:139], v[64:67], v[160:163], v[136:139]
	v_mfma_f32_16x16x32_bf16 v[136:139], v[72:75], v[164:167], v[136:139]
	v_mfma_f32_16x16x32_bf16 v[124:127], v[108:111], v[160:163], v[124:127]
	v_mfma_f32_16x16x32_bf16 v[124:127], v[116:119], v[164:167], v[124:127]
	v_mfma_f32_16x16x32_bf16 v[132:135], v[88:91], v[160:163], v[132:135]
	v_mfma_f32_16x16x32_bf16 v[132:135], v[96:99], v[164:167], v[132:135]
	v_mfma_f32_16x16x32_bf16 v[120:123], v[128:131], v[160:163], v[120:123]
	v_mfma_f32_16x16x32_bf16 v[120:123], v[140:143], v[164:167], v[120:123]
	v_mfma_f32_16x16x32_bf16 v[112:115], v[64:67], v[168:171], v[112:115]
	v_mfma_f32_16x16x32_bf16 v[112:115], v[72:75], v[180:183], v[112:115]
	v_mfma_f32_16x16x32_bf16 v[100:103], v[108:111], v[168:171], v[100:103]
	v_mfma_f32_16x16x32_bf16 v[100:103], v[116:119], v[180:183], v[100:103]
	v_mfma_f32_16x16x32_bf16 v[104:107], v[88:91], v[168:171], v[104:107]
	v_mfma_f32_16x16x32_bf16 v[104:107], v[96:99], v[180:183], v[104:107]
	v_mfma_f32_16x16x32_bf16 v[92:95], v[128:131], v[168:171], v[92:95]
	v_mfma_f32_16x16x32_bf16 v[92:95], v[140:143], v[180:183], v[92:95]
	v_mfma_f32_16x16x32_bf16 v[84:87], v[64:67], v[184:187], v[84:87]
	v_mfma_f32_16x16x32_bf16 v[84:87], v[72:75], v[188:191], v[84:87]
	v_mfma_f32_16x16x32_bf16 v[76:79], v[108:111], v[184:187], v[76:79]
	v_mfma_f32_16x16x32_bf16 v[76:79], v[116:119], v[188:191], v[76:79]
	v_mfma_f32_16x16x32_bf16 v[80:83], v[88:91], v[184:187], v[80:83]
	v_mfma_f32_16x16x32_bf16 v[80:83], v[96:99], v[188:191], v[80:83]
	v_mfma_f32_16x16x32_bf16 v[68:71], v[128:131], v[184:187], v[68:71]
	v_mfma_f32_16x16x32_bf16 v[68:71], v[140:143], v[188:191], v[68:71]
	s_barrier
	s_add_i32 s2, s67, s28
	v_lshl_add_u64 v[192:193], s[92:93], 0, v[216:217]
	s_mov_b32 m0, s2
	ds_read_b128 v[152:155], v240 offset:16384
	ds_read_b128 v[156:159], v240 offset:17408
	ds_read_b128 v[160:163], v240 offset:18432
	ds_read_b128 v[164:167], v240 offset:19456
	ds_read_b128 v[168:171], v240 offset:20480
	ds_read_b128 v[180:183], v240 offset:21504
	ds_read_b128 v[184:187], v240 offset:22528
	ds_read_b128 v[188:191], v240 offset:23552
	global_load_lds_dwordx4 v[192:193], off
	s_add_i32 m0, s2, 0x2000
	s_add_u32 s2, s92, 0x80000
	v_lshl_add_u64 v[194:195], s[92:93], 0, v[228:229]
	s_addc_u32 s3, s93, 0
	s_add_i32 s67, s76, s28
	global_load_lds_dwordx4 v[194:195], off
	v_lshl_add_u64 v[196:197], s[2:3], 0, v[216:217]
	s_mov_b32 m0, s67
	v_lshl_add_u64 v[198:199], s[94:95], 0, v[226:227]
	global_load_lds_dwordx4 v[196:197], off
	v_lshl_add_u64 v[196:197], s[2:3], 0, v[228:229]
	s_add_i32 m0, s67, 0x2000
	s_nop 0
	global_load_lds_dwordx4 v[196:197], off
	v_lshl_add_u64 v[196:197], s[94:95], 0, v[224:225]
	s_mov_b32 m0, s39
	s_nop 0
	global_load_lds_dwordx4 v[196:197], off
	s_mov_b32 m0, s53
	s_nop 0
	global_load_lds_dwordx4 v[198:199], off
	s_waitcnt vmcnt(8)
	s_waitcnt lgkmcnt(0)
	s_barrier
	s_waitcnt lgkmcnt(0)
	v_mfma_f32_16x16x32_bf16 v[60:63], v[64:67], v[152:155], v[60:63]
	v_mfma_f32_16x16x32_bf16 v[60:63], v[72:75], v[156:159], v[60:63]
	v_mfma_f32_16x16x32_bf16 v[52:55], v[108:111], v[152:155], v[52:55]
	v_mfma_f32_16x16x32_bf16 v[52:55], v[116:119], v[156:159], v[52:55]
	v_mfma_f32_16x16x32_bf16 v[56:59], v[88:91], v[152:155], v[56:59]
	v_mfma_f32_16x16x32_bf16 v[56:59], v[96:99], v[156:159], v[56:59]
	v_mfma_f32_16x16x32_bf16 v[48:51], v[128:131], v[152:155], v[48:51]
	v_mfma_f32_16x16x32_bf16 v[48:51], v[140:143], v[156:159], v[48:51]
	v_mfma_f32_16x16x32_bf16 v[44:47], v[64:67], v[160:163], v[44:47]
	v_mfma_f32_16x16x32_bf16 v[44:47], v[72:75], v[164:167], v[44:47]
	v_mfma_f32_16x16x32_bf16 v[36:39], v[108:111], v[160:163], v[36:39]
	v_mfma_f32_16x16x32_bf16 v[36:39], v[116:119], v[164:167], v[36:39]
	v_mfma_f32_16x16x32_bf16 v[40:43], v[88:91], v[160:163], v[40:43]
	v_mfma_f32_16x16x32_bf16 v[40:43], v[96:99], v[164:167], v[40:43]
	v_mfma_f32_16x16x32_bf16 v[32:35], v[128:131], v[160:163], v[32:35]
	v_mfma_f32_16x16x32_bf16 v[32:35], v[140:143], v[164:167], v[32:35]
	v_mfma_f32_16x16x32_bf16 v[28:31], v[64:67], v[168:171], v[28:31]
	v_mfma_f32_16x16x32_bf16 v[28:31], v[72:75], v[180:183], v[28:31]
	v_mfma_f32_16x16x32_bf16 v[20:23], v[108:111], v[168:171], v[20:23]
	v_mfma_f32_16x16x32_bf16 v[20:23], v[116:119], v[180:183], v[20:23]
	v_mfma_f32_16x16x32_bf16 v[24:27], v[88:91], v[168:171], v[24:27]
	v_mfma_f32_16x16x32_bf16 v[24:27], v[96:99], v[180:183], v[24:27]
	v_mfma_f32_16x16x32_bf16 v[16:19], v[128:131], v[168:171], v[16:19]
	v_mfma_f32_16x16x32_bf16 v[16:19], v[140:143], v[180:183], v[16:19]
	v_mfma_f32_16x16x32_bf16 v[12:15], v[64:67], v[184:187], v[12:15]
	v_mfma_f32_16x16x32_bf16 v[12:15], v[72:75], v[188:191], v[12:15]
	v_mfma_f32_16x16x32_bf16 v[4:7], v[108:111], v[184:187], v[4:7]
	v_mfma_f32_16x16x32_bf16 v[4:7], v[116:119], v[188:191], v[4:7]
	v_mfma_f32_16x16x32_bf16 v[8:11], v[88:91], v[184:187], v[8:11]
	v_mfma_f32_16x16x32_bf16 v[8:11], v[96:99], v[188:191], v[8:11]
	v_mfma_f32_16x16x32_bf16 v[0:3], v[128:131], v[184:187], v[0:3]
	v_mfma_f32_16x16x32_bf16 v[0:3], v[140:143], v[188:191], v[0:3]
	s_barrier
	s_add_i32 s67, 0, 0x18000
	s_add_i32 s76, 0, 0x1c000
	v_add_u32_e32 v96, s67, v238
	v_add_u32_e32 v140, s76, v238
	ds_read_b128 v[64:67], v96
	ds_read_b128 v[72:75], v96 offset:1024
	ds_read_b128 v[88:91], v96 offset:2048
	ds_read_b128 v[96:99], v96 offset:3072
	ds_read_b128 v[108:111], v140
	ds_read_b128 v[116:119], v140 offset:1024
	ds_read_b128 v[128:131], v140 offset:2048
	ds_read_b128 v[140:143], v140 offset:3072
	s_add_u32 s2, s94, 0x80000
	s_addc_u32 s3, s95, 0
	s_mov_b32 m0, s55
	v_lshl_add_u64 v[200:201], s[2:3], 0, v[224:225]
	ds_read_b128 v[152:155], v240 offset:32768
	ds_read_b128 v[156:159], v240 offset:33792
	ds_read_b128 v[160:163], v240 offset:34816
	ds_read_b128 v[164:167], v240 offset:35840
	ds_read_b128 v[168:171], v240 offset:36864
	ds_read_b128 v[180:183], v240 offset:37888
	ds_read_b128 v[184:187], v240 offset:38912
	ds_read_b128 v[188:191], v240 offset:39936
	global_load_lds_dwordx4 v[200:201], off
	v_lshl_add_u64 v[200:201], s[2:3], 0, v[226:227]
	s_mov_b32 m0, s56
	s_nop 0
	global_load_lds_dwordx4 v[200:201], off
	s_waitcnt vmcnt(8)
	s_waitcnt lgkmcnt(0)
	s_barrier
	s_waitcnt lgkmcnt(0)
	v_mfma_f32_16x16x32_bf16 v[176:179], v[64:67], v[152:155], v[176:179]
	v_mfma_f32_16x16x32_bf16 v[176:179], v[72:75], v[156:159], v[176:179]
	v_mfma_f32_16x16x32_bf16 v[148:151], v[108:111], v[152:155], v[148:151]
	v_mfma_f32_16x16x32_bf16 v[148:151], v[116:119], v[156:159], v[148:151]
	v_mfma_f32_16x16x32_bf16 v[172:175], v[88:91], v[152:155], v[172:175]
	v_mfma_f32_16x16x32_bf16 v[172:175], v[96:99], v[156:159], v[172:175]
	v_mfma_f32_16x16x32_bf16 v[144:147], v[128:131], v[152:155], v[144:147]
	v_mfma_f32_16x16x32_bf16 v[144:147], v[140:143], v[156:159], v[144:147]
	v_mfma_f32_16x16x32_bf16 v[136:139], v[64:67], v[160:163], v[136:139]
	v_mfma_f32_16x16x32_bf16 v[136:139], v[72:75], v[164:167], v[136:139]
	v_mfma_f32_16x16x32_bf16 v[124:127], v[108:111], v[160:163], v[124:127]
	v_mfma_f32_16x16x32_bf16 v[124:127], v[116:119], v[164:167], v[124:127]
	v_mfma_f32_16x16x32_bf16 v[132:135], v[88:91], v[160:163], v[132:135]
	v_mfma_f32_16x16x32_bf16 v[132:135], v[96:99], v[164:167], v[132:135]
	v_mfma_f32_16x16x32_bf16 v[120:123], v[128:131], v[160:163], v[120:123]
	v_mfma_f32_16x16x32_bf16 v[120:123], v[140:143], v[164:167], v[120:123]
	v_mfma_f32_16x16x32_bf16 v[112:115], v[64:67], v[168:171], v[112:115]
	v_mfma_f32_16x16x32_bf16 v[112:115], v[72:75], v[180:183], v[112:115]
	v_mfma_f32_16x16x32_bf16 v[100:103], v[108:111], v[168:171], v[100:103]
	v_mfma_f32_16x16x32_bf16 v[100:103], v[116:119], v[180:183], v[100:103]
	v_mfma_f32_16x16x32_bf16 v[104:107], v[88:91], v[168:171], v[104:107]
	v_mfma_f32_16x16x32_bf16 v[104:107], v[96:99], v[180:183], v[104:107]
	v_mfma_f32_16x16x32_bf16 v[92:95], v[128:131], v[168:171], v[92:95]
	v_mfma_f32_16x16x32_bf16 v[92:95], v[140:143], v[180:183], v[92:95]
	v_mfma_f32_16x16x32_bf16 v[84:87], v[64:67], v[184:187], v[84:87]
	v_mfma_f32_16x16x32_bf16 v[84:87], v[72:75], v[188:191], v[84:87]
	v_mfma_f32_16x16x32_bf16 v[76:79], v[108:111], v[184:187], v[76:79]
	v_mfma_f32_16x16x32_bf16 v[76:79], v[116:119], v[188:191], v[76:79]
	v_mfma_f32_16x16x32_bf16 v[80:83], v[88:91], v[184:187], v[80:83]
	v_mfma_f32_16x16x32_bf16 v[80:83], v[96:99], v[188:191], v[80:83]
	v_mfma_f32_16x16x32_bf16 v[68:71], v[128:131], v[184:187], v[68:71]
	v_mfma_f32_16x16x32_bf16 v[68:71], v[140:143], v[188:191], v[68:71]
	s_barrier
	s_add_i32 s2, s67, s28
	v_lshl_add_u64 v[192:193], v[192:193], 0, s[30:31]
	s_mov_b32 m0, s2
	ds_read_b128 v[152:155], v240 offset:49152
	ds_read_b128 v[156:159], v240 offset:50176
	ds_read_b128 v[160:163], v240 offset:51200
	ds_read_b128 v[164:167], v240 offset:52224
	ds_read_b128 v[168:171], v240 offset:53248
	ds_read_b128 v[180:183], v240 offset:54272
	ds_read_b128 v[184:187], v240 offset:55296
	ds_read_b128 v[188:191], v240 offset:56320
	global_load_lds_dwordx4 v[192:193], off
	s_add_i32 m0, s2, 0x2000
	s_add_u32 s2, s92, 0x80080
	v_lshl_add_u64 v[192:193], v[194:195], 0, s[30:31]
	s_addc_u32 s3, s93, 0
	s_add_i32 s67, s76, s28
	global_load_lds_dwordx4 v[192:193], off
	v_lshl_add_u64 v[192:193], s[2:3], 0, v[216:217]
	s_mov_b32 m0, s67
	s_nop 0
	global_load_lds_dwordx4 v[192:193], off
	v_lshl_add_u64 v[192:193], s[2:3], 0, v[228:229]
	s_add_i32 m0, s67, 0x2000
	s_nop 0
	global_load_lds_dwordx4 v[192:193], off
	v_lshl_add_u64 v[192:193], v[196:197], 0, s[30:31]
	s_mov_b32 m0, s70
	s_nop 0
	global_load_lds_dwordx4 v[192:193], off
	v_lshl_add_u64 v[192:193], v[198:199], 0, s[30:31]
	s_mov_b32 m0, s71
	s_nop 0
	global_load_lds_dwordx4 v[192:193], off
	s_waitcnt vmcnt(8)
	s_waitcnt lgkmcnt(0)
	s_barrier
	s_waitcnt lgkmcnt(0)
	v_mfma_f32_16x16x32_bf16 v[60:63], v[64:67], v[152:155], v[60:63]
	v_mfma_f32_16x16x32_bf16 v[60:63], v[72:75], v[156:159], v[60:63]
	v_mfma_f32_16x16x32_bf16 v[52:55], v[108:111], v[152:155], v[52:55]
	v_mfma_f32_16x16x32_bf16 v[52:55], v[116:119], v[156:159], v[52:55]
	v_mfma_f32_16x16x32_bf16 v[56:59], v[88:91], v[152:155], v[56:59]
	v_mfma_f32_16x16x32_bf16 v[56:59], v[96:99], v[156:159], v[56:59]
	v_mfma_f32_16x16x32_bf16 v[48:51], v[128:131], v[152:155], v[48:51]
	v_mfma_f32_16x16x32_bf16 v[48:51], v[140:143], v[156:159], v[48:51]
	v_mfma_f32_16x16x32_bf16 v[44:47], v[64:67], v[160:163], v[44:47]
	v_mfma_f32_16x16x32_bf16 v[44:47], v[72:75], v[164:167], v[44:47]
	v_mfma_f32_16x16x32_bf16 v[36:39], v[108:111], v[160:163], v[36:39]
	v_mfma_f32_16x16x32_bf16 v[36:39], v[116:119], v[164:167], v[36:39]
	v_mfma_f32_16x16x32_bf16 v[40:43], v[88:91], v[160:163], v[40:43]
	v_mfma_f32_16x16x32_bf16 v[40:43], v[96:99], v[164:167], v[40:43]
	v_mfma_f32_16x16x32_bf16 v[32:35], v[128:131], v[160:163], v[32:35]
	v_mfma_f32_16x16x32_bf16 v[32:35], v[140:143], v[164:167], v[32:35]
	v_mfma_f32_16x16x32_bf16 v[28:31], v[64:67], v[168:171], v[28:31]
	v_mfma_f32_16x16x32_bf16 v[28:31], v[72:75], v[180:183], v[28:31]
	v_mfma_f32_16x16x32_bf16 v[20:23], v[108:111], v[168:171], v[20:23]
	v_mfma_f32_16x16x32_bf16 v[20:23], v[116:119], v[180:183], v[20:23]
	v_mfma_f32_16x16x32_bf16 v[24:27], v[88:91], v[168:171], v[24:27]
	v_mfma_f32_16x16x32_bf16 v[24:27], v[96:99], v[180:183], v[24:27]
	v_mfma_f32_16x16x32_bf16 v[16:19], v[128:131], v[168:171], v[16:19]
	v_mfma_f32_16x16x32_bf16 v[16:19], v[140:143], v[180:183], v[16:19]
	v_mfma_f32_16x16x32_bf16 v[12:15], v[64:67], v[184:187], v[12:15]
	v_mfma_f32_16x16x32_bf16 v[12:15], v[72:75], v[188:191], v[12:15]
	v_mfma_f32_16x16x32_bf16 v[4:7], v[108:111], v[184:187], v[4:7]
	v_mfma_f32_16x16x32_bf16 v[4:7], v[116:119], v[188:191], v[4:7]
	v_mfma_f32_16x16x32_bf16 v[8:11], v[88:91], v[184:187], v[8:11]
	v_mfma_f32_16x16x32_bf16 v[8:11], v[96:99], v[188:191], v[8:11]
	v_mfma_f32_16x16x32_bf16 v[0:3], v[128:131], v[184:187], v[0:3]
	v_mfma_f32_16x16x32_bf16 v[0:3], v[140:143], v[188:191], v[0:3]
	s_barrier
	s_add_i32 s20, s20, 2
	s_add_u32 s90, s90, 0x100
	s_addc_u32 s91, s91, 0
	s_add_u32 s89, s89, 0x100
	s_addc_u32 s14, s14, 0
	s_cmp_gt_u32 s20, 29
	s_cbranch_scc0 .LBB0_595
	s_and_b64 vcc, exec, s[74:75]
	s_cbranch_vccz .LBB0_598
	s_barrier

.LBB0_638:
	s_ashr_i32 s87, s86, 31
	s_lshl_b64 s[40:41], s[86:87], 20
	s_add_u32 s88, s14, s40
	s_addc_u32 s89, s15, s41
	s_and_b64 s[40:41], s[4:5], exec
	s_cselect_b32 s7, s89, s11
	s_cselect_b32 s9, s88, s10
	s_ashr_i32 s85, s84, 31
	s_lshl_b64 s[40:41], s[84:85], 20
	s_add_u32 s90, s24, s40
	s_addc_u32 s91, s26, s41
	s_and_b64 s[40:41], s[4:5], exec
	s_cselect_b32 s40, s91, s93
	s_cselect_b32 s41, s90, s92
	s_add_u32 s10, s10, 0x80080
	s_addc_u32 s11, s11, 0
	s_add_u32 s54, s92, 0x100
	s_addc_u32 s55, s93, 0
	s_mov_b32 s85, -2
	s_add_u32 s67, s10, 0xfff80080
	s_addc_u32 s87, s11, -1
	s_add_i32 s96, 0, 0x10000
	s_cmp_eq_u32 s85, 28
	s_cselect_b32 s95, s7, s87
	s_cselect_b32 s94, s9, s67
	s_cselect_b32 s93, s40, s55
	s_cselect_b32 s92, s41, s54
	s_add_i32 s67, 0, 0x14000
	v_add_u32_e32 v52, s96, v194
	v_add_u32_e32 v124, s67, v194
	ds_read_b128 v[40:43], v52
	ds_read_b128 v[44:47], v52 offset:1024
	ds_read_b128 v[48:51], v52 offset:2048
	ds_read_b128 v[52:55], v52 offset:3072
	ds_read_b128 v[64:67], v124
	ds_read_b128 v[100:103], v124 offset:1024
	ds_read_b128 v[120:123], v124 offset:2048
	ds_read_b128 v[124:127], v124 offset:3072
	v_lshl_add_u64 v[208:209], s[10:11], 0, v[186:187]
	s_add_i32 m0, s57, 0xc000
	ds_read_b128 v[136:139], v195
	ds_read_b128 v[140:143], v195 offset:1024
	ds_read_b128 v[144:147], v195 offset:2048
	ds_read_b128 v[172:175], v195 offset:3072
	ds_read_b128 v[190:193], v195 offset:4096
	ds_read_b128 v[196:199], v195 offset:5120
	ds_read_b128 v[200:203], v195 offset:6144
	ds_read_b128 v[204:207], v195 offset:7168
	global_load_lds_dwordx4 v[208:209], off
	v_lshl_add_u64 v[208:209], s[10:11], 0, v[188:189]
	s_add_i32 m0, s57, 0xe000
	s_nop 0
	global_load_lds_dwordx4 v[208:209], off
	s_waitcnt vmcnt(8)
	s_waitcnt lgkmcnt(0)
	s_barrier
	s_waitcnt lgkmcnt(0)
	v_mfma_f32_16x16x32_bf16 v[168:171], v[40:43], v[136:139], 0
	v_mfma_f32_16x16x32_bf16 v[168:171], v[44:47], v[140:143], v[168:171]
	v_mfma_f32_16x16x32_bf16 v[160:163], v[64:67], v[136:139], 0
	v_mfma_f32_16x16x32_bf16 v[160:163], v[100:103], v[140:143], v[160:163]
	v_mfma_f32_16x16x32_bf16 v[164:167], v[48:51], v[136:139], 0
	v_mfma_f32_16x16x32_bf16 v[164:167], v[52:55], v[140:143], v[164:167]
	v_mfma_f32_16x16x32_bf16 v[132:135], v[64:67], v[144:147], 0
	v_mfma_f32_16x16x32_bf16 v[132:135], v[100:103], v[172:175], v[132:135]
	v_mfma_f32_16x16x32_bf16 v[152:155], v[40:43], v[144:147], 0
	v_mfma_f32_16x16x32_bf16 v[152:155], v[44:47], v[172:175], v[152:155]
	v_mfma_f32_16x16x32_bf16 v[128:131], v[120:123], v[144:147], 0
	v_mfma_f32_16x16x32_bf16 v[128:131], v[124:127], v[172:175], v[128:131]
	v_mfma_f32_16x16x32_bf16 v[148:151], v[48:51], v[144:147], 0
	v_mfma_f32_16x16x32_bf16 v[148:151], v[52:55], v[172:175], v[148:151]
	v_mfma_f32_16x16x32_bf16 v[108:111], v[64:67], v[190:193], 0
	v_mfma_f32_16x16x32_bf16 v[108:111], v[100:103], v[196:199], v[108:111]
	v_mfma_f32_16x16x32_bf16 v[116:119], v[40:43], v[190:193], 0
	v_mfma_f32_16x16x32_bf16 v[116:119], v[44:47], v[196:199], v[116:119]
	v_mfma_f32_16x16x32_bf16 v[104:107], v[120:123], v[190:193], 0
	v_mfma_f32_16x16x32_bf16 v[104:107], v[124:127], v[196:199], v[104:107]
	v_mfma_f32_16x16x32_bf16 v[112:115], v[48:51], v[190:193], 0
	v_mfma_f32_16x16x32_bf16 v[112:115], v[52:55], v[196:199], v[112:115]
	v_mfma_f32_16x16x32_bf16 v[88:91], v[64:67], v[200:203], 0
	v_mfma_f32_16x16x32_bf16 v[88:91], v[100:103], v[204:207], v[88:91]
	v_mfma_f32_16x16x32_bf16 v[96:99], v[40:43], v[200:203], 0
	v_mfma_f32_16x16x32_bf16 v[96:99], v[44:47], v[204:207], v[96:99]
	v_mfma_f32_16x16x32_bf16 v[84:87], v[120:123], v[200:203], 0
	v_mfma_f32_16x16x32_bf16 v[84:87], v[124:127], v[204:207], v[84:87]
	v_mfma_f32_16x16x32_bf16 v[92:95], v[48:51], v[200:203], 0
	v_mfma_f32_16x16x32_bf16 v[92:95], v[52:55], v[204:207], v[92:95]
	v_mfma_f32_16x16x32_bf16 v[136:139], v[120:123], v[136:139], 0
	v_mfma_f32_16x16x32_bf16 v[136:139], v[124:127], v[140:143], v[136:139]
	s_barrier
	s_add_i32 s87, s96, s56
	v_lshl_add_u64 v[212:213], s[92:93], 0, v[178:179]
	s_mov_b32 m0, s87
	ds_read_b128 v[140:143], v195 offset:16384
	ds_read_b128 v[144:147], v195 offset:17408
	ds_read_b128 v[156:159], v195 offset:18432
	ds_read_b128 v[172:175], v195 offset:19456
	ds_read_b128 v[190:193], v195 offset:20480
	ds_read_b128 v[196:199], v195 offset:21504
	ds_read_b128 v[200:203], v195 offset:22528
	ds_read_b128 v[204:207], v195 offset:23552
	global_load_lds_dwordx4 v[212:213], off
	s_add_i32 m0, s87, 0x2000
	s_add_u32 vcc_lo, s92, 0x80000
	v_lshl_add_u64 v[214:215], s[92:93], 0, v[182:183]
	s_addc_u32 vcc_hi, s93, 0
	s_add_i32 s67, s67, s56
	global_load_lds_dwordx4 v[214:215], off
	v_lshl_add_u64 v[208:209], vcc, 0, v[178:179]
	s_mov_b32 m0, s67
	v_lshl_add_u64 v[224:225], s[94:95], 0, v[176:177]
	global_load_lds_dwordx4 v[208:209], off
	v_lshl_add_u64 v[208:209], vcc, 0, v[182:183]
	s_add_i32 m0, s67, 0x2000
	v_lshl_add_u64 v[226:227], s[94:95], 0, v[180:181]
	global_load_lds_dwordx4 v[208:209], off
	s_mov_b32 m0, s57
	s_nop 0
	global_load_lds_dwordx4 v[224:225], off
	s_mov_b32 m0, s61
	s_nop 0
	global_load_lds_dwordx4 v[226:227], off
	s_waitcnt vmcnt(8)
	s_waitcnt lgkmcnt(0)
	s_barrier
	s_waitcnt lgkmcnt(0)
	v_mfma_f32_16x16x32_bf16 v[80:83], v[40:43], v[140:143], 0
	v_mfma_f32_16x16x32_bf16 v[80:83], v[44:47], v[144:147], v[80:83]
	v_mfma_f32_16x16x32_bf16 v[36:39], v[64:67], v[156:159], 0
	v_mfma_f32_16x16x32_bf16 v[36:39], v[100:103], v[172:175], v[36:39]
	v_mfma_f32_16x16x32_bf16 v[76:79], v[48:51], v[140:143], 0
	v_mfma_f32_16x16x32_bf16 v[76:79], v[52:55], v[144:147], v[76:79]
	v_mfma_f32_16x16x32_bf16 v[32:35], v[120:123], v[156:159], 0
	v_mfma_f32_16x16x32_bf16 v[32:35], v[124:127], v[172:175], v[32:35]
	v_mfma_f32_16x16x32_bf16 v[60:63], v[40:43], v[156:159], 0
	v_mfma_f32_16x16x32_bf16 v[60:63], v[44:47], v[172:175], v[60:63]
	v_mfma_f32_16x16x32_bf16 v[20:23], v[64:67], v[190:193], 0
	v_mfma_f32_16x16x32_bf16 v[20:23], v[100:103], v[196:199], v[20:23]
	v_mfma_f32_16x16x32_bf16 v[56:59], v[48:51], v[156:159], 0
	v_mfma_f32_16x16x32_bf16 v[56:59], v[52:55], v[172:175], v[56:59]
	v_mfma_f32_16x16x32_bf16 v[16:19], v[120:123], v[190:193], 0
	v_mfma_f32_16x16x32_bf16 v[16:19], v[124:127], v[196:199], v[16:19]
	v_mfma_f32_16x16x32_bf16 v[28:31], v[40:43], v[190:193], 0
	v_mfma_f32_16x16x32_bf16 v[28:31], v[44:47], v[196:199], v[28:31]
	v_mfma_f32_16x16x32_bf16 v[4:7], v[64:67], v[200:203], 0
	v_mfma_f32_16x16x32_bf16 v[4:7], v[100:103], v[204:207], v[4:7]
	v_mfma_f32_16x16x32_bf16 v[24:27], v[48:51], v[190:193], 0
	v_mfma_f32_16x16x32_bf16 v[24:27], v[52:55], v[196:199], v[24:27]
	v_mfma_f32_16x16x32_bf16 v[0:3], v[120:123], v[200:203], 0
	v_mfma_f32_16x16x32_bf16 v[0:3], v[124:127], v[204:207], v[0:3]
	v_mfma_f32_16x16x32_bf16 v[12:15], v[40:43], v[200:203], 0
	v_mfma_f32_16x16x32_bf16 v[12:15], v[44:47], v[204:207], v[12:15]
	v_mfma_f32_16x16x32_bf16 v[40:43], v[64:67], v[140:143], 0
	v_mfma_f32_16x16x32_bf16 v[40:43], v[100:103], v[144:147], v[40:43]
	v_mfma_f32_16x16x32_bf16 v[8:11], v[48:51], v[200:203], 0
	v_mfma_f32_16x16x32_bf16 v[8:11], v[52:55], v[204:207], v[8:11]
	v_mfma_f32_16x16x32_bf16 v[44:47], v[120:123], v[140:143], 0
	v_mfma_f32_16x16x32_bf16 v[44:47], v[124:127], v[144:147], v[44:47]
	s_barrier
	s_add_i32 s67, 0, 0x18000
	s_add_i32 s87, 0, 0x1c000
	v_add_u32_e32 v68, s67, v194
	v_add_u32_e32 v72, s87, v194
	ds_read_b128 v[48:51], v68
	ds_read_b128 v[52:55], v68 offset:1024
	ds_read_b128 v[64:67], v68 offset:2048
	ds_read_b128 v[68:71], v68 offset:3072
	ds_read_b128 v[100:103], v72
	ds_read_b128 v[120:123], v72 offset:1024
	ds_read_b128 v[124:127], v72 offset:2048
	ds_read_b128 v[140:143], v72 offset:3072
	s_add_u32 s94, s94, 0x80000
	s_addc_u32 s95, s95, 0
	s_mov_b32 m0, s68
	v_lshl_add_u64 v[156:157], s[94:95], 0, v[176:177]
	ds_read_b128 v[72:75], v195 offset:32768
	ds_read_b128 v[144:147], v195 offset:33792
	ds_read_b128 v[172:175], v195 offset:34816
	ds_read_b128 v[190:193], v195 offset:35840
	ds_read_b128 v[196:199], v195 offset:36864
	ds_read_b128 v[200:203], v195 offset:37888
	ds_read_b128 v[204:207], v195 offset:38912
	ds_read_b128 v[208:211], v195 offset:39936
	global_load_lds_dwordx4 v[156:157], off
	v_lshl_add_u64 v[156:157], s[94:95], 0, v[180:181]
	s_mov_b32 m0, s69
	s_nop 0
	global_load_lds_dwordx4 v[156:157], off
	s_waitcnt vmcnt(8)
	s_waitcnt lgkmcnt(0)
	s_barrier
	s_waitcnt lgkmcnt(0)
	v_mfma_f32_16x16x32_bf16 v[156:159], v[48:51], v[72:75], v[168:171]
	v_mfma_f32_16x16x32_bf16 v[168:171], v[52:55], v[144:147], v[156:159]
	v_mfma_f32_16x16x32_bf16 v[156:159], v[64:67], v[72:75], v[164:167]
	v_mfma_f32_16x16x32_bf16 v[164:167], v[68:71], v[144:147], v[156:159]
	v_mfma_f32_16x16x32_bf16 v[152:155], v[48:51], v[172:175], v[152:155]
	v_mfma_f32_16x16x32_bf16 v[152:155], v[52:55], v[190:193], v[152:155]
	v_mfma_f32_16x16x32_bf16 v[148:151], v[64:67], v[172:175], v[148:151]
	v_mfma_f32_16x16x32_bf16 v[148:151], v[68:71], v[190:193], v[148:151]
	v_mfma_f32_16x16x32_bf16 v[116:119], v[48:51], v[196:199], v[116:119]
	v_mfma_f32_16x16x32_bf16 v[116:119], v[52:55], v[200:203], v[116:119]
	v_mfma_f32_16x16x32_bf16 v[112:115], v[64:67], v[196:199], v[112:115]
	v_mfma_f32_16x16x32_bf16 v[112:115], v[68:71], v[200:203], v[112:115]
	v_mfma_f32_16x16x32_bf16 v[96:99], v[48:51], v[204:207], v[96:99]
	v_mfma_f32_16x16x32_bf16 v[96:99], v[52:55], v[208:211], v[96:99]
	v_mfma_f32_16x16x32_bf16 v[92:95], v[64:67], v[204:207], v[92:95]
	v_mfma_f32_16x16x32_bf16 v[92:95], v[68:71], v[208:211], v[92:95]
	v_mfma_f32_16x16x32_bf16 v[156:159], v[100:103], v[72:75], v[160:163]
	v_mfma_f32_16x16x32_bf16 v[160:163], v[120:123], v[144:147], v[156:159]
	v_mfma_f32_16x16x32_bf16 v[72:75], v[124:127], v[72:75], v[136:139]
	v_mfma_f32_16x16x32_bf16 v[156:159], v[140:143], v[144:147], v[72:75]
	v_mfma_f32_16x16x32_bf16 v[72:75], v[100:103], v[172:175], v[132:135]
	v_mfma_f32_16x16x32_bf16 v[132:135], v[120:123], v[190:193], v[72:75]
	v_mfma_f32_16x16x32_bf16 v[72:75], v[124:127], v[172:175], v[128:131]
	v_mfma_f32_16x16x32_bf16 v[128:131], v[140:143], v[190:193], v[72:75]
	v_mfma_f32_16x16x32_bf16 v[72:75], v[100:103], v[196:199], v[108:111]
	v_mfma_f32_16x16x32_bf16 v[108:111], v[120:123], v[200:203], v[72:75]
	v_mfma_f32_16x16x32_bf16 v[72:75], v[124:127], v[196:199], v[104:107]
	v_mfma_f32_16x16x32_bf16 v[104:107], v[140:143], v[200:203], v[72:75]
	v_mfma_f32_16x16x32_bf16 v[72:75], v[100:103], v[204:207], v[88:91]
	v_mfma_f32_16x16x32_bf16 v[88:91], v[120:123], v[208:211], v[72:75]
	v_mfma_f32_16x16x32_bf16 v[72:75], v[124:127], v[204:207], v[84:87]
	v_mfma_f32_16x16x32_bf16 v[84:87], v[140:143], v[208:211], v[72:75]
	s_barrier
	s_add_i32 s67, s67, s56
	s_nop 3
	v_lshl_add_u64 v[72:73], v[212:213], 0, s[30:31]
	s_mov_b32 m0, s67
	ds_read_b128 v[136:139], v195 offset:49152
	ds_read_b128 v[144:147], v195 offset:50176
	ds_read_b128 v[172:175], v195 offset:51200
	ds_read_b128 v[190:193], v195 offset:52224
	ds_read_b128 v[196:199], v195 offset:53248
	ds_read_b128 v[200:203], v195 offset:54272
	ds_read_b128 v[204:207], v195 offset:55296
	ds_read_b128 v[208:211], v195 offset:56320
	global_load_lds_dwordx4 v[72:73], off
	s_add_i32 m0, s67, 0x2000
	s_add_u32 s92, s92, 0x80080
	v_lshl_add_u64 v[72:73], v[214:215], 0, s[30:31]
	s_addc_u32 s93, s93, 0
	s_add_i32 s67, s87, s56
	global_load_lds_dwordx4 v[72:73], off
	v_lshl_add_u64 v[72:73], s[92:93], 0, v[178:179]
	s_mov_b32 m0, s67
	s_nop 0
	global_load_lds_dwordx4 v[72:73], off
	v_lshl_add_u64 v[72:73], s[92:93], 0, v[182:183]
	s_add_i32 m0, s67, 0x2000
	s_nop 0
	global_load_lds_dwordx4 v[72:73], off
	v_lshl_add_u64 v[72:73], v[224:225], 0, s[30:31]
	s_mov_b32 m0, s2
	s_nop 0
	global_load_lds_dwordx4 v[72:73], off
	v_lshl_add_u64 v[72:73], v[226:227], 0, s[30:31]
	s_mov_b32 m0, s28
	s_nop 0
	global_load_lds_dwordx4 v[72:73], off
	s_waitcnt vmcnt(8)
	s_waitcnt lgkmcnt(0)
	s_barrier
	s_waitcnt lgkmcnt(0)
	v_mfma_f32_16x16x32_bf16 v[72:75], v[48:51], v[136:139], v[80:83]
	v_mfma_f32_16x16x32_bf16 v[80:83], v[52:55], v[144:147], v[72:75]
	v_mfma_f32_16x16x32_bf16 v[72:75], v[64:67], v[136:139], v[76:79]
	v_mfma_f32_16x16x32_bf16 v[76:79], v[68:71], v[144:147], v[72:75]
	v_mfma_f32_16x16x32_bf16 v[60:63], v[48:51], v[172:175], v[60:63]
	v_mfma_f32_16x16x32_bf16 v[60:63], v[52:55], v[190:193], v[60:63]
	v_mfma_f32_16x16x32_bf16 v[56:59], v[64:67], v[172:175], v[56:59]
	v_mfma_f32_16x16x32_bf16 v[56:59], v[68:71], v[190:193], v[56:59]
	v_mfma_f32_16x16x32_bf16 v[28:31], v[48:51], v[196:199], v[28:31]
	v_mfma_f32_16x16x32_bf16 v[28:31], v[52:55], v[200:203], v[28:31]
	v_mfma_f32_16x16x32_bf16 v[24:27], v[64:67], v[196:199], v[24:27]
	v_mfma_f32_16x16x32_bf16 v[24:27], v[68:71], v[200:203], v[24:27]
	v_mfma_f32_16x16x32_bf16 v[12:15], v[48:51], v[204:207], v[12:15]
	v_mfma_f32_16x16x32_bf16 v[12:15], v[52:55], v[208:211], v[12:15]
	v_mfma_f32_16x16x32_bf16 v[8:11], v[64:67], v[204:207], v[8:11]
	v_mfma_f32_16x16x32_bf16 v[8:11], v[68:71], v[208:211], v[8:11]
	v_mfma_f32_16x16x32_bf16 v[40:43], v[100:103], v[136:139], v[40:43]
	v_mfma_f32_16x16x32_bf16 v[72:75], v[120:123], v[144:147], v[40:43]
	v_mfma_f32_16x16x32_bf16 v[40:43], v[124:127], v[136:139], v[44:47]
	v_mfma_f32_16x16x32_bf16 v[68:71], v[140:143], v[144:147], v[40:43]
	v_mfma_f32_16x16x32_bf16 v[36:39], v[100:103], v[172:175], v[36:39]
	v_mfma_f32_16x16x32_bf16 v[36:39], v[120:123], v[190:193], v[36:39]
	v_mfma_f32_16x16x32_bf16 v[32:35], v[124:127], v[172:175], v[32:35]
	v_mfma_f32_16x16x32_bf16 v[32:35], v[140:143], v[190:193], v[32:35]
	v_mfma_f32_16x16x32_bf16 v[20:23], v[100:103], v[196:199], v[20:23]
	v_mfma_f32_16x16x32_bf16 v[20:23], v[120:123], v[200:203], v[20:23]
	v_mfma_f32_16x16x32_bf16 v[16:19], v[124:127], v[196:199], v[16:19]
	v_mfma_f32_16x16x32_bf16 v[16:19], v[140:143], v[200:203], v[16:19]
	v_mfma_f32_16x16x32_bf16 v[4:7], v[100:103], v[204:207], v[4:7]
	v_mfma_f32_16x16x32_bf16 v[4:7], v[120:123], v[208:211], v[4:7]
	v_mfma_f32_16x16x32_bf16 v[0:3], v[124:127], v[204:207], v[0:3]
	v_mfma_f32_16x16x32_bf16 v[0:3], v[140:143], v[208:211], v[0:3]
	s_barrier
	s_add_i32 s85, s85, 2
	s_add_u32 s10, s10, 0x100
	s_addc_u32 s11, s11, 0
	s_add_u32 s54, s54, 0x100
	s_addc_u32 s55, s55, 0
.LBB0_639:
	s_add_u32 s67, s10, 0xfff80080
	s_addc_u32 s87, s11, -1
	s_add_i32 s96, 0, 0x10000
	s_cmp_eq_u32 s85, 28
	s_cselect_b32 s95, s7, s87
	s_cselect_b32 s94, s9, s67
	s_cselect_b32 s93, s40, s55
	s_cselect_b32 s92, s41, s54
	s_add_i32 s67, 0, 0x14000
	v_add_u32_e32 v52, s96, v194
	v_add_u32_e32 v124, s67, v194
	ds_read_b128 v[40:43], v52
	ds_read_b128 v[44:47], v52 offset:1024
	ds_read_b128 v[48:51], v52 offset:2048
	ds_read_b128 v[52:55], v52 offset:3072
	ds_read_b128 v[64:67], v124
	ds_read_b128 v[100:103], v124 offset:1024
	ds_read_b128 v[120:123], v124 offset:2048
	ds_read_b128 v[124:127], v124 offset:3072
	v_lshl_add_u64 v[208:209], s[10:11], 0, v[186:187]
	s_add_i32 m0, s57, 0xc000
	ds_read_b128 v[136:139], v195
	ds_read_b128 v[140:143], v195 offset:1024
	ds_read_b128 v[144:147], v195 offset:2048
	ds_read_b128 v[172:175], v195 offset:3072
	ds_read_b128 v[190:193], v195 offset:4096
	ds_read_b128 v[196:199], v195 offset:5120
	ds_read_b128 v[200:203], v195 offset:6144
	ds_read_b128 v[204:207], v195 offset:7168
	global_load_lds_dwordx4 v[208:209], off
	v_lshl_add_u64 v[208:209], s[10:11], 0, v[188:189]
	s_add_i32 m0, s57, 0xe000
	s_nop 0
	global_load_lds_dwordx4 v[208:209], off
	s_waitcnt vmcnt(8)
	s_waitcnt lgkmcnt(0)
	s_barrier
	s_waitcnt lgkmcnt(0)
	v_mfma_f32_16x16x32_bf16 v[168:171], v[40:43], v[136:139], v[168:171]
	v_mfma_f32_16x16x32_bf16 v[168:171], v[44:47], v[140:143], v[168:171]
	v_mfma_f32_16x16x32_bf16 v[160:163], v[64:67], v[136:139], v[160:163]
	v_mfma_f32_16x16x32_bf16 v[160:163], v[100:103], v[140:143], v[160:163]
	v_mfma_f32_16x16x32_bf16 v[164:167], v[48:51], v[136:139], v[164:167]
	v_mfma_f32_16x16x32_bf16 v[164:167], v[52:55], v[140:143], v[164:167]
	v_mfma_f32_16x16x32_bf16 v[132:135], v[64:67], v[144:147], v[132:135]
	v_mfma_f32_16x16x32_bf16 v[132:135], v[100:103], v[172:175], v[132:135]
	v_mfma_f32_16x16x32_bf16 v[152:155], v[40:43], v[144:147], v[152:155]
	v_mfma_f32_16x16x32_bf16 v[152:155], v[44:47], v[172:175], v[152:155]
	v_mfma_f32_16x16x32_bf16 v[128:131], v[120:123], v[144:147], v[128:131]
	v_mfma_f32_16x16x32_bf16 v[128:131], v[124:127], v[172:175], v[128:131]
	v_mfma_f32_16x16x32_bf16 v[148:151], v[48:51], v[144:147], v[148:151]
	v_mfma_f32_16x16x32_bf16 v[148:151], v[52:55], v[172:175], v[148:151]
	v_mfma_f32_16x16x32_bf16 v[108:111], v[64:67], v[190:193], v[108:111]
	v_mfma_f32_16x16x32_bf16 v[108:111], v[100:103], v[196:199], v[108:111]
	v_mfma_f32_16x16x32_bf16 v[116:119], v[40:43], v[190:193], v[116:119]
	v_mfma_f32_16x16x32_bf16 v[116:119], v[44:47], v[196:199], v[116:119]
	v_mfma_f32_16x16x32_bf16 v[104:107], v[120:123], v[190:193], v[104:107]
	v_mfma_f32_16x16x32_bf16 v[104:107], v[124:127], v[196:199], v[104:107]
	v_mfma_f32_16x16x32_bf16 v[112:115], v[48:51], v[190:193], v[112:115]
	v_mfma_f32_16x16x32_bf16 v[112:115], v[52:55], v[196:199], v[112:115]
	v_mfma_f32_16x16x32_bf16 v[88:91], v[64:67], v[200:203], v[88:91]
	v_mfma_f32_16x16x32_bf16 v[88:91], v[100:103], v[204:207], v[88:91]
	v_mfma_f32_16x16x32_bf16 v[96:99], v[40:43], v[200:203], v[96:99]
	v_mfma_f32_16x16x32_bf16 v[96:99], v[44:47], v[204:207], v[96:99]
	v_mfma_f32_16x16x32_bf16 v[84:87], v[120:123], v[200:203], v[84:87]
	v_mfma_f32_16x16x32_bf16 v[84:87], v[124:127], v[204:207], v[84:87]
	v_mfma_f32_16x16x32_bf16 v[92:95], v[48:51], v[200:203], v[92:95]
	v_mfma_f32_16x16x32_bf16 v[92:95], v[52:55], v[204:207], v[92:95]
	v_mfma_f32_16x16x32_bf16 v[136:139], v[120:123], v[136:139], v[156:159]
	v_mfma_f32_16x16x32_bf16 v[136:139], v[124:127], v[140:143], v[136:139]
	s_barrier
	s_add_i32 s87, s96, s56
	v_lshl_add_u64 v[212:213], s[92:93], 0, v[178:179]
	s_mov_b32 m0, s87
	ds_read_b128 v[140:143], v195 offset:16384
	ds_read_b128 v[144:147], v195 offset:17408
	ds_read_b128 v[156:159], v195 offset:18432
	ds_read_b128 v[172:175], v195 offset:19456
	ds_read_b128 v[190:193], v195 offset:20480
	ds_read_b128 v[196:199], v195 offset:21504
	ds_read_b128 v[200:203], v195 offset:22528
	ds_read_b128 v[204:207], v195 offset:23552
	global_load_lds_dwordx4 v[212:213], off
	s_add_i32 m0, s87, 0x2000
	s_add_u32 vcc_lo, s92, 0x80000
	v_lshl_add_u64 v[214:215], s[92:93], 0, v[182:183]
	s_addc_u32 vcc_hi, s93, 0
	s_add_i32 s67, s67, s56
	global_load_lds_dwordx4 v[214:215], off
	v_lshl_add_u64 v[208:209], vcc, 0, v[178:179]
	s_mov_b32 m0, s67
	v_lshl_add_u64 v[224:225], s[94:95], 0, v[176:177]
	global_load_lds_dwordx4 v[208:209], off
	v_lshl_add_u64 v[208:209], vcc, 0, v[182:183]
	s_add_i32 m0, s67, 0x2000
	v_lshl_add_u64 v[226:227], s[94:95], 0, v[180:181]
	global_load_lds_dwordx4 v[208:209], off
	s_mov_b32 m0, s57
	s_nop 0
	global_load_lds_dwordx4 v[224:225], off
	s_mov_b32 m0, s61
	s_nop 0
	global_load_lds_dwordx4 v[226:227], off
	s_waitcnt vmcnt(8)
	s_waitcnt lgkmcnt(0)
	s_barrier
	s_waitcnt lgkmcnt(0)
	v_mfma_f32_16x16x32_bf16 v[80:83], v[40:43], v[140:143], v[80:83]
	v_mfma_f32_16x16x32_bf16 v[80:83], v[44:47], v[144:147], v[80:83]
	v_mfma_f32_16x16x32_bf16 v[36:39], v[64:67], v[156:159], v[36:39]
	v_mfma_f32_16x16x32_bf16 v[36:39], v[100:103], v[172:175], v[36:39]
	v_mfma_f32_16x16x32_bf16 v[76:79], v[48:51], v[140:143], v[76:79]
	v_mfma_f32_16x16x32_bf16 v[76:79], v[52:55], v[144:147], v[76:79]
	v_mfma_f32_16x16x32_bf16 v[32:35], v[120:123], v[156:159], v[32:35]
	v_mfma_f32_16x16x32_bf16 v[32:35], v[124:127], v[172:175], v[32:35]
	v_mfma_f32_16x16x32_bf16 v[60:63], v[40:43], v[156:159], v[60:63]
	v_mfma_f32_16x16x32_bf16 v[60:63], v[44:47], v[172:175], v[60:63]
	v_mfma_f32_16x16x32_bf16 v[20:23], v[64:67], v[190:193], v[20:23]
	v_mfma_f32_16x16x32_bf16 v[20:23], v[100:103], v[196:199], v[20:23]
	v_mfma_f32_16x16x32_bf16 v[56:59], v[48:51], v[156:159], v[56:59]
	v_mfma_f32_16x16x32_bf16 v[56:59], v[52:55], v[172:175], v[56:59]
	v_mfma_f32_16x16x32_bf16 v[16:19], v[120:123], v[190:193], v[16:19]
	v_mfma_f32_16x16x32_bf16 v[16:19], v[124:127], v[196:199], v[16:19]
	v_mfma_f32_16x16x32_bf16 v[28:31], v[40:43], v[190:193], v[28:31]
	v_mfma_f32_16x16x32_bf16 v[28:31], v[44:47], v[196:199], v[28:31]
	v_mfma_f32_16x16x32_bf16 v[4:7], v[64:67], v[200:203], v[4:7]
	v_mfma_f32_16x16x32_bf16 v[4:7], v[100:103], v[204:207], v[4:7]
	v_mfma_f32_16x16x32_bf16 v[24:27], v[48:51], v[190:193], v[24:27]
	v_mfma_f32_16x16x32_bf16 v[24:27], v[52:55], v[196:199], v[24:27]
	v_mfma_f32_16x16x32_bf16 v[0:3], v[120:123], v[200:203], v[0:3]
	v_mfma_f32_16x16x32_bf16 v[0:3], v[124:127], v[204:207], v[0:3]
	v_mfma_f32_16x16x32_bf16 v[12:15], v[40:43], v[200:203], v[12:15]
	v_mfma_f32_16x16x32_bf16 v[12:15], v[44:47], v[204:207], v[12:15]
	v_mfma_f32_16x16x32_bf16 v[40:43], v[64:67], v[140:143], v[72:75]
	v_mfma_f32_16x16x32_bf16 v[40:43], v[100:103], v[144:147], v[40:43]
	v_mfma_f32_16x16x32_bf16 v[8:11], v[48:51], v[200:203], v[8:11]
	v_mfma_f32_16x16x32_bf16 v[8:11], v[52:55], v[204:207], v[8:11]
	v_mfma_f32_16x16x32_bf16 v[44:47], v[120:123], v[140:143], v[68:71]
	v_mfma_f32_16x16x32_bf16 v[44:47], v[124:127], v[144:147], v[44:47]
	s_barrier
	s_add_i32 s67, 0, 0x18000
	s_add_i32 s87, 0, 0x1c000
	v_add_u32_e32 v68, s67, v194
	v_add_u32_e32 v72, s87, v194
	ds_read_b128 v[48:51], v68
	ds_read_b128 v[52:55], v68 offset:1024
	ds_read_b128 v[64:67], v68 offset:2048
	ds_read_b128 v[68:71], v68 offset:3072
	ds_read_b128 v[100:103], v72
	ds_read_b128 v[120:123], v72 offset:1024
	ds_read_b128 v[124:127], v72 offset:2048
	ds_read_b128 v[140:143], v72 offset:3072
	s_add_u32 s94, s94, 0x80000
	s_addc_u32 s95, s95, 0
	s_mov_b32 m0, s68
	v_lshl_add_u64 v[156:157], s[94:95], 0, v[176:177]
	ds_read_b128 v[72:75], v195 offset:32768
	ds_read_b128 v[144:147], v195 offset:33792
	ds_read_b128 v[172:175], v195 offset:34816
	ds_read_b128 v[190:193], v195 offset:35840
	ds_read_b128 v[196:199], v195 offset:36864
	ds_read_b128 v[200:203], v195 offset:37888
	ds_read_b128 v[204:207], v195 offset:38912
	ds_read_b128 v[208:211], v195 offset:39936
	global_load_lds_dwordx4 v[156:157], off
	v_lshl_add_u64 v[156:157], s[94:95], 0, v[180:181]
	s_mov_b32 m0, s69
	s_nop 0
	global_load_lds_dwordx4 v[156:157], off
	s_waitcnt vmcnt(8)
	s_waitcnt lgkmcnt(0)
	s_barrier
	s_waitcnt lgkmcnt(0)
	v_mfma_f32_16x16x32_bf16 v[156:159], v[48:51], v[72:75], v[168:171]
	v_mfma_f32_16x16x32_bf16 v[168:171], v[52:55], v[144:147], v[156:159]
	v_mfma_f32_16x16x32_bf16 v[156:159], v[64:67], v[72:75], v[164:167]
	v_mfma_f32_16x16x32_bf16 v[164:167], v[68:71], v[144:147], v[156:159]
	v_mfma_f32_16x16x32_bf16 v[152:155], v[48:51], v[172:175], v[152:155]
	v_mfma_f32_16x16x32_bf16 v[152:155], v[52:55], v[190:193], v[152:155]
	v_mfma_f32_16x16x32_bf16 v[148:151], v[64:67], v[172:175], v[148:151]
	v_mfma_f32_16x16x32_bf16 v[148:151], v[68:71], v[190:193], v[148:151]
	v_mfma_f32_16x16x32_bf16 v[116:119], v[48:51], v[196:199], v[116:119]
	v_mfma_f32_16x16x32_bf16 v[116:119], v[52:55], v[200:203], v[116:119]
	v_mfma_f32_16x16x32_bf16 v[112:115], v[64:67], v[196:199], v[112:115]
	v_mfma_f32_16x16x32_bf16 v[112:115], v[68:71], v[200:203], v[112:115]
	v_mfma_f32_16x16x32_bf16 v[96:99], v[48:51], v[204:207], v[96:99]
	v_mfma_f32_16x16x32_bf16 v[96:99], v[52:55], v[208:211], v[96:99]
	v_mfma_f32_16x16x32_bf16 v[92:95], v[64:67], v[204:207], v[92:95]
	v_mfma_f32_16x16x32_bf16 v[92:95], v[68:71], v[208:211], v[92:95]
	v_mfma_f32_16x16x32_bf16 v[156:159], v[100:103], v[72:75], v[160:163]
	v_mfma_f32_16x16x32_bf16 v[160:163], v[120:123], v[144:147], v[156:159]
	v_mfma_f32_16x16x32_bf16 v[72:75], v[124:127], v[72:75], v[136:139]
	v_mfma_f32_16x16x32_bf16 v[156:159], v[140:143], v[144:147], v[72:75]
	v_mfma_f32_16x16x32_bf16 v[72:75], v[100:103], v[172:175], v[132:135]
	v_mfma_f32_16x16x32_bf16 v[132:135], v[120:123], v[190:193], v[72:75]
	v_mfma_f32_16x16x32_bf16 v[72:75], v[124:127], v[172:175], v[128:131]
	v_mfma_f32_16x16x32_bf16 v[128:131], v[140:143], v[190:193], v[72:75]
	v_mfma_f32_16x16x32_bf16 v[72:75], v[100:103], v[196:199], v[108:111]
	v_mfma_f32_16x16x32_bf16 v[108:111], v[120:123], v[200:203], v[72:75]
	v_mfma_f32_16x16x32_bf16 v[72:75], v[124:127], v[196:199], v[104:107]
	v_mfma_f32_16x16x32_bf16 v[104:107], v[140:143], v[200:203], v[72:75]
	v_mfma_f32_16x16x32_bf16 v[72:75], v[100:103], v[204:207], v[88:91]
	v_mfma_f32_16x16x32_bf16 v[88:91], v[120:123], v[208:211], v[72:75]
	v_mfma_f32_16x16x32_bf16 v[72:75], v[124:127], v[204:207], v[84:87]
	v_mfma_f32_16x16x32_bf16 v[84:87], v[140:143], v[208:211], v[72:75]
	s_barrier
	s_add_i32 s67, s67, s56
	s_nop 3
	v_lshl_add_u64 v[72:73], v[212:213], 0, s[30:31]
	s_mov_b32 m0, s67
	ds_read_b128 v[136:139], v195 offset:49152
	ds_read_b128 v[144:147], v195 offset:50176
	ds_read_b128 v[172:175], v195 offset:51200
	ds_read_b128 v[190:193], v195 offset:52224
	ds_read_b128 v[196:199], v195 offset:53248
	ds_read_b128 v[200:203], v195 offset:54272
	ds_read_b128 v[204:207], v195 offset:55296
	ds_read_b128 v[208:211], v195 offset:56320
	global_load_lds_dwordx4 v[72:73], off
	s_add_i32 m0, s67, 0x2000
	s_add_u32 s92, s92, 0x80080
	v_lshl_add_u64 v[72:73], v[214:215], 0, s[30:31]
	s_addc_u32 s93, s93, 0
	s_add_i32 s67, s87, s56
	global_load_lds_dwordx4 v[72:73], off
	v_lshl_add_u64 v[72:73], s[92:93], 0, v[178:179]
	s_mov_b32 m0, s67
	s_nop 0
	global_load_lds_dwordx4 v[72:73], off
	v_lshl_add_u64 v[72:73], s[92:93], 0, v[182:183]
	s_add_i32 m0, s67, 0x2000
	s_nop 0
	global_load_lds_dwordx4 v[72:73], off
	v_lshl_add_u64 v[72:73], v[224:225], 0, s[30:31]
	s_mov_b32 m0, s2
	s_nop 0
	global_load_lds_dwordx4 v[72:73], off
	v_lshl_add_u64 v[72:73], v[226:227], 0, s[30:31]
	s_mov_b32 m0, s28
	s_nop 0
	global_load_lds_dwordx4 v[72:73], off
	s_waitcnt vmcnt(8)
	s_waitcnt lgkmcnt(0)
	s_barrier
	s_waitcnt lgkmcnt(0)
	v_mfma_f32_16x16x32_bf16 v[72:75], v[48:51], v[136:139], v[80:83]
	v_mfma_f32_16x16x32_bf16 v[80:83], v[52:55], v[144:147], v[72:75]
	v_mfma_f32_16x16x32_bf16 v[72:75], v[64:67], v[136:139], v[76:79]
	v_mfma_f32_16x16x32_bf16 v[76:79], v[68:71], v[144:147], v[72:75]
	v_mfma_f32_16x16x32_bf16 v[60:63], v[48:51], v[172:175], v[60:63]
	v_mfma_f32_16x16x32_bf16 v[60:63], v[52:55], v[190:193], v[60:63]
	v_mfma_f32_16x16x32_bf16 v[56:59], v[64:67], v[172:175], v[56:59]
	v_mfma_f32_16x16x32_bf16 v[56:59], v[68:71], v[190:193], v[56:59]
	v_mfma_f32_16x16x32_bf16 v[28:31], v[48:51], v[196:199], v[28:31]
	v_mfma_f32_16x16x32_bf16 v[28:31], v[52:55], v[200:203], v[28:31]
	v_mfma_f32_16x16x32_bf16 v[24:27], v[64:67], v[196:199], v[24:27]
	v_mfma_f32_16x16x32_bf16 v[24:27], v[68:71], v[200:203], v[24:27]
	v_mfma_f32_16x16x32_bf16 v[12:15], v[48:51], v[204:207], v[12:15]
	v_mfma_f32_16x16x32_bf16 v[12:15], v[52:55], v[208:211], v[12:15]
	v_mfma_f32_16x16x32_bf16 v[8:11], v[64:67], v[204:207], v[8:11]
	v_mfma_f32_16x16x32_bf16 v[8:11], v[68:71], v[208:211], v[8:11]
	v_mfma_f32_16x16x32_bf16 v[40:43], v[100:103], v[136:139], v[40:43]
	v_mfma_f32_16x16x32_bf16 v[72:75], v[120:123], v[144:147], v[40:43]
	v_mfma_f32_16x16x32_bf16 v[40:43], v[124:127], v[136:139], v[44:47]
	v_mfma_f32_16x16x32_bf16 v[68:71], v[140:143], v[144:147], v[40:43]
	v_mfma_f32_16x16x32_bf16 v[36:39], v[100:103], v[172:175], v[36:39]
	v_mfma_f32_16x16x32_bf16 v[36:39], v[120:123], v[190:193], v[36:39]
	v_mfma_f32_16x16x32_bf16 v[32:35], v[124:127], v[172:175], v[32:35]
	v_mfma_f32_16x16x32_bf16 v[32:35], v[140:143], v[190:193], v[32:35]
	v_mfma_f32_16x16x32_bf16 v[20:23], v[100:103], v[196:199], v[20:23]
	v_mfma_f32_16x16x32_bf16 v[20:23], v[120:123], v[200:203], v[20:23]
	v_mfma_f32_16x16x32_bf16 v[16:19], v[124:127], v[196:199], v[16:19]
	v_mfma_f32_16x16x32_bf16 v[16:19], v[140:143], v[200:203], v[16:19]
	v_mfma_f32_16x16x32_bf16 v[4:7], v[100:103], v[204:207], v[4:7]
	v_mfma_f32_16x16x32_bf16 v[4:7], v[120:123], v[208:211], v[4:7]
	v_mfma_f32_16x16x32_bf16 v[0:3], v[124:127], v[204:207], v[0:3]
	v_mfma_f32_16x16x32_bf16 v[0:3], v[140:143], v[208:211], v[0:3]
	s_barrier
	s_add_i32 s85, s85, 2
	s_add_u32 s10, s10, 0x100
	s_addc_u32 s11, s11, 0
	s_add_u32 s54, s54, 0x100
	s_addc_u32 s55, s55, 0
	s_cmp_gt_u32 s85, 29
	s_cbranch_scc0 .LBB0_639
	s_and_b64 vcc, exec, s[80:81]
	s_cbranch_vccz .LBB0_642
	s_barrier

.LBB0_964:
	s_ashr_i32 s79, s78, 31
	s_lshl_b64 s[82:83], s[78:79], 20
	s_add_u32 s82, s14, s82
	s_addc_u32 s83, s15, s83
	s_and_b64 s[84:85], s[80:81], exec
	s_cselect_b32 s79, s83, s93
	s_cselect_b32 s96, s82, s92
	s_ashr_i32 s77, s76, 31
	s_lshl_b64 s[84:85], s[76:77], 20
	s_add_u32 s84, s24, s84
	s_addc_u32 s85, s26, s85
	s_and_b64 vcc, s[80:81], exec
	s_cselect_b32 s77, s85, s91
	s_cselect_b32 vcc_lo, s84, s90
	s_lshl_b32 s86, s86, 8
	s_ashr_i32 s87, s86, 31
	s_lshl_b64 s[74:75], s[86:87], 2
	s_add_u32 s74, s88, s74
	s_addc_u32 s75, s89, s75
	s_add_i32 m0, s71, s40
	s_add_u32 s88, s92, 0x80080
	global_load_lds_dwordx4 v239, s[74:75]
	s_addc_u32 s89, s93, 0
	s_add_u32 s87, s90, 0x100
	s_addc_u32 vcc_hi, s91, 0
	s_mov_b32 s71, -2
	s_waitcnt vmcnt(0)
	s_add_u32 s67, s88, 0xfff80080
	s_addc_u32 s74, s89, -1
	s_add_i32 s75, 0, 0x10000
	s_cmp_eq_u32 s71, 28
	s_cselect_b32 s93, s79, s74
	s_cselect_b32 s92, s96, s67
	s_cselect_b32 s91, s77, vcc_hi
	s_cselect_b32 s90, vcc_lo, s87
	s_add_i32 s67, 0, 0x14000
	v_add_u32_e32 v96, s75, v238
	v_add_u32_e32 v140, s67, v238
	ds_read_b128 v[64:67], v96
	ds_read_b128 v[72:75], v96 offset:1024
	ds_read_b128 v[88:91], v96 offset:2048
	ds_read_b128 v[96:99], v96 offset:3072
	ds_read_b128 v[108:111], v140
	ds_read_b128 v[116:119], v140 offset:1024
	ds_read_b128 v[128:131], v140 offset:2048
	ds_read_b128 v[140:143], v140 offset:3072
	v_lshl_add_u64 v[192:193], s[88:89], 0, v[230:231]
	s_add_i32 m0, s28, 0xc000
	ds_read_b128 v[152:155], v240
	ds_read_b128 v[156:159], v240 offset:1024
	ds_read_b128 v[160:163], v240 offset:2048
	ds_read_b128 v[164:167], v240 offset:3072
	ds_read_b128 v[168:171], v240 offset:4096
	ds_read_b128 v[180:183], v240 offset:5120
	ds_read_b128 v[184:187], v240 offset:6144
	ds_read_b128 v[188:191], v240 offset:7168
	global_load_lds_dwordx4 v[192:193], off
	v_lshl_add_u64 v[192:193], s[88:89], 0, v[232:233]
	s_add_i32 m0, s28, 0xe000
	s_nop 0
	global_load_lds_dwordx4 v[192:193], off
	s_waitcnt vmcnt(8)
	s_waitcnt lgkmcnt(0)
	s_barrier
	s_waitcnt lgkmcnt(0)
	v_mfma_f32_16x16x32_bf16 v[176:179], v[64:67], v[152:155], 0
	v_mfma_f32_16x16x32_bf16 v[176:179], v[72:75], v[156:159], v[176:179]
	v_mfma_f32_16x16x32_bf16 v[148:151], v[108:111], v[152:155], 0
	v_mfma_f32_16x16x32_bf16 v[148:151], v[116:119], v[156:159], v[148:151]
	v_mfma_f32_16x16x32_bf16 v[172:175], v[88:91], v[152:155], 0
	v_mfma_f32_16x16x32_bf16 v[172:175], v[96:99], v[156:159], v[172:175]
	v_mfma_f32_16x16x32_bf16 v[144:147], v[128:131], v[152:155], 0
	v_mfma_f32_16x16x32_bf16 v[144:147], v[140:143], v[156:159], v[144:147]
	v_mfma_f32_16x16x32_bf16 v[136:139], v[64:67], v[160:163], 0
	v_mfma_f32_16x16x32_bf16 v[136:139], v[72:75], v[164:167], v[136:139]
	v_mfma_f32_16x16x32_bf16 v[124:127], v[108:111], v[160:163], 0
	v_mfma_f32_16x16x32_bf16 v[124:127], v[116:119], v[164:167], v[124:127]
	v_mfma_f32_16x16x32_bf16 v[132:135], v[88:91], v[160:163], 0
	v_mfma_f32_16x16x32_bf16 v[132:135], v[96:99], v[164:167], v[132:135]
	v_mfma_f32_16x16x32_bf16 v[120:123], v[128:131], v[160:163], 0
	v_mfma_f32_16x16x32_bf16 v[120:123], v[140:143], v[164:167], v[120:123]
	v_mfma_f32_16x16x32_bf16 v[112:115], v[64:67], v[168:171], 0
	v_mfma_f32_16x16x32_bf16 v[112:115], v[72:75], v[180:183], v[112:115]
	v_mfma_f32_16x16x32_bf16 v[100:103], v[108:111], v[168:171], 0
	v_mfma_f32_16x16x32_bf16 v[100:103], v[116:119], v[180:183], v[100:103]
	v_mfma_f32_16x16x32_bf16 v[104:107], v[88:91], v[168:171], 0
	v_mfma_f32_16x16x32_bf16 v[104:107], v[96:99], v[180:183], v[104:107]
	v_mfma_f32_16x16x32_bf16 v[92:95], v[128:131], v[168:171], 0
	v_mfma_f32_16x16x32_bf16 v[92:95], v[140:143], v[180:183], v[92:95]
	v_mfma_f32_16x16x32_bf16 v[84:87], v[64:67], v[184:187], 0
	v_mfma_f32_16x16x32_bf16 v[84:87], v[72:75], v[188:191], v[84:87]
	v_mfma_f32_16x16x32_bf16 v[76:79], v[108:111], v[184:187], 0
	v_mfma_f32_16x16x32_bf16 v[76:79], v[116:119], v[188:191], v[76:79]
	v_mfma_f32_16x16x32_bf16 v[80:83], v[88:91], v[184:187], 0
	v_mfma_f32_16x16x32_bf16 v[80:83], v[96:99], v[188:191], v[80:83]
	v_mfma_f32_16x16x32_bf16 v[68:71], v[128:131], v[184:187], 0
	v_mfma_f32_16x16x32_bf16 v[68:71], v[140:143], v[188:191], v[68:71]
	s_barrier
	s_add_i32 s74, s75, s2
	v_lshl_add_u64 v[192:193], s[90:91], 0, v[216:217]
	s_mov_b32 m0, s74
	ds_read_b128 v[152:155], v240 offset:16384
	ds_read_b128 v[156:159], v240 offset:17408
	ds_read_b128 v[160:163], v240 offset:18432
	ds_read_b128 v[164:167], v240 offset:19456
	ds_read_b128 v[168:171], v240 offset:20480
	ds_read_b128 v[180:183], v240 offset:21504
	ds_read_b128 v[184:187], v240 offset:22528
	ds_read_b128 v[188:191], v240 offset:23552
	global_load_lds_dwordx4 v[192:193], off
	s_add_i32 m0, s74, 0x2000
	s_add_u32 s74, s90, 0x80000
	v_lshl_add_u64 v[194:195], s[90:91], 0, v[228:229]
	s_addc_u32 s75, s91, 0
	s_add_i32 s67, s67, s2
	global_load_lds_dwordx4 v[194:195], off
	v_lshl_add_u64 v[196:197], s[74:75], 0, v[216:217]
	s_mov_b32 m0, s67
	v_lshl_add_u64 v[198:199], s[92:93], 0, v[226:227]
	global_load_lds_dwordx4 v[196:197], off
	v_lshl_add_u64 v[196:197], s[74:75], 0, v[228:229]
	s_add_i32 m0, s67, 0x2000
	s_nop 0
	global_load_lds_dwordx4 v[196:197], off
	v_lshl_add_u64 v[196:197], s[92:93], 0, v[224:225]
	s_mov_b32 m0, s28
	s_nop 0
	global_load_lds_dwordx4 v[196:197], off
	s_mov_b32 m0, s29
	s_nop 0
	global_load_lds_dwordx4 v[198:199], off
	s_waitcnt vmcnt(8)
	s_waitcnt lgkmcnt(0)
	s_barrier
	s_waitcnt lgkmcnt(0)
	v_mfma_f32_16x16x32_bf16 v[60:63], v[64:67], v[152:155], 0
	v_mfma_f32_16x16x32_bf16 v[60:63], v[72:75], v[156:159], v[60:63]
	v_mfma_f32_16x16x32_bf16 v[52:55], v[108:111], v[152:155], 0
	v_mfma_f32_16x16x32_bf16 v[52:55], v[116:119], v[156:159], v[52:55]
	v_mfma_f32_16x16x32_bf16 v[56:59], v[88:91], v[152:155], 0
	v_mfma_f32_16x16x32_bf16 v[56:59], v[96:99], v[156:159], v[56:59]
	v_mfma_f32_16x16x32_bf16 v[48:51], v[128:131], v[152:155], 0
	v_mfma_f32_16x16x32_bf16 v[48:51], v[140:143], v[156:159], v[48:51]
	v_mfma_f32_16x16x32_bf16 v[44:47], v[64:67], v[160:163], 0
	v_mfma_f32_16x16x32_bf16 v[44:47], v[72:75], v[164:167], v[44:47]
	v_mfma_f32_16x16x32_bf16 v[36:39], v[108:111], v[160:163], 0
	v_mfma_f32_16x16x32_bf16 v[36:39], v[116:119], v[164:167], v[36:39]
	v_mfma_f32_16x16x32_bf16 v[40:43], v[88:91], v[160:163], 0
	v_mfma_f32_16x16x32_bf16 v[40:43], v[96:99], v[164:167], v[40:43]
	v_mfma_f32_16x16x32_bf16 v[32:35], v[128:131], v[160:163], 0
	v_mfma_f32_16x16x32_bf16 v[32:35], v[140:143], v[164:167], v[32:35]
	v_mfma_f32_16x16x32_bf16 v[28:31], v[64:67], v[168:171], 0
	v_mfma_f32_16x16x32_bf16 v[28:31], v[72:75], v[180:183], v[28:31]
	v_mfma_f32_16x16x32_bf16 v[20:23], v[108:111], v[168:171], 0
	v_mfma_f32_16x16x32_bf16 v[20:23], v[116:119], v[180:183], v[20:23]
	v_mfma_f32_16x16x32_bf16 v[24:27], v[88:91], v[168:171], 0
	v_mfma_f32_16x16x32_bf16 v[24:27], v[96:99], v[180:183], v[24:27]
	v_mfma_f32_16x16x32_bf16 v[16:19], v[128:131], v[168:171], 0
	v_mfma_f32_16x16x32_bf16 v[16:19], v[140:143], v[180:183], v[16:19]
	v_mfma_f32_16x16x32_bf16 v[12:15], v[64:67], v[184:187], 0
	v_mfma_f32_16x16x32_bf16 v[12:15], v[72:75], v[188:191], v[12:15]
	v_mfma_f32_16x16x32_bf16 v[4:7], v[108:111], v[184:187], 0
	v_mfma_f32_16x16x32_bf16 v[4:7], v[116:119], v[188:191], v[4:7]
	v_mfma_f32_16x16x32_bf16 v[8:11], v[88:91], v[184:187], 0
	v_mfma_f32_16x16x32_bf16 v[8:11], v[96:99], v[188:191], v[8:11]
	v_mfma_f32_16x16x32_bf16 v[0:3], v[128:131], v[184:187], 0
	v_mfma_f32_16x16x32_bf16 v[0:3], v[140:143], v[188:191], v[0:3]
	s_barrier
	s_add_i32 s67, 0, 0x18000
	s_add_i32 s3, 0, 0x1c000
	v_add_u32_e32 v96, s67, v238
	v_add_u32_e32 v140, s3, v238
	ds_read_b128 v[64:67], v96
	ds_read_b128 v[72:75], v96 offset:1024
	ds_read_b128 v[88:91], v96 offset:2048
	ds_read_b128 v[96:99], v96 offset:3072
	ds_read_b128 v[108:111], v140
	ds_read_b128 v[116:119], v140 offset:1024
	ds_read_b128 v[128:131], v140 offset:2048
	ds_read_b128 v[140:143], v140 offset:3072
	s_add_u32 s74, s92, 0x80000
	s_addc_u32 s75, s93, 0
	s_mov_b32 m0, s34
	v_lshl_add_u64 v[200:201], s[74:75], 0, v[224:225]
	ds_read_b128 v[152:155], v240 offset:32768
	ds_read_b128 v[156:159], v240 offset:33792
	ds_read_b128 v[160:163], v240 offset:34816
	ds_read_b128 v[164:167], v240 offset:35840
	ds_read_b128 v[168:171], v240 offset:36864
	ds_read_b128 v[180:183], v240 offset:37888
	ds_read_b128 v[184:187], v240 offset:38912
	ds_read_b128 v[188:191], v240 offset:39936
	global_load_lds_dwordx4 v[200:201], off
	v_lshl_add_u64 v[200:201], s[74:75], 0, v[226:227]
	s_mov_b32 m0, s35
	s_nop 0
	global_load_lds_dwordx4 v[200:201], off
	s_waitcnt vmcnt(8)
	s_waitcnt lgkmcnt(0)
	s_barrier
	s_waitcnt lgkmcnt(0)
	v_mfma_f32_16x16x32_bf16 v[176:179], v[64:67], v[152:155], v[176:179]
	v_mfma_f32_16x16x32_bf16 v[176:179], v[72:75], v[156:159], v[176:179]
	v_mfma_f32_16x16x32_bf16 v[148:151], v[108:111], v[152:155], v[148:151]
	v_mfma_f32_16x16x32_bf16 v[148:151], v[116:119], v[156:159], v[148:151]
	v_mfma_f32_16x16x32_bf16 v[172:175], v[88:91], v[152:155], v[172:175]
	v_mfma_f32_16x16x32_bf16 v[172:175], v[96:99], v[156:159], v[172:175]
	v_mfma_f32_16x16x32_bf16 v[144:147], v[128:131], v[152:155], v[144:147]
	v_mfma_f32_16x16x32_bf16 v[144:147], v[140:143], v[156:159], v[144:147]
	v_mfma_f32_16x16x32_bf16 v[136:139], v[64:67], v[160:163], v[136:139]
	v_mfma_f32_16x16x32_bf16 v[136:139], v[72:75], v[164:167], v[136:139]
	v_mfma_f32_16x16x32_bf16 v[124:127], v[108:111], v[160:163], v[124:127]
	v_mfma_f32_16x16x32_bf16 v[124:127], v[116:119], v[164:167], v[124:127]
	v_mfma_f32_16x16x32_bf16 v[132:135], v[88:91], v[160:163], v[132:135]
	v_mfma_f32_16x16x32_bf16 v[132:135], v[96:99], v[164:167], v[132:135]
	v_mfma_f32_16x16x32_bf16 v[120:123], v[128:131], v[160:163], v[120:123]
	v_mfma_f32_16x16x32_bf16 v[120:123], v[140:143], v[164:167], v[120:123]
	v_mfma_f32_16x16x32_bf16 v[112:115], v[64:67], v[168:171], v[112:115]
	v_mfma_f32_16x16x32_bf16 v[112:115], v[72:75], v[180:183], v[112:115]
	v_mfma_f32_16x16x32_bf16 v[100:103], v[108:111], v[168:171], v[100:103]
	v_mfma_f32_16x16x32_bf16 v[100:103], v[116:119], v[180:183], v[100:103]
	v_mfma_f32_16x16x32_bf16 v[104:107], v[88:91], v[168:171], v[104:107]
	v_mfma_f32_16x16x32_bf16 v[104:107], v[96:99], v[180:183], v[104:107]
	v_mfma_f32_16x16x32_bf16 v[92:95], v[128:131], v[168:171], v[92:95]
	v_mfma_f32_16x16x32_bf16 v[92:95], v[140:143], v[180:183], v[92:95]
	v_mfma_f32_16x16x32_bf16 v[84:87], v[64:67], v[184:187], v[84:87]
	v_mfma_f32_16x16x32_bf16 v[84:87], v[72:75], v[188:191], v[84:87]
	v_mfma_f32_16x16x32_bf16 v[76:79], v[108:111], v[184:187], v[76:79]
	v_mfma_f32_16x16x32_bf16 v[76:79], v[116:119], v[188:191], v[76:79]
	v_mfma_f32_16x16x32_bf16 v[80:83], v[88:91], v[184:187], v[80:83]
	v_mfma_f32_16x16x32_bf16 v[80:83], v[96:99], v[188:191], v[80:83]
	v_mfma_f32_16x16x32_bf16 v[68:71], v[128:131], v[184:187], v[68:71]
	v_mfma_f32_16x16x32_bf16 v[68:71], v[140:143], v[188:191], v[68:71]
	s_barrier
	s_add_i32 s67, s67, s2
	v_lshl_add_u64 v[192:193], v[192:193], 0, s[30:31]
	s_mov_b32 m0, s67
	ds_read_b128 v[152:155], v240 offset:49152
	ds_read_b128 v[156:159], v240 offset:50176
	ds_read_b128 v[160:163], v240 offset:51200
	ds_read_b128 v[164:167], v240 offset:52224
	ds_read_b128 v[168:171], v240 offset:53248
	ds_read_b128 v[180:183], v240 offset:54272
	ds_read_b128 v[184:187], v240 offset:55296
	ds_read_b128 v[188:191], v240 offset:56320
	global_load_lds_dwordx4 v[192:193], off
	s_add_i32 m0, s67, 0x2000
	s_add_u32 s74, s90, 0x80080
	v_lshl_add_u64 v[192:193], v[194:195], 0, s[30:31]
	s_addc_u32 s75, s91, 0
	s_add_i32 s3, s3, s2
	global_load_lds_dwordx4 v[192:193], off
	v_lshl_add_u64 v[192:193], s[74:75], 0, v[216:217]
	s_mov_b32 m0, s3
	s_nop 0
	global_load_lds_dwordx4 v[192:193], off
	v_lshl_add_u64 v[192:193], s[74:75], 0, v[228:229]
	s_add_i32 m0, s3, 0x2000
	s_nop 0
	global_load_lds_dwordx4 v[192:193], off
	v_lshl_add_u64 v[192:193], v[196:197], 0, s[30:31]
	s_mov_b32 m0, s60
	s_nop 0
	global_load_lds_dwordx4 v[192:193], off
	v_lshl_add_u64 v[192:193], v[198:199], 0, s[30:31]
	s_mov_b32 m0, s61
	s_nop 0
	global_load_lds_dwordx4 v[192:193], off
	s_waitcnt vmcnt(8)
	s_waitcnt lgkmcnt(0)
	s_barrier
	s_waitcnt lgkmcnt(0)
	v_mfma_f32_16x16x32_bf16 v[60:63], v[64:67], v[152:155], v[60:63]
	v_mfma_f32_16x16x32_bf16 v[60:63], v[72:75], v[156:159], v[60:63]
	v_mfma_f32_16x16x32_bf16 v[52:55], v[108:111], v[152:155], v[52:55]
	v_mfma_f32_16x16x32_bf16 v[52:55], v[116:119], v[156:159], v[52:55]
	v_mfma_f32_16x16x32_bf16 v[56:59], v[88:91], v[152:155], v[56:59]
	v_mfma_f32_16x16x32_bf16 v[56:59], v[96:99], v[156:159], v[56:59]
	v_mfma_f32_16x16x32_bf16 v[48:51], v[128:131], v[152:155], v[48:51]
	v_mfma_f32_16x16x32_bf16 v[48:51], v[140:143], v[156:159], v[48:51]
	v_mfma_f32_16x16x32_bf16 v[44:47], v[64:67], v[160:163], v[44:47]
	v_mfma_f32_16x16x32_bf16 v[44:47], v[72:75], v[164:167], v[44:47]
	v_mfma_f32_16x16x32_bf16 v[36:39], v[108:111], v[160:163], v[36:39]
	v_mfma_f32_16x16x32_bf16 v[36:39], v[116:119], v[164:167], v[36:39]
	v_mfma_f32_16x16x32_bf16 v[40:43], v[88:91], v[160:163], v[40:43]
	v_mfma_f32_16x16x32_bf16 v[40:43], v[96:99], v[164:167], v[40:43]
	v_mfma_f32_16x16x32_bf16 v[32:35], v[128:131], v[160:163], v[32:35]
	v_mfma_f32_16x16x32_bf16 v[32:35], v[140:143], v[164:167], v[32:35]
	v_mfma_f32_16x16x32_bf16 v[28:31], v[64:67], v[168:171], v[28:31]
	v_mfma_f32_16x16x32_bf16 v[28:31], v[72:75], v[180:183], v[28:31]
	v_mfma_f32_16x16x32_bf16 v[20:23], v[108:111], v[168:171], v[20:23]
	v_mfma_f32_16x16x32_bf16 v[20:23], v[116:119], v[180:183], v[20:23]
	v_mfma_f32_16x16x32_bf16 v[24:27], v[88:91], v[168:171], v[24:27]
	v_mfma_f32_16x16x32_bf16 v[24:27], v[96:99], v[180:183], v[24:27]
	v_mfma_f32_16x16x32_bf16 v[16:19], v[128:131], v[168:171], v[16:19]
	v_mfma_f32_16x16x32_bf16 v[16:19], v[140:143], v[180:183], v[16:19]
	v_mfma_f32_16x16x32_bf16 v[12:15], v[64:67], v[184:187], v[12:15]
	v_mfma_f32_16x16x32_bf16 v[12:15], v[72:75], v[188:191], v[12:15]
	v_mfma_f32_16x16x32_bf16 v[4:7], v[108:111], v[184:187], v[4:7]
	v_mfma_f32_16x16x32_bf16 v[4:7], v[116:119], v[188:191], v[4:7]
	v_mfma_f32_16x16x32_bf16 v[8:11], v[88:91], v[184:187], v[8:11]
	v_mfma_f32_16x16x32_bf16 v[8:11], v[96:99], v[188:191], v[8:11]
	v_mfma_f32_16x16x32_bf16 v[0:3], v[128:131], v[184:187], v[0:3]
	v_mfma_f32_16x16x32_bf16 v[0:3], v[140:143], v[188:191], v[0:3]
	s_barrier
	s_add_i32 s71, s71, 2
	s_add_u32 s88, s88, 0x100
	s_addc_u32 s89, s89, 0
	s_add_u32 s87, s87, 0x100
	s_addc_u32 vcc_hi, vcc_hi, 0
.LBB0_965:
	s_add_u32 s67, s88, 0xfff80080
	s_addc_u32 s74, s89, -1
	s_add_i32 s75, 0, 0x10000
	s_cmp_eq_u32 s71, 28
	s_cselect_b32 s93, s79, s74
	s_cselect_b32 s92, s96, s67
	s_cselect_b32 s91, s77, vcc_hi
	s_cselect_b32 s90, vcc_lo, s87
	s_add_i32 s67, 0, 0x14000
	v_add_u32_e32 v96, s75, v238
	v_add_u32_e32 v140, s67, v238
	ds_read_b128 v[64:67], v96
	ds_read_b128 v[72:75], v96 offset:1024
	ds_read_b128 v[88:91], v96 offset:2048
	ds_read_b128 v[96:99], v96 offset:3072
	ds_read_b128 v[108:111], v140
	ds_read_b128 v[116:119], v140 offset:1024
	ds_read_b128 v[128:131], v140 offset:2048
	ds_read_b128 v[140:143], v140 offset:3072
	v_lshl_add_u64 v[192:193], s[88:89], 0, v[230:231]
	s_add_i32 m0, s28, 0xc000
	ds_read_b128 v[152:155], v240
	ds_read_b128 v[156:159], v240 offset:1024
	ds_read_b128 v[160:163], v240 offset:2048
	ds_read_b128 v[164:167], v240 offset:3072
	ds_read_b128 v[168:171], v240 offset:4096
	ds_read_b128 v[180:183], v240 offset:5120
	ds_read_b128 v[184:187], v240 offset:6144
	ds_read_b128 v[188:191], v240 offset:7168
	global_load_lds_dwordx4 v[192:193], off
	v_lshl_add_u64 v[192:193], s[88:89], 0, v[232:233]
	s_add_i32 m0, s28, 0xe000
	s_nop 0
	global_load_lds_dwordx4 v[192:193], off
	s_waitcnt vmcnt(8)
	s_waitcnt lgkmcnt(0)
	s_barrier
	s_waitcnt lgkmcnt(0)
	v_mfma_f32_16x16x32_bf16 v[176:179], v[64:67], v[152:155], v[176:179]
	v_mfma_f32_16x16x32_bf16 v[176:179], v[72:75], v[156:159], v[176:179]
	v_mfma_f32_16x16x32_bf16 v[148:151], v[108:111], v[152:155], v[148:151]
	v_mfma_f32_16x16x32_bf16 v[148:151], v[116:119], v[156:159], v[148:151]
	v_mfma_f32_16x16x32_bf16 v[172:175], v[88:91], v[152:155], v[172:175]
	v_mfma_f32_16x16x32_bf16 v[172:175], v[96:99], v[156:159], v[172:175]
	v_mfma_f32_16x16x32_bf16 v[144:147], v[128:131], v[152:155], v[144:147]
	v_mfma_f32_16x16x32_bf16 v[144:147], v[140:143], v[156:159], v[144:147]
	v_mfma_f32_16x16x32_bf16 v[136:139], v[64:67], v[160:163], v[136:139]
	v_mfma_f32_16x16x32_bf16 v[136:139], v[72:75], v[164:167], v[136:139]
	v_mfma_f32_16x16x32_bf16 v[124:127], v[108:111], v[160:163], v[124:127]
	v_mfma_f32_16x16x32_bf16 v[124:127], v[116:119], v[164:167], v[124:127]
	v_mfma_f32_16x16x32_bf16 v[132:135], v[88:91], v[160:163], v[132:135]
	v_mfma_f32_16x16x32_bf16 v[132:135], v[96:99], v[164:167], v[132:135]
	v_mfma_f32_16x16x32_bf16 v[120:123], v[128:131], v[160:163], v[120:123]
	v_mfma_f32_16x16x32_bf16 v[120:123], v[140:143], v[164:167], v[120:123]
	v_mfma_f32_16x16x32_bf16 v[112:115], v[64:67], v[168:171], v[112:115]
	v_mfma_f32_16x16x32_bf16 v[112:115], v[72:75], v[180:183], v[112:115]
	v_mfma_f32_16x16x32_bf16 v[100:103], v[108:111], v[168:171], v[100:103]
	v_mfma_f32_16x16x32_bf16 v[100:103], v[116:119], v[180:183], v[100:103]
	v_mfma_f32_16x16x32_bf16 v[104:107], v[88:91], v[168:171], v[104:107]
	v_mfma_f32_16x16x32_bf16 v[104:107], v[96:99], v[180:183], v[104:107]
	v_mfma_f32_16x16x32_bf16 v[92:95], v[128:131], v[168:171], v[92:95]
	v_mfma_f32_16x16x32_bf16 v[92:95], v[140:143], v[180:183], v[92:95]
	v_mfma_f32_16x16x32_bf16 v[84:87], v[64:67], v[184:187], v[84:87]
	v_mfma_f32_16x16x32_bf16 v[84:87], v[72:75], v[188:191], v[84:87]
	v_mfma_f32_16x16x32_bf16 v[76:79], v[108:111], v[184:187], v[76:79]
	v_mfma_f32_16x16x32_bf16 v[76:79], v[116:119], v[188:191], v[76:79]
	v_mfma_f32_16x16x32_bf16 v[80:83], v[88:91], v[184:187], v[80:83]
	v_mfma_f32_16x16x32_bf16 v[80:83], v[96:99], v[188:191], v[80:83]
	v_mfma_f32_16x16x32_bf16 v[68:71], v[128:131], v[184:187], v[68:71]
	v_mfma_f32_16x16x32_bf16 v[68:71], v[140:143], v[188:191], v[68:71]
	s_barrier
	s_add_i32 s74, s75, s2
	v_lshl_add_u64 v[192:193], s[90:91], 0, v[216:217]
	s_mov_b32 m0, s74
	ds_read_b128 v[152:155], v240 offset:16384
	ds_read_b128 v[156:159], v240 offset:17408
	ds_read_b128 v[160:163], v240 offset:18432
	ds_read_b128 v[164:167], v240 offset:19456
	ds_read_b128 v[168:171], v240 offset:20480
	ds_read_b128 v[180:183], v240 offset:21504
	ds_read_b128 v[184:187], v240 offset:22528
	ds_read_b128 v[188:191], v240 offset:23552
	global_load_lds_dwordx4 v[192:193], off
	s_add_i32 m0, s74, 0x2000
	s_add_u32 s74, s90, 0x80000
	v_lshl_add_u64 v[194:195], s[90:91], 0, v[228:229]
	s_addc_u32 s75, s91, 0
	s_add_i32 s67, s67, s2
	global_load_lds_dwordx4 v[194:195], off
	v_lshl_add_u64 v[196:197], s[74:75], 0, v[216:217]
	s_mov_b32 m0, s67
	v_lshl_add_u64 v[198:199], s[92:93], 0, v[226:227]
	global_load_lds_dwordx4 v[196:197], off
	v_lshl_add_u64 v[196:197], s[74:75], 0, v[228:229]
	s_add_i32 m0, s67, 0x2000
	s_nop 0
	global_load_lds_dwordx4 v[196:197], off
	v_lshl_add_u64 v[196:197], s[92:93], 0, v[224:225]
	s_mov_b32 m0, s28
	s_nop 0
	global_load_lds_dwordx4 v[196:197], off
	s_mov_b32 m0, s29
	s_nop 0
	global_load_lds_dwordx4 v[198:199], off
	s_waitcnt vmcnt(8)
	s_waitcnt lgkmcnt(0)
	s_barrier
	s_waitcnt lgkmcnt(0)
	v_mfma_f32_16x16x32_bf16 v[60:63], v[64:67], v[152:155], v[60:63]
	v_mfma_f32_16x16x32_bf16 v[60:63], v[72:75], v[156:159], v[60:63]
	v_mfma_f32_16x16x32_bf16 v[52:55], v[108:111], v[152:155], v[52:55]
	v_mfma_f32_16x16x32_bf16 v[52:55], v[116:119], v[156:159], v[52:55]
	v_mfma_f32_16x16x32_bf16 v[56:59], v[88:91], v[152:155], v[56:59]
	v_mfma_f32_16x16x32_bf16 v[56:59], v[96:99], v[156:159], v[56:59]
	v_mfma_f32_16x16x32_bf16 v[48:51], v[128:131], v[152:155], v[48:51]
	v_mfma_f32_16x16x32_bf16 v[48:51], v[140:143], v[156:159], v[48:51]
	v_mfma_f32_16x16x32_bf16 v[44:47], v[64:67], v[160:163], v[44:47]
	v_mfma_f32_16x16x32_bf16 v[44:47], v[72:75], v[164:167], v[44:47]
	v_mfma_f32_16x16x32_bf16 v[36:39], v[108:111], v[160:163], v[36:39]
	v_mfma_f32_16x16x32_bf16 v[36:39], v[116:119], v[164:167], v[36:39]
	v_mfma_f32_16x16x32_bf16 v[40:43], v[88:91], v[160:163], v[40:43]
	v_mfma_f32_16x16x32_bf16 v[40:43], v[96:99], v[164:167], v[40:43]
	v_mfma_f32_16x16x32_bf16 v[32:35], v[128:131], v[160:163], v[32:35]
	v_mfma_f32_16x16x32_bf16 v[32:35], v[140:143], v[164:167], v[32:35]
	v_mfma_f32_16x16x32_bf16 v[28:31], v[64:67], v[168:171], v[28:31]
	v_mfma_f32_16x16x32_bf16 v[28:31], v[72:75], v[180:183], v[28:31]
	v_mfma_f32_16x16x32_bf16 v[20:23], v[108:111], v[168:171], v[20:23]
	v_mfma_f32_16x16x32_bf16 v[20:23], v[116:119], v[180:183], v[20:23]
	v_mfma_f32_16x16x32_bf16 v[24:27], v[88:91], v[168:171], v[24:27]
	v_mfma_f32_16x16x32_bf16 v[24:27], v[96:99], v[180:183], v[24:27]
	v_mfma_f32_16x16x32_bf16 v[16:19], v[128:131], v[168:171], v[16:19]
	v_mfma_f32_16x16x32_bf16 v[16:19], v[140:143], v[180:183], v[16:19]
	v_mfma_f32_16x16x32_bf16 v[12:15], v[64:67], v[184:187], v[12:15]
	v_mfma_f32_16x16x32_bf16 v[12:15], v[72:75], v[188:191], v[12:15]
	v_mfma_f32_16x16x32_bf16 v[4:7], v[108:111], v[184:187], v[4:7]
	v_mfma_f32_16x16x32_bf16 v[4:7], v[116:119], v[188:191], v[4:7]
	v_mfma_f32_16x16x32_bf16 v[8:11], v[88:91], v[184:187], v[8:11]
	v_mfma_f32_16x16x32_bf16 v[8:11], v[96:99], v[188:191], v[8:11]
	v_mfma_f32_16x16x32_bf16 v[0:3], v[128:131], v[184:187], v[0:3]
	v_mfma_f32_16x16x32_bf16 v[0:3], v[140:143], v[188:191], v[0:3]
	s_barrier
	s_add_i32 s67, 0, 0x18000
	s_add_i32 s3, 0, 0x1c000
	v_add_u32_e32 v96, s67, v238
	v_add_u32_e32 v140, s3, v238
	ds_read_b128 v[64:67], v96
	ds_read_b128 v[72:75], v96 offset:1024
	ds_read_b128 v[88:91], v96 offset:2048
	ds_read_b128 v[96:99], v96 offset:3072
	ds_read_b128 v[108:111], v140
	ds_read_b128 v[116:119], v140 offset:1024
	ds_read_b128 v[128:131], v140 offset:2048
	ds_read_b128 v[140:143], v140 offset:3072
	s_add_u32 s74, s92, 0x80000
	s_addc_u32 s75, s93, 0
	s_mov_b32 m0, s34
	v_lshl_add_u64 v[200:201], s[74:75], 0, v[224:225]
	ds_read_b128 v[152:155], v240 offset:32768
	ds_read_b128 v[156:159], v240 offset:33792
	ds_read_b128 v[160:163], v240 offset:34816
	ds_read_b128 v[164:167], v240 offset:35840
	ds_read_b128 v[168:171], v240 offset:36864
	ds_read_b128 v[180:183], v240 offset:37888
	ds_read_b128 v[184:187], v240 offset:38912
	ds_read_b128 v[188:191], v240 offset:39936
	global_load_lds_dwordx4 v[200:201], off
	v_lshl_add_u64 v[200:201], s[74:75], 0, v[226:227]
	s_mov_b32 m0, s35
	s_nop 0
	global_load_lds_dwordx4 v[200:201], off
	s_waitcnt vmcnt(8)
	s_waitcnt lgkmcnt(0)
	s_barrier
	s_waitcnt lgkmcnt(0)
	v_mfma_f32_16x16x32_bf16 v[176:179], v[64:67], v[152:155], v[176:179]
	v_mfma_f32_16x16x32_bf16 v[176:179], v[72:75], v[156:159], v[176:179]
	v_mfma_f32_16x16x32_bf16 v[148:151], v[108:111], v[152:155], v[148:151]
	v_mfma_f32_16x16x32_bf16 v[148:151], v[116:119], v[156:159], v[148:151]
	v_mfma_f32_16x16x32_bf16 v[172:175], v[88:91], v[152:155], v[172:175]
	v_mfma_f32_16x16x32_bf16 v[172:175], v[96:99], v[156:159], v[172:175]
	v_mfma_f32_16x16x32_bf16 v[144:147], v[128:131], v[152:155], v[144:147]
	v_mfma_f32_16x16x32_bf16 v[144:147], v[140:143], v[156:159], v[144:147]
	v_mfma_f32_16x16x32_bf16 v[136:139], v[64:67], v[160:163], v[136:139]
	v_mfma_f32_16x16x32_bf16 v[136:139], v[72:75], v[164:167], v[136:139]
	v_mfma_f32_16x16x32_bf16 v[124:127], v[108:111], v[160:163], v[124:127]
	v_mfma_f32_16x16x32_bf16 v[124:127], v[116:119], v[164:167], v[124:127]
	v_mfma_f32_16x16x32_bf16 v[132:135], v[88:91], v[160:163], v[132:135]
	v_mfma_f32_16x16x32_bf16 v[132:135], v[96:99], v[164:167], v[132:135]
	v_mfma_f32_16x16x32_bf16 v[120:123], v[128:131], v[160:163], v[120:123]
	v_mfma_f32_16x16x32_bf16 v[120:123], v[140:143], v[164:167], v[120:123]
	v_mfma_f32_16x16x32_bf16 v[112:115], v[64:67], v[168:171], v[112:115]
	v_mfma_f32_16x16x32_bf16 v[112:115], v[72:75], v[180:183], v[112:115]
	v_mfma_f32_16x16x32_bf16 v[100:103], v[108:111], v[168:171], v[100:103]
	v_mfma_f32_16x16x32_bf16 v[100:103], v[116:119], v[180:183], v[100:103]
	v_mfma_f32_16x16x32_bf16 v[104:107], v[88:91], v[168:171], v[104:107]
	v_mfma_f32_16x16x32_bf16 v[104:107], v[96:99], v[180:183], v[104:107]
	v_mfma_f32_16x16x32_bf16 v[92:95], v[128:131], v[168:171], v[92:95]
	v_mfma_f32_16x16x32_bf16 v[92:95], v[140:143], v[180:183], v[92:95]
	v_mfma_f32_16x16x32_bf16 v[84:87], v[64:67], v[184:187], v[84:87]
	v_mfma_f32_16x16x32_bf16 v[84:87], v[72:75], v[188:191], v[84:87]
	v_mfma_f32_16x16x32_bf16 v[76:79], v[108:111], v[184:187], v[76:79]
	v_mfma_f32_16x16x32_bf16 v[76:79], v[116:119], v[188:191], v[76:79]
	v_mfma_f32_16x16x32_bf16 v[80:83], v[88:91], v[184:187], v[80:83]
	v_mfma_f32_16x16x32_bf16 v[80:83], v[96:99], v[188:191], v[80:83]
	v_mfma_f32_16x16x32_bf16 v[68:71], v[128:131], v[184:187], v[68:71]
	v_mfma_f32_16x16x32_bf16 v[68:71], v[140:143], v[188:191], v[68:71]
	s_barrier
	s_add_i32 s67, s67, s2
	v_lshl_add_u64 v[192:193], v[192:193], 0, s[30:31]
	s_mov_b32 m0, s67
	ds_read_b128 v[152:155], v240 offset:49152
	ds_read_b128 v[156:159], v240 offset:50176
	ds_read_b128 v[160:163], v240 offset:51200
	ds_read_b128 v[164:167], v240 offset:52224
	ds_read_b128 v[168:171], v240 offset:53248
	ds_read_b128 v[180:183], v240 offset:54272
	ds_read_b128 v[184:187], v240 offset:55296
	ds_read_b128 v[188:191], v240 offset:56320
	global_load_lds_dwordx4 v[192:193], off
	s_add_i32 m0, s67, 0x2000
	s_add_u32 s74, s90, 0x80080
	v_lshl_add_u64 v[192:193], v[194:195], 0, s[30:31]
	s_addc_u32 s75, s91, 0
	s_add_i32 s3, s3, s2
	global_load_lds_dwordx4 v[192:193], off
	v_lshl_add_u64 v[192:193], s[74:75], 0, v[216:217]
	s_mov_b32 m0, s3
	s_nop 0
	global_load_lds_dwordx4 v[192:193], off
	v_lshl_add_u64 v[192:193], s[74:75], 0, v[228:229]
	s_add_i32 m0, s3, 0x2000
	s_nop 0
	global_load_lds_dwordx4 v[192:193], off
	v_lshl_add_u64 v[192:193], v[196:197], 0, s[30:31]
	s_mov_b32 m0, s60
	s_nop 0
	global_load_lds_dwordx4 v[192:193], off
	v_lshl_add_u64 v[192:193], v[198:199], 0, s[30:31]
	s_mov_b32 m0, s61
	s_nop 0
	global_load_lds_dwordx4 v[192:193], off
	s_waitcnt vmcnt(8)
	s_waitcnt lgkmcnt(0)
	s_barrier
	s_waitcnt lgkmcnt(0)
	v_mfma_f32_16x16x32_bf16 v[60:63], v[64:67], v[152:155], v[60:63]
	v_mfma_f32_16x16x32_bf16 v[60:63], v[72:75], v[156:159], v[60:63]
	v_mfma_f32_16x16x32_bf16 v[52:55], v[108:111], v[152:155], v[52:55]
	v_mfma_f32_16x16x32_bf16 v[52:55], v[116:119], v[156:159], v[52:55]
	v_mfma_f32_16x16x32_bf16 v[56:59], v[88:91], v[152:155], v[56:59]
	v_mfma_f32_16x16x32_bf16 v[56:59], v[96:99], v[156:159], v[56:59]
	v_mfma_f32_16x16x32_bf16 v[48:51], v[128:131], v[152:155], v[48:51]
	v_mfma_f32_16x16x32_bf16 v[48:51], v[140:143], v[156:159], v[48:51]
	v_mfma_f32_16x16x32_bf16 v[44:47], v[64:67], v[160:163], v[44:47]
	v_mfma_f32_16x16x32_bf16 v[44:47], v[72:75], v[164:167], v[44:47]
	v_mfma_f32_16x16x32_bf16 v[36:39], v[108:111], v[160:163], v[36:39]
	v_mfma_f32_16x16x32_bf16 v[36:39], v[116:119], v[164:167], v[36:39]
	v_mfma_f32_16x16x32_bf16 v[40:43], v[88:91], v[160:163], v[40:43]
	v_mfma_f32_16x16x32_bf16 v[40:43], v[96:99], v[164:167], v[40:43]
	v_mfma_f32_16x16x32_bf16 v[32:35], v[128:131], v[160:163], v[32:35]
	v_mfma_f32_16x16x32_bf16 v[32:35], v[140:143], v[164:167], v[32:35]
	v_mfma_f32_16x16x32_bf16 v[28:31], v[64:67], v[168:171], v[28:31]
	v_mfma_f32_16x16x32_bf16 v[28:31], v[72:75], v[180:183], v[28:31]
	v_mfma_f32_16x16x32_bf16 v[20:23], v[108:111], v[168:171], v[20:23]
	v_mfma_f32_16x16x32_bf16 v[20:23], v[116:119], v[180:183], v[20:23]
	v_mfma_f32_16x16x32_bf16 v[24:27], v[88:91], v[168:171], v[24:27]
	v_mfma_f32_16x16x32_bf16 v[24:27], v[96:99], v[180:183], v[24:27]
	v_mfma_f32_16x16x32_bf16 v[16:19], v[128:131], v[168:171], v[16:19]
	v_mfma_f32_16x16x32_bf16 v[16:19], v[140:143], v[180:183], v[16:19]
	v_mfma_f32_16x16x32_bf16 v[12:15], v[64:67], v[184:187], v[12:15]
	v_mfma_f32_16x16x32_bf16 v[12:15], v[72:75], v[188:191], v[12:15]
	v_mfma_f32_16x16x32_bf16 v[4:7], v[108:111], v[184:187], v[4:7]
	v_mfma_f32_16x16x32_bf16 v[4:7], v[116:119], v[188:191], v[4:7]
	v_mfma_f32_16x16x32_bf16 v[8:11], v[88:91], v[184:187], v[8:11]
	v_mfma_f32_16x16x32_bf16 v[8:11], v[96:99], v[188:191], v[8:11]
	v_mfma_f32_16x16x32_bf16 v[0:3], v[128:131], v[184:187], v[0:3]
	v_mfma_f32_16x16x32_bf16 v[0:3], v[140:143], v[188:191], v[0:3]
	s_barrier
	s_add_i32 s71, s71, 2
	s_add_u32 s88, s88, 0x100
	s_addc_u32 s89, s89, 0
	s_add_u32 s87, s87, 0x100
	s_addc_u32 vcc_hi, vcc_hi, 0
	s_cmp_gt_u32 s71, 29
	s_cbranch_scc0 .LBB0_965
	s_and_b64 vcc, exec, s[22:23]
	s_cbranch_vccz .LBB0_968
	s_barrier

.LBB0_1189:
	s_ashr_i32 s75, s74, 31
	s_lshl_b64 s[72:73], s[74:75], 20
	s_add_u32 s76, s2, s72
	s_addc_u32 s77, s3, s73
	s_and_b64 s[72:73], s[4:5], exec
	s_cselect_b32 s71, s77, s83
	s_cselect_b32 s72, s76, s82
	s_ashr_i32 s23, s22, 31
	s_lshl_b64 s[78:79], s[22:23], 20
	s_add_u32 s78, s14, s78
	s_addc_u32 s79, s15, s79
	s_and_b64 s[86:87], s[4:5], exec
	s_cselect_b32 s23, s79, s85
	s_cselect_b32 s73, s78, s84
	s_add_u32 s82, s82, 0x80080
	s_addc_u32 s83, s83, 0
	s_add_u32 s75, s84, 0x100
	s_addc_u32 s81, s85, 0
	s_mov_b32 s88, -2
	s_add_u32 s67, s82, 0xfff80080
	s_addc_u32 s84, s83, -1
	s_add_i32 s89, 0, 0x10000
	s_cmp_eq_u32 s88, 28
	s_cselect_b32 s87, s71, s84
	s_cselect_b32 s86, s72, s67
	s_cselect_b32 s85, s23, s81
	s_cselect_b32 s84, s73, s75
	s_add_i32 s67, 0, 0x14000
	v_add_u32_e32 v76, s89, v192
	v_add_u32_e32 v156, s67, v192
	ds_read_b128 v[64:67], v76
	ds_read_b128 v[68:71], v76 offset:1024
	ds_read_b128 v[72:75], v76 offset:2048
	ds_read_b128 v[76:79], v76 offset:3072
	ds_read_b128 v[80:83], v156
	ds_read_b128 v[116:119], v156 offset:1024
	ds_read_b128 v[152:155], v156 offset:2048
	ds_read_b128 v[156:159], v156 offset:3072
	v_lshl_add_u64 v[190:191], s[82:83], 0, v[186:187]
	s_add_i32 m0, s28, 0xc000
	ds_read_b128 v[160:163], v193
	ds_read_b128 v[164:167], v193 offset:1024
	ds_read_b128 v[168:171], v193 offset:2048
	ds_read_b128 v[172:175], v193 offset:3072
	ds_read_b128 v[194:197], v193 offset:4096
	ds_read_b128 v[198:201], v193 offset:5120
	ds_read_b128 v[202:205], v193 offset:6144
	ds_read_b128 v[206:209], v193 offset:7168
	global_load_lds_dwordx4 v[190:191], off
	v_lshl_add_u64 v[190:191], s[82:83], 0, v[188:189]
	s_add_i32 m0, s28, 0xe000
	s_nop 0
	global_load_lds_dwordx4 v[190:191], off
	s_waitcnt vmcnt(8)
	s_waitcnt lgkmcnt(0)
	s_barrier
	s_waitcnt lgkmcnt(0)
	v_mfma_f32_16x16x32_bf16 v[148:151], v[64:67], v[160:163], 0
	v_mfma_f32_16x16x32_bf16 v[148:151], v[68:71], v[164:167], v[148:151]
	v_mfma_f32_16x16x32_bf16 v[140:143], v[80:83], v[160:163], 0
	v_mfma_f32_16x16x32_bf16 v[140:143], v[116:119], v[164:167], v[140:143]
	v_mfma_f32_16x16x32_bf16 v[144:147], v[72:75], v[160:163], 0
	v_mfma_f32_16x16x32_bf16 v[144:147], v[76:79], v[164:167], v[144:147]
	v_mfma_f32_16x16x32_bf16 v[136:139], v[152:155], v[160:163], 0
	v_mfma_f32_16x16x32_bf16 v[136:139], v[156:159], v[164:167], v[136:139]
	v_mfma_f32_16x16x32_bf16 v[132:135], v[64:67], v[168:171], 0
	v_mfma_f32_16x16x32_bf16 v[132:135], v[68:71], v[172:175], v[132:135]
	v_mfma_f32_16x16x32_bf16 v[124:127], v[80:83], v[168:171], 0
	v_mfma_f32_16x16x32_bf16 v[124:127], v[116:119], v[172:175], v[124:127]
	v_mfma_f32_16x16x32_bf16 v[128:131], v[72:75], v[168:171], 0
	v_mfma_f32_16x16x32_bf16 v[128:131], v[76:79], v[172:175], v[128:131]
	v_mfma_f32_16x16x32_bf16 v[120:123], v[152:155], v[168:171], 0
	v_mfma_f32_16x16x32_bf16 v[120:123], v[156:159], v[172:175], v[120:123]
	v_mfma_f32_16x16x32_bf16 v[112:115], v[64:67], v[194:197], 0
	v_mfma_f32_16x16x32_bf16 v[112:115], v[68:71], v[198:201], v[112:115]
	v_mfma_f32_16x16x32_bf16 v[104:107], v[80:83], v[194:197], 0
	v_mfma_f32_16x16x32_bf16 v[104:107], v[116:119], v[198:201], v[104:107]
	v_mfma_f32_16x16x32_bf16 v[108:111], v[72:75], v[194:197], 0
	v_mfma_f32_16x16x32_bf16 v[108:111], v[76:79], v[198:201], v[108:111]
	v_mfma_f32_16x16x32_bf16 v[100:103], v[152:155], v[194:197], 0
	v_mfma_f32_16x16x32_bf16 v[100:103], v[156:159], v[198:201], v[100:103]
	v_mfma_f32_16x16x32_bf16 v[96:99], v[64:67], v[202:205], 0
	v_mfma_f32_16x16x32_bf16 v[96:99], v[68:71], v[206:209], v[96:99]
	v_mfma_f32_16x16x32_bf16 v[88:91], v[80:83], v[202:205], 0
	v_mfma_f32_16x16x32_bf16 v[88:91], v[116:119], v[206:209], v[88:91]
	v_mfma_f32_16x16x32_bf16 v[92:95], v[72:75], v[202:205], 0
	v_mfma_f32_16x16x32_bf16 v[92:95], v[76:79], v[206:209], v[92:95]
	v_mfma_f32_16x16x32_bf16 v[84:87], v[152:155], v[202:205], 0
	v_mfma_f32_16x16x32_bf16 v[84:87], v[156:159], v[206:209], v[84:87]
	s_barrier
	s_add_i32 s89, s89, s24
	v_lshl_add_u64 v[190:191], s[84:85], 0, v[180:181]
	s_mov_b32 m0, s89
	ds_read_b128 v[160:163], v193 offset:16384
	ds_read_b128 v[164:167], v193 offset:17408
	ds_read_b128 v[168:171], v193 offset:18432
	ds_read_b128 v[172:175], v193 offset:19456
	ds_read_b128 v[194:197], v193 offset:20480
	ds_read_b128 v[198:201], v193 offset:21504
	ds_read_b128 v[202:205], v193 offset:22528
	ds_read_b128 v[206:209], v193 offset:23552
	global_load_lds_dwordx4 v[190:191], off
	s_add_i32 m0, s89, 0x2000
	s_add_u32 s90, s84, 0x80000
	v_lshl_add_u64 v[210:211], s[84:85], 0, v[176:177]
	s_addc_u32 s91, s85, 0
	s_add_i32 s67, s67, s24
	global_load_lds_dwordx4 v[210:211], off
	v_lshl_add_u64 v[212:213], s[90:91], 0, v[180:181]
	s_mov_b32 m0, s67
	v_lshl_add_u64 v[214:215], s[86:87], 0, v[178:179]
	global_load_lds_dwordx4 v[212:213], off
	v_lshl_add_u64 v[212:213], s[90:91], 0, v[176:177]
	s_add_i32 m0, s67, 0x2000
	s_nop 0
	global_load_lds_dwordx4 v[212:213], off
	v_lshl_add_u64 v[212:213], s[86:87], 0, v[182:183]
	s_mov_b32 m0, s28
	s_nop 0
	global_load_lds_dwordx4 v[212:213], off
	s_mov_b32 m0, s29
	s_nop 0
	global_load_lds_dwordx4 v[214:215], off
	s_waitcnt vmcnt(8)
	s_waitcnt lgkmcnt(0)
	s_barrier
	s_waitcnt lgkmcnt(0)
	v_mfma_f32_16x16x32_bf16 v[60:63], v[64:67], v[160:163], 0
	v_mfma_f32_16x16x32_bf16 v[60:63], v[68:71], v[164:167], v[60:63]
	v_mfma_f32_16x16x32_bf16 v[52:55], v[80:83], v[160:163], 0
	v_mfma_f32_16x16x32_bf16 v[52:55], v[116:119], v[164:167], v[52:55]
	v_mfma_f32_16x16x32_bf16 v[56:59], v[72:75], v[160:163], 0
	v_mfma_f32_16x16x32_bf16 v[56:59], v[76:79], v[164:167], v[56:59]
	v_mfma_f32_16x16x32_bf16 v[48:51], v[152:155], v[160:163], 0
	v_mfma_f32_16x16x32_bf16 v[48:51], v[156:159], v[164:167], v[48:51]
	v_mfma_f32_16x16x32_bf16 v[44:47], v[64:67], v[168:171], 0
	v_mfma_f32_16x16x32_bf16 v[44:47], v[68:71], v[172:175], v[44:47]
	v_mfma_f32_16x16x32_bf16 v[36:39], v[80:83], v[168:171], 0
	v_mfma_f32_16x16x32_bf16 v[36:39], v[116:119], v[172:175], v[36:39]
	v_mfma_f32_16x16x32_bf16 v[40:43], v[72:75], v[168:171], 0
	v_mfma_f32_16x16x32_bf16 v[40:43], v[76:79], v[172:175], v[40:43]
	v_mfma_f32_16x16x32_bf16 v[32:35], v[152:155], v[168:171], 0
	v_mfma_f32_16x16x32_bf16 v[32:35], v[156:159], v[172:175], v[32:35]
	v_mfma_f32_16x16x32_bf16 v[28:31], v[64:67], v[194:197], 0
	v_mfma_f32_16x16x32_bf16 v[28:31], v[68:71], v[198:201], v[28:31]
	v_mfma_f32_16x16x32_bf16 v[20:23], v[80:83], v[194:197], 0
	v_mfma_f32_16x16x32_bf16 v[20:23], v[116:119], v[198:201], v[20:23]
	v_mfma_f32_16x16x32_bf16 v[24:27], v[72:75], v[194:197], 0
	v_mfma_f32_16x16x32_bf16 v[24:27], v[76:79], v[198:201], v[24:27]
	v_mfma_f32_16x16x32_bf16 v[16:19], v[152:155], v[194:197], 0
	v_mfma_f32_16x16x32_bf16 v[16:19], v[156:159], v[198:201], v[16:19]
	v_mfma_f32_16x16x32_bf16 v[12:15], v[64:67], v[202:205], 0
	v_mfma_f32_16x16x32_bf16 v[12:15], v[68:71], v[206:209], v[12:15]
	v_mfma_f32_16x16x32_bf16 v[4:7], v[80:83], v[202:205], 0
	v_mfma_f32_16x16x32_bf16 v[4:7], v[116:119], v[206:209], v[4:7]
	v_mfma_f32_16x16x32_bf16 v[8:11], v[72:75], v[202:205], 0
	v_mfma_f32_16x16x32_bf16 v[8:11], v[76:79], v[206:209], v[8:11]
	v_mfma_f32_16x16x32_bf16 v[0:3], v[152:155], v[202:205], 0
	v_mfma_f32_16x16x32_bf16 v[0:3], v[156:159], v[206:209], v[0:3]
	s_barrier
	s_add_i32 s67, 0, 0x18000
	s_add_i32 s89, 0, 0x1c000
	v_add_u32_e32 v76, s67, v192
	v_add_u32_e32 v156, s89, v192
	ds_read_b128 v[64:67], v76
	ds_read_b128 v[68:71], v76 offset:1024
	ds_read_b128 v[72:75], v76 offset:2048
	ds_read_b128 v[76:79], v76 offset:3072
	ds_read_b128 v[80:83], v156
	ds_read_b128 v[116:119], v156 offset:1024
	ds_read_b128 v[152:155], v156 offset:2048
	ds_read_b128 v[156:159], v156 offset:3072
	s_add_u32 s86, s86, 0x80000
	s_addc_u32 s87, s87, 0
	s_mov_b32 m0, s34
	v_lshl_add_u64 v[218:219], s[86:87], 0, v[182:183]
	ds_read_b128 v[160:163], v193 offset:32768
	ds_read_b128 v[164:167], v193 offset:33792
	ds_read_b128 v[168:171], v193 offset:34816
	ds_read_b128 v[172:175], v193 offset:35840
	ds_read_b128 v[194:197], v193 offset:36864
	ds_read_b128 v[198:201], v193 offset:37888
	ds_read_b128 v[202:205], v193 offset:38912
	ds_read_b128 v[206:209], v193 offset:39936
	global_load_lds_dwordx4 v[218:219], off
	v_lshl_add_u64 v[218:219], s[86:87], 0, v[178:179]
	s_mov_b32 m0, s35
	s_nop 0
	global_load_lds_dwordx4 v[218:219], off
	s_waitcnt vmcnt(8)
	s_waitcnt lgkmcnt(0)
	s_barrier
	s_waitcnt lgkmcnt(0)
	v_mfma_f32_16x16x32_bf16 v[148:151], v[64:67], v[160:163], v[148:151]
	v_mfma_f32_16x16x32_bf16 v[148:151], v[68:71], v[164:167], v[148:151]
	v_mfma_f32_16x16x32_bf16 v[140:143], v[80:83], v[160:163], v[140:143]
	v_mfma_f32_16x16x32_bf16 v[140:143], v[116:119], v[164:167], v[140:143]
	v_mfma_f32_16x16x32_bf16 v[144:147], v[72:75], v[160:163], v[144:147]
	v_mfma_f32_16x16x32_bf16 v[144:147], v[76:79], v[164:167], v[144:147]
	v_mfma_f32_16x16x32_bf16 v[136:139], v[152:155], v[160:163], v[136:139]
	v_mfma_f32_16x16x32_bf16 v[136:139], v[156:159], v[164:167], v[136:139]
	v_mfma_f32_16x16x32_bf16 v[132:135], v[64:67], v[168:171], v[132:135]
	v_mfma_f32_16x16x32_bf16 v[132:135], v[68:71], v[172:175], v[132:135]
	v_mfma_f32_16x16x32_bf16 v[124:127], v[80:83], v[168:171], v[124:127]
	v_mfma_f32_16x16x32_bf16 v[124:127], v[116:119], v[172:175], v[124:127]
	v_mfma_f32_16x16x32_bf16 v[128:131], v[72:75], v[168:171], v[128:131]
	v_mfma_f32_16x16x32_bf16 v[128:131], v[76:79], v[172:175], v[128:131]
	v_mfma_f32_16x16x32_bf16 v[120:123], v[152:155], v[168:171], v[120:123]
	v_mfma_f32_16x16x32_bf16 v[120:123], v[156:159], v[172:175], v[120:123]
	v_mfma_f32_16x16x32_bf16 v[112:115], v[64:67], v[194:197], v[112:115]
	v_mfma_f32_16x16x32_bf16 v[112:115], v[68:71], v[198:201], v[112:115]
	v_mfma_f32_16x16x32_bf16 v[104:107], v[80:83], v[194:197], v[104:107]
	v_mfma_f32_16x16x32_bf16 v[104:107], v[116:119], v[198:201], v[104:107]
	v_mfma_f32_16x16x32_bf16 v[108:111], v[72:75], v[194:197], v[108:111]
	v_mfma_f32_16x16x32_bf16 v[108:111], v[76:79], v[198:201], v[108:111]
	v_mfma_f32_16x16x32_bf16 v[100:103], v[152:155], v[194:197], v[100:103]
	v_mfma_f32_16x16x32_bf16 v[100:103], v[156:159], v[198:201], v[100:103]
	v_mfma_f32_16x16x32_bf16 v[96:99], v[64:67], v[202:205], v[96:99]
	v_mfma_f32_16x16x32_bf16 v[96:99], v[68:71], v[206:209], v[96:99]
	v_mfma_f32_16x16x32_bf16 v[88:91], v[80:83], v[202:205], v[88:91]
	v_mfma_f32_16x16x32_bf16 v[88:91], v[116:119], v[206:209], v[88:91]
	v_mfma_f32_16x16x32_bf16 v[92:95], v[72:75], v[202:205], v[92:95]
	v_mfma_f32_16x16x32_bf16 v[92:95], v[76:79], v[206:209], v[92:95]
	v_mfma_f32_16x16x32_bf16 v[84:87], v[152:155], v[202:205], v[84:87]
	v_mfma_f32_16x16x32_bf16 v[84:87], v[156:159], v[206:209], v[84:87]
	s_barrier
	s_add_i32 s67, s67, s24
	v_lshl_add_u64 v[190:191], v[190:191], 0, s[30:31]
	s_mov_b32 m0, s67
	ds_read_b128 v[160:163], v193 offset:49152
	ds_read_b128 v[164:167], v193 offset:50176
	ds_read_b128 v[168:171], v193 offset:51200
	ds_read_b128 v[172:175], v193 offset:52224
	ds_read_b128 v[194:197], v193 offset:53248
	ds_read_b128 v[198:201], v193 offset:54272
	ds_read_b128 v[202:205], v193 offset:55296
	ds_read_b128 v[206:209], v193 offset:56320
	global_load_lds_dwordx4 v[190:191], off
	s_add_i32 m0, s67, 0x2000
	s_add_u32 s84, s84, 0x80080
	v_lshl_add_u64 v[190:191], v[210:211], 0, s[30:31]
	s_addc_u32 s85, s85, 0
	s_add_i32 s67, s89, s24
	global_load_lds_dwordx4 v[190:191], off
	v_lshl_add_u64 v[190:191], s[84:85], 0, v[180:181]
	s_mov_b32 m0, s67
	s_nop 0
	global_load_lds_dwordx4 v[190:191], off
	v_lshl_add_u64 v[190:191], s[84:85], 0, v[176:177]
	s_add_i32 m0, s67, 0x2000
	s_nop 0
	global_load_lds_dwordx4 v[190:191], off
	v_lshl_add_u64 v[190:191], v[212:213], 0, s[30:31]
	s_mov_b32 m0, s53
	s_nop 0
	global_load_lds_dwordx4 v[190:191], off
	v_lshl_add_u64 v[190:191], v[214:215], 0, s[30:31]
	s_mov_b32 m0, s54
	s_nop 0
	global_load_lds_dwordx4 v[190:191], off
	s_waitcnt vmcnt(8)
	s_waitcnt lgkmcnt(0)
	s_barrier
	s_waitcnt lgkmcnt(0)
	v_mfma_f32_16x16x32_bf16 v[60:63], v[64:67], v[160:163], v[60:63]
	v_mfma_f32_16x16x32_bf16 v[60:63], v[68:71], v[164:167], v[60:63]
	v_mfma_f32_16x16x32_bf16 v[52:55], v[80:83], v[160:163], v[52:55]
	v_mfma_f32_16x16x32_bf16 v[52:55], v[116:119], v[164:167], v[52:55]
	v_mfma_f32_16x16x32_bf16 v[56:59], v[72:75], v[160:163], v[56:59]
	v_mfma_f32_16x16x32_bf16 v[56:59], v[76:79], v[164:167], v[56:59]
	v_mfma_f32_16x16x32_bf16 v[48:51], v[152:155], v[160:163], v[48:51]
	v_mfma_f32_16x16x32_bf16 v[48:51], v[156:159], v[164:167], v[48:51]
	v_mfma_f32_16x16x32_bf16 v[44:47], v[64:67], v[168:171], v[44:47]
	v_mfma_f32_16x16x32_bf16 v[44:47], v[68:71], v[172:175], v[44:47]
	v_mfma_f32_16x16x32_bf16 v[36:39], v[80:83], v[168:171], v[36:39]
	v_mfma_f32_16x16x32_bf16 v[36:39], v[116:119], v[172:175], v[36:39]
	v_mfma_f32_16x16x32_bf16 v[40:43], v[72:75], v[168:171], v[40:43]
	v_mfma_f32_16x16x32_bf16 v[40:43], v[76:79], v[172:175], v[40:43]
	v_mfma_f32_16x16x32_bf16 v[32:35], v[152:155], v[168:171], v[32:35]
	v_mfma_f32_16x16x32_bf16 v[32:35], v[156:159], v[172:175], v[32:35]
	v_mfma_f32_16x16x32_bf16 v[28:31], v[64:67], v[194:197], v[28:31]
	v_mfma_f32_16x16x32_bf16 v[28:31], v[68:71], v[198:201], v[28:31]
	v_mfma_f32_16x16x32_bf16 v[20:23], v[80:83], v[194:197], v[20:23]
	v_mfma_f32_16x16x32_bf16 v[20:23], v[116:119], v[198:201], v[20:23]
	v_mfma_f32_16x16x32_bf16 v[24:27], v[72:75], v[194:197], v[24:27]
	v_mfma_f32_16x16x32_bf16 v[24:27], v[76:79], v[198:201], v[24:27]
	v_mfma_f32_16x16x32_bf16 v[16:19], v[152:155], v[194:197], v[16:19]
	v_mfma_f32_16x16x32_bf16 v[16:19], v[156:159], v[198:201], v[16:19]
	v_mfma_f32_16x16x32_bf16 v[12:15], v[64:67], v[202:205], v[12:15]
	v_mfma_f32_16x16x32_bf16 v[12:15], v[68:71], v[206:209], v[12:15]
	v_mfma_f32_16x16x32_bf16 v[4:7], v[80:83], v[202:205], v[4:7]
	v_mfma_f32_16x16x32_bf16 v[4:7], v[116:119], v[206:209], v[4:7]
	v_mfma_f32_16x16x32_bf16 v[8:11], v[72:75], v[202:205], v[8:11]
	v_mfma_f32_16x16x32_bf16 v[8:11], v[76:79], v[206:209], v[8:11]
	v_mfma_f32_16x16x32_bf16 v[0:3], v[152:155], v[202:205], v[0:3]
	v_mfma_f32_16x16x32_bf16 v[0:3], v[156:159], v[206:209], v[0:3]
	s_barrier
	s_add_i32 s88, s88, 2
	s_add_u32 s82, s82, 0x100
	s_addc_u32 s83, s83, 0
	s_add_u32 s75, s75, 0x100
	s_addc_u32 s81, s81, 0
.LBB0_1190:
	s_add_u32 s67, s82, 0xfff80080
	s_addc_u32 s84, s83, -1
	s_add_i32 s89, 0, 0x10000
	s_cmp_eq_u32 s88, 28
	s_cselect_b32 s87, s71, s84
	s_cselect_b32 s86, s72, s67
	s_cselect_b32 s85, s23, s81
	s_cselect_b32 s84, s73, s75
	s_add_i32 s67, 0, 0x14000
	v_add_u32_e32 v76, s89, v192
	v_add_u32_e32 v156, s67, v192
	ds_read_b128 v[64:67], v76
	ds_read_b128 v[68:71], v76 offset:1024
	ds_read_b128 v[72:75], v76 offset:2048
	ds_read_b128 v[76:79], v76 offset:3072
	ds_read_b128 v[80:83], v156
	ds_read_b128 v[116:119], v156 offset:1024
	ds_read_b128 v[152:155], v156 offset:2048
	ds_read_b128 v[156:159], v156 offset:3072
	v_lshl_add_u64 v[190:191], s[82:83], 0, v[186:187]
	s_add_i32 m0, s28, 0xc000
	ds_read_b128 v[160:163], v193
	ds_read_b128 v[164:167], v193 offset:1024
	ds_read_b128 v[168:171], v193 offset:2048
	ds_read_b128 v[172:175], v193 offset:3072
	ds_read_b128 v[194:197], v193 offset:4096
	ds_read_b128 v[198:201], v193 offset:5120
	ds_read_b128 v[202:205], v193 offset:6144
	ds_read_b128 v[206:209], v193 offset:7168
	global_load_lds_dwordx4 v[190:191], off
	v_lshl_add_u64 v[190:191], s[82:83], 0, v[188:189]
	s_add_i32 m0, s28, 0xe000
	s_nop 0
	global_load_lds_dwordx4 v[190:191], off
	s_waitcnt vmcnt(8)
	s_waitcnt lgkmcnt(0)
	s_barrier
	s_waitcnt lgkmcnt(0)
	v_mfma_f32_16x16x32_bf16 v[148:151], v[64:67], v[160:163], v[148:151]
	v_mfma_f32_16x16x32_bf16 v[148:151], v[68:71], v[164:167], v[148:151]
	v_mfma_f32_16x16x32_bf16 v[140:143], v[80:83], v[160:163], v[140:143]
	v_mfma_f32_16x16x32_bf16 v[140:143], v[116:119], v[164:167], v[140:143]
	v_mfma_f32_16x16x32_bf16 v[144:147], v[72:75], v[160:163], v[144:147]
	v_mfma_f32_16x16x32_bf16 v[144:147], v[76:79], v[164:167], v[144:147]
	v_mfma_f32_16x16x32_bf16 v[136:139], v[152:155], v[160:163], v[136:139]
	v_mfma_f32_16x16x32_bf16 v[136:139], v[156:159], v[164:167], v[136:139]
	v_mfma_f32_16x16x32_bf16 v[132:135], v[64:67], v[168:171], v[132:135]
	v_mfma_f32_16x16x32_bf16 v[132:135], v[68:71], v[172:175], v[132:135]
	v_mfma_f32_16x16x32_bf16 v[124:127], v[80:83], v[168:171], v[124:127]
	v_mfma_f32_16x16x32_bf16 v[124:127], v[116:119], v[172:175], v[124:127]
	v_mfma_f32_16x16x32_bf16 v[128:131], v[72:75], v[168:171], v[128:131]
	v_mfma_f32_16x16x32_bf16 v[128:131], v[76:79], v[172:175], v[128:131]
	v_mfma_f32_16x16x32_bf16 v[120:123], v[152:155], v[168:171], v[120:123]
	v_mfma_f32_16x16x32_bf16 v[120:123], v[156:159], v[172:175], v[120:123]
	v_mfma_f32_16x16x32_bf16 v[112:115], v[64:67], v[194:197], v[112:115]
	v_mfma_f32_16x16x32_bf16 v[112:115], v[68:71], v[198:201], v[112:115]
	v_mfma_f32_16x16x32_bf16 v[104:107], v[80:83], v[194:197], v[104:107]
	v_mfma_f32_16x16x32_bf16 v[104:107], v[116:119], v[198:201], v[104:107]
	v_mfma_f32_16x16x32_bf16 v[108:111], v[72:75], v[194:197], v[108:111]
	v_mfma_f32_16x16x32_bf16 v[108:111], v[76:79], v[198:201], v[108:111]
	v_mfma_f32_16x16x32_bf16 v[100:103], v[152:155], v[194:197], v[100:103]
	v_mfma_f32_16x16x32_bf16 v[100:103], v[156:159], v[198:201], v[100:103]
	v_mfma_f32_16x16x32_bf16 v[96:99], v[64:67], v[202:205], v[96:99]
	v_mfma_f32_16x16x32_bf16 v[96:99], v[68:71], v[206:209], v[96:99]
	v_mfma_f32_16x16x32_bf16 v[88:91], v[80:83], v[202:205], v[88:91]
	v_mfma_f32_16x16x32_bf16 v[88:91], v[116:119], v[206:209], v[88:91]
	v_mfma_f32_16x16x32_bf16 v[92:95], v[72:75], v[202:205], v[92:95]
	v_mfma_f32_16x16x32_bf16 v[92:95], v[76:79], v[206:209], v[92:95]
	v_mfma_f32_16x16x32_bf16 v[84:87], v[152:155], v[202:205], v[84:87]
	v_mfma_f32_16x16x32_bf16 v[84:87], v[156:159], v[206:209], v[84:87]
	s_barrier
	s_add_i32 s89, s89, s24
	v_lshl_add_u64 v[190:191], s[84:85], 0, v[180:181]
	s_mov_b32 m0, s89
	ds_read_b128 v[160:163], v193 offset:16384
	ds_read_b128 v[164:167], v193 offset:17408
	ds_read_b128 v[168:171], v193 offset:18432
	ds_read_b128 v[172:175], v193 offset:19456
	ds_read_b128 v[194:197], v193 offset:20480
	ds_read_b128 v[198:201], v193 offset:21504
	ds_read_b128 v[202:205], v193 offset:22528
	ds_read_b128 v[206:209], v193 offset:23552
	global_load_lds_dwordx4 v[190:191], off
	s_add_i32 m0, s89, 0x2000
	s_add_u32 s90, s84, 0x80000
	v_lshl_add_u64 v[210:211], s[84:85], 0, v[176:177]
	s_addc_u32 s91, s85, 0
	s_add_i32 s67, s67, s24
	global_load_lds_dwordx4 v[210:211], off
	v_lshl_add_u64 v[212:213], s[90:91], 0, v[180:181]
	s_mov_b32 m0, s67
	v_lshl_add_u64 v[214:215], s[86:87], 0, v[178:179]
	global_load_lds_dwordx4 v[212:213], off
	v_lshl_add_u64 v[212:213], s[90:91], 0, v[176:177]
	s_add_i32 m0, s67, 0x2000
	s_nop 0
	global_load_lds_dwordx4 v[212:213], off
	v_lshl_add_u64 v[212:213], s[86:87], 0, v[182:183]
	s_mov_b32 m0, s28
	s_nop 0
	global_load_lds_dwordx4 v[212:213], off
	s_mov_b32 m0, s29
	s_nop 0
	global_load_lds_dwordx4 v[214:215], off
	s_waitcnt vmcnt(8)
	s_waitcnt lgkmcnt(0)
	s_barrier
	s_waitcnt lgkmcnt(0)
	v_mfma_f32_16x16x32_bf16 v[60:63], v[64:67], v[160:163], v[60:63]
	v_mfma_f32_16x16x32_bf16 v[60:63], v[68:71], v[164:167], v[60:63]
	v_mfma_f32_16x16x32_bf16 v[52:55], v[80:83], v[160:163], v[52:55]
	v_mfma_f32_16x16x32_bf16 v[52:55], v[116:119], v[164:167], v[52:55]
	v_mfma_f32_16x16x32_bf16 v[56:59], v[72:75], v[160:163], v[56:59]
	v_mfma_f32_16x16x32_bf16 v[56:59], v[76:79], v[164:167], v[56:59]
	v_mfma_f32_16x16x32_bf16 v[48:51], v[152:155], v[160:163], v[48:51]
	v_mfma_f32_16x16x32_bf16 v[48:51], v[156:159], v[164:167], v[48:51]
	v_mfma_f32_16x16x32_bf16 v[44:47], v[64:67], v[168:171], v[44:47]
	v_mfma_f32_16x16x32_bf16 v[44:47], v[68:71], v[172:175], v[44:47]
	v_mfma_f32_16x16x32_bf16 v[36:39], v[80:83], v[168:171], v[36:39]
	v_mfma_f32_16x16x32_bf16 v[36:39], v[116:119], v[172:175], v[36:39]
	v_mfma_f32_16x16x32_bf16 v[40:43], v[72:75], v[168:171], v[40:43]
	v_mfma_f32_16x16x32_bf16 v[40:43], v[76:79], v[172:175], v[40:43]
	v_mfma_f32_16x16x32_bf16 v[32:35], v[152:155], v[168:171], v[32:35]
	v_mfma_f32_16x16x32_bf16 v[32:35], v[156:159], v[172:175], v[32:35]
	v_mfma_f32_16x16x32_bf16 v[28:31], v[64:67], v[194:197], v[28:31]
	v_mfma_f32_16x16x32_bf16 v[28:31], v[68:71], v[198:201], v[28:31]
	v_mfma_f32_16x16x32_bf16 v[20:23], v[80:83], v[194:197], v[20:23]
	v_mfma_f32_16x16x32_bf16 v[20:23], v[116:119], v[198:201], v[20:23]
	v_mfma_f32_16x16x32_bf16 v[24:27], v[72:75], v[194:197], v[24:27]
	v_mfma_f32_16x16x32_bf16 v[24:27], v[76:79], v[198:201], v[24:27]
	v_mfma_f32_16x16x32_bf16 v[16:19], v[152:155], v[194:197], v[16:19]
	v_mfma_f32_16x16x32_bf16 v[16:19], v[156:159], v[198:201], v[16:19]
	v_mfma_f32_16x16x32_bf16 v[12:15], v[64:67], v[202:205], v[12:15]
	v_mfma_f32_16x16x32_bf16 v[12:15], v[68:71], v[206:209], v[12:15]
	v_mfma_f32_16x16x32_bf16 v[4:7], v[80:83], v[202:205], v[4:7]
	v_mfma_f32_16x16x32_bf16 v[4:7], v[116:119], v[206:209], v[4:7]
	v_mfma_f32_16x16x32_bf16 v[8:11], v[72:75], v[202:205], v[8:11]
	v_mfma_f32_16x16x32_bf16 v[8:11], v[76:79], v[206:209], v[8:11]
	v_mfma_f32_16x16x32_bf16 v[0:3], v[152:155], v[202:205], v[0:3]
	v_mfma_f32_16x16x32_bf16 v[0:3], v[156:159], v[206:209], v[0:3]
	s_barrier
	s_add_i32 s67, 0, 0x18000
	s_add_i32 s89, 0, 0x1c000
	v_add_u32_e32 v76, s67, v192
	v_add_u32_e32 v156, s89, v192
	ds_read_b128 v[64:67], v76
	ds_read_b128 v[68:71], v76 offset:1024
	ds_read_b128 v[72:75], v76 offset:2048
	ds_read_b128 v[76:79], v76 offset:3072
	ds_read_b128 v[80:83], v156
	ds_read_b128 v[116:119], v156 offset:1024
	ds_read_b128 v[152:155], v156 offset:2048
	ds_read_b128 v[156:159], v156 offset:3072
	s_add_u32 s86, s86, 0x80000
	s_addc_u32 s87, s87, 0
	s_mov_b32 m0, s34
	v_lshl_add_u64 v[218:219], s[86:87], 0, v[182:183]
	ds_read_b128 v[160:163], v193 offset:32768
	ds_read_b128 v[164:167], v193 offset:33792
	ds_read_b128 v[168:171], v193 offset:34816
	ds_read_b128 v[172:175], v193 offset:35840
	ds_read_b128 v[194:197], v193 offset:36864
	ds_read_b128 v[198:201], v193 offset:37888
	ds_read_b128 v[202:205], v193 offset:38912
	ds_read_b128 v[206:209], v193 offset:39936
	global_load_lds_dwordx4 v[218:219], off
	v_lshl_add_u64 v[218:219], s[86:87], 0, v[178:179]
	s_mov_b32 m0, s35
	s_nop 0
	global_load_lds_dwordx4 v[218:219], off
	s_waitcnt vmcnt(8)
	s_waitcnt lgkmcnt(0)
	s_barrier
	s_waitcnt lgkmcnt(0)
	v_mfma_f32_16x16x32_bf16 v[148:151], v[64:67], v[160:163], v[148:151]
	v_mfma_f32_16x16x32_bf16 v[148:151], v[68:71], v[164:167], v[148:151]
	v_mfma_f32_16x16x32_bf16 v[140:143], v[80:83], v[160:163], v[140:143]
	v_mfma_f32_16x16x32_bf16 v[140:143], v[116:119], v[164:167], v[140:143]
	v_mfma_f32_16x16x32_bf16 v[144:147], v[72:75], v[160:163], v[144:147]
	v_mfma_f32_16x16x32_bf16 v[144:147], v[76:79], v[164:167], v[144:147]
	v_mfma_f32_16x16x32_bf16 v[136:139], v[152:155], v[160:163], v[136:139]
	v_mfma_f32_16x16x32_bf16 v[136:139], v[156:159], v[164:167], v[136:139]
	v_mfma_f32_16x16x32_bf16 v[132:135], v[64:67], v[168:171], v[132:135]
	v_mfma_f32_16x16x32_bf16 v[132:135], v[68:71], v[172:175], v[132:135]
	v_mfma_f32_16x16x32_bf16 v[124:127], v[80:83], v[168:171], v[124:127]
	v_mfma_f32_16x16x32_bf16 v[124:127], v[116:119], v[172:175], v[124:127]
	v_mfma_f32_16x16x32_bf16 v[128:131], v[72:75], v[168:171], v[128:131]
	v_mfma_f32_16x16x32_bf16 v[128:131], v[76:79], v[172:175], v[128:131]
	v_mfma_f32_16x16x32_bf16 v[120:123], v[152:155], v[168:171], v[120:123]
	v_mfma_f32_16x16x32_bf16 v[120:123], v[156:159], v[172:175], v[120:123]
	v_mfma_f32_16x16x32_bf16 v[112:115], v[64:67], v[194:197], v[112:115]
	v_mfma_f32_16x16x32_bf16 v[112:115], v[68:71], v[198:201], v[112:115]
	v_mfma_f32_16x16x32_bf16 v[104:107], v[80:83], v[194:197], v[104:107]
	v_mfma_f32_16x16x32_bf16 v[104:107], v[116:119], v[198:201], v[104:107]
	v_mfma_f32_16x16x32_bf16 v[108:111], v[72:75], v[194:197], v[108:111]
	v_mfma_f32_16x16x32_bf16 v[108:111], v[76:79], v[198:201], v[108:111]
	v_mfma_f32_16x16x32_bf16 v[100:103], v[152:155], v[194:197], v[100:103]
	v_mfma_f32_16x16x32_bf16 v[100:103], v[156:159], v[198:201], v[100:103]
	v_mfma_f32_16x16x32_bf16 v[96:99], v[64:67], v[202:205], v[96:99]
	v_mfma_f32_16x16x32_bf16 v[96:99], v[68:71], v[206:209], v[96:99]
	v_mfma_f32_16x16x32_bf16 v[88:91], v[80:83], v[202:205], v[88:91]
	v_mfma_f32_16x16x32_bf16 v[88:91], v[116:119], v[206:209], v[88:91]
	v_mfma_f32_16x16x32_bf16 v[92:95], v[72:75], v[202:205], v[92:95]
	v_mfma_f32_16x16x32_bf16 v[92:95], v[76:79], v[206:209], v[92:95]
	v_mfma_f32_16x16x32_bf16 v[84:87], v[152:155], v[202:205], v[84:87]
	v_mfma_f32_16x16x32_bf16 v[84:87], v[156:159], v[206:209], v[84:87]
	s_barrier
	s_add_i32 s67, s67, s24
	v_lshl_add_u64 v[190:191], v[190:191], 0, s[30:31]
	s_mov_b32 m0, s67
	ds_read_b128 v[160:163], v193 offset:49152
	ds_read_b128 v[164:167], v193 offset:50176
	ds_read_b128 v[168:171], v193 offset:51200
	ds_read_b128 v[172:175], v193 offset:52224
	ds_read_b128 v[194:197], v193 offset:53248
	ds_read_b128 v[198:201], v193 offset:54272
	ds_read_b128 v[202:205], v193 offset:55296
	ds_read_b128 v[206:209], v193 offset:56320
	global_load_lds_dwordx4 v[190:191], off
	s_add_i32 m0, s67, 0x2000
	s_add_u32 s84, s84, 0x80080
	v_lshl_add_u64 v[190:191], v[210:211], 0, s[30:31]
	s_addc_u32 s85, s85, 0
	s_add_i32 s67, s89, s24
	global_load_lds_dwordx4 v[190:191], off
	v_lshl_add_u64 v[190:191], s[84:85], 0, v[180:181]
	s_mov_b32 m0, s67
	s_nop 0
	global_load_lds_dwordx4 v[190:191], off
	v_lshl_add_u64 v[190:191], s[84:85], 0, v[176:177]
	s_add_i32 m0, s67, 0x2000
	s_nop 0
	global_load_lds_dwordx4 v[190:191], off
	v_lshl_add_u64 v[190:191], v[212:213], 0, s[30:31]
	s_mov_b32 m0, s53
	s_nop 0
	global_load_lds_dwordx4 v[190:191], off
	v_lshl_add_u64 v[190:191], v[214:215], 0, s[30:31]
	s_mov_b32 m0, s54
	s_nop 0
	global_load_lds_dwordx4 v[190:191], off
	s_waitcnt vmcnt(8)
	s_waitcnt lgkmcnt(0)
	s_barrier
	s_waitcnt lgkmcnt(0)
	v_mfma_f32_16x16x32_bf16 v[60:63], v[64:67], v[160:163], v[60:63]
	v_mfma_f32_16x16x32_bf16 v[60:63], v[68:71], v[164:167], v[60:63]
	v_mfma_f32_16x16x32_bf16 v[52:55], v[80:83], v[160:163], v[52:55]
	v_mfma_f32_16x16x32_bf16 v[52:55], v[116:119], v[164:167], v[52:55]
	v_mfma_f32_16x16x32_bf16 v[56:59], v[72:75], v[160:163], v[56:59]
	v_mfma_f32_16x16x32_bf16 v[56:59], v[76:79], v[164:167], v[56:59]
	v_mfma_f32_16x16x32_bf16 v[48:51], v[152:155], v[160:163], v[48:51]
	v_mfma_f32_16x16x32_bf16 v[48:51], v[156:159], v[164:167], v[48:51]
	v_mfma_f32_16x16x32_bf16 v[44:47], v[64:67], v[168:171], v[44:47]
	v_mfma_f32_16x16x32_bf16 v[44:47], v[68:71], v[172:175], v[44:47]
	v_mfma_f32_16x16x32_bf16 v[36:39], v[80:83], v[168:171], v[36:39]
	v_mfma_f32_16x16x32_bf16 v[36:39], v[116:119], v[172:175], v[36:39]
	v_mfma_f32_16x16x32_bf16 v[40:43], v[72:75], v[168:171], v[40:43]
	v_mfma_f32_16x16x32_bf16 v[40:43], v[76:79], v[172:175], v[40:43]
	v_mfma_f32_16x16x32_bf16 v[32:35], v[152:155], v[168:171], v[32:35]
	v_mfma_f32_16x16x32_bf16 v[32:35], v[156:159], v[172:175], v[32:35]
	v_mfma_f32_16x16x32_bf16 v[28:31], v[64:67], v[194:197], v[28:31]
	v_mfma_f32_16x16x32_bf16 v[28:31], v[68:71], v[198:201], v[28:31]
	v_mfma_f32_16x16x32_bf16 v[20:23], v[80:83], v[194:197], v[20:23]
	v_mfma_f32_16x16x32_bf16 v[20:23], v[116:119], v[198:201], v[20:23]
	v_mfma_f32_16x16x32_bf16 v[24:27], v[72:75], v[194:197], v[24:27]
	v_mfma_f32_16x16x32_bf16 v[24:27], v[76:79], v[198:201], v[24:27]
	v_mfma_f32_16x16x32_bf16 v[16:19], v[152:155], v[194:197], v[16:19]
	v_mfma_f32_16x16x32_bf16 v[16:19], v[156:159], v[198:201], v[16:19]
	v_mfma_f32_16x16x32_bf16 v[12:15], v[64:67], v[202:205], v[12:15]
	v_mfma_f32_16x16x32_bf16 v[12:15], v[68:71], v[206:209], v[12:15]
	v_mfma_f32_16x16x32_bf16 v[4:7], v[80:83], v[202:205], v[4:7]
	v_mfma_f32_16x16x32_bf16 v[4:7], v[116:119], v[206:209], v[4:7]
	v_mfma_f32_16x16x32_bf16 v[8:11], v[72:75], v[202:205], v[8:11]
	v_mfma_f32_16x16x32_bf16 v[8:11], v[76:79], v[206:209], v[8:11]
	v_mfma_f32_16x16x32_bf16 v[0:3], v[152:155], v[202:205], v[0:3]
	v_mfma_f32_16x16x32_bf16 v[0:3], v[156:159], v[206:209], v[0:3]
	s_barrier
	s_add_i32 s88, s88, 2
	s_add_u32 s82, s82, 0x100
	s_addc_u32 s83, s83, 0
	s_add_u32 s75, s75, 0x100
	s_addc_u32 s81, s81, 0
	s_cmp_gt_u32 s88, 29
	s_cbranch_scc0 .LBB0_1190
	s_and_b64 vcc, exec, s[18:19]
	s_cbranch_vccz .LBB0_1193
	s_barrier

.LBB0_1289:
	s_lshl_b32 s80, s96, 8
	s_ashr_i32 s81, s80, 31
	s_lshl_b64 s[86:87], s[80:81], 2
	s_add_u32 s84, s84, s86
	s_addc_u32 s85, s85, s87
	s_add_i32 m0, s94, s41
	s_add_u32 s81, s82, 0x100
	global_load_lds_dwordx4 v239, s[84:85]
	s_addc_u32 s96, s83, 0
	s_cmp_eq_u32 s54, 5
	s_cselect_b32 vcc_lo, 66, -2
	s_bfe_u32 s86, s1, 0x20003
	s_cmp_eq_u32 s86, 3
	s_cselect_b32 s86, -8, 0
	s_cmp_eq_u32 s54, 5
	s_cselect_b32 s86, s86, 0
	s_add_i32 vcc_lo, vcc_lo, s86
	s_add_u32 s82, s78, 0x100
	s_addc_u32 s83, s79, 0
	s_add_i32 s94, 0, 0x10000
	s_cmpk_eq_i32 vcc_lo, 0x54
	s_cselect_b32 s87, s75, s83
	s_cselect_b32 s86, s74, s82
	s_cselect_b32 s85, s77, s96
	s_cselect_b32 s84, s76, s81
	s_add_i32 vcc_hi, 0, 0x14000
	v_add_u32_e32 v96, s94, v238
	v_add_u32_e32 v140, vcc_hi, v238
	ds_read_b128 v[64:67], v96
	ds_read_b128 v[72:75], v96 offset:1024
	ds_read_b128 v[88:91], v96 offset:2048
	ds_read_b128 v[96:99], v96 offset:3072
	ds_read_b128 v[108:111], v140
	ds_read_b128 v[116:119], v140 offset:1024
	ds_read_b128 v[128:131], v140 offset:2048
	ds_read_b128 v[140:143], v140 offset:3072
	v_lshl_add_u64 v[192:193], s[78:79], 0, v[230:231]
	s_add_i32 m0, s29, 0xc000
	ds_read_b128 v[152:155], v240
	ds_read_b128 v[156:159], v240 offset:1024
	ds_read_b128 v[160:163], v240 offset:2048
	ds_read_b128 v[164:167], v240 offset:3072
	ds_read_b128 v[168:171], v240 offset:4096
	ds_read_b128 v[180:183], v240 offset:5120
	ds_read_b128 v[184:187], v240 offset:6144
	ds_read_b128 v[188:191], v240 offset:7168
	global_load_lds_dwordx4 v[192:193], off
	v_lshl_add_u64 v[192:193], s[78:79], 0, v[232:233]
	s_add_i32 m0, s29, 0xe000
	s_nop 0
	global_load_lds_dwordx4 v[192:193], off
	s_waitcnt vmcnt(8)
	s_waitcnt lgkmcnt(0)
	s_barrier
	s_waitcnt lgkmcnt(0)
	v_mfma_f32_16x16x32_bf16 v[176:179], v[64:67], v[152:155], 0
	v_mfma_f32_16x16x32_bf16 v[176:179], v[72:75], v[156:159], v[176:179]
	v_mfma_f32_16x16x32_bf16 v[148:151], v[108:111], v[152:155], 0
	v_mfma_f32_16x16x32_bf16 v[148:151], v[116:119], v[156:159], v[148:151]
	v_mfma_f32_16x16x32_bf16 v[172:175], v[88:91], v[152:155], 0
	v_mfma_f32_16x16x32_bf16 v[172:175], v[96:99], v[156:159], v[172:175]
	v_mfma_f32_16x16x32_bf16 v[144:147], v[128:131], v[152:155], 0
	v_mfma_f32_16x16x32_bf16 v[144:147], v[140:143], v[156:159], v[144:147]
	v_mfma_f32_16x16x32_bf16 v[136:139], v[64:67], v[160:163], 0
	v_mfma_f32_16x16x32_bf16 v[136:139], v[72:75], v[164:167], v[136:139]
	v_mfma_f32_16x16x32_bf16 v[124:127], v[108:111], v[160:163], 0
	v_mfma_f32_16x16x32_bf16 v[124:127], v[116:119], v[164:167], v[124:127]
	v_mfma_f32_16x16x32_bf16 v[132:135], v[88:91], v[160:163], 0
	v_mfma_f32_16x16x32_bf16 v[132:135], v[96:99], v[164:167], v[132:135]
	v_mfma_f32_16x16x32_bf16 v[120:123], v[128:131], v[160:163], 0
	v_mfma_f32_16x16x32_bf16 v[120:123], v[140:143], v[164:167], v[120:123]
	v_mfma_f32_16x16x32_bf16 v[112:115], v[64:67], v[168:171], 0
	v_mfma_f32_16x16x32_bf16 v[112:115], v[72:75], v[180:183], v[112:115]
	v_mfma_f32_16x16x32_bf16 v[100:103], v[108:111], v[168:171], 0
	v_mfma_f32_16x16x32_bf16 v[100:103], v[116:119], v[180:183], v[100:103]
	v_mfma_f32_16x16x32_bf16 v[104:107], v[88:91], v[168:171], 0
	v_mfma_f32_16x16x32_bf16 v[104:107], v[96:99], v[180:183], v[104:107]
	v_mfma_f32_16x16x32_bf16 v[92:95], v[128:131], v[168:171], 0
	v_mfma_f32_16x16x32_bf16 v[92:95], v[140:143], v[180:183], v[92:95]
	v_mfma_f32_16x16x32_bf16 v[84:87], v[64:67], v[184:187], 0
	v_mfma_f32_16x16x32_bf16 v[84:87], v[72:75], v[188:191], v[84:87]
	v_mfma_f32_16x16x32_bf16 v[76:79], v[108:111], v[184:187], 0
	v_mfma_f32_16x16x32_bf16 v[76:79], v[116:119], v[188:191], v[76:79]
	v_mfma_f32_16x16x32_bf16 v[80:83], v[88:91], v[184:187], 0
	v_mfma_f32_16x16x32_bf16 v[80:83], v[96:99], v[188:191], v[80:83]
	v_mfma_f32_16x16x32_bf16 v[68:71], v[128:131], v[184:187], 0
	v_mfma_f32_16x16x32_bf16 v[68:71], v[140:143], v[188:191], v[68:71]
	s_barrier
	s_add_i32 s78, s94, s2
	v_lshl_add_u64 v[192:193], s[84:85], 0, v[216:217]
	s_mov_b32 m0, s78
	ds_read_b128 v[152:155], v240 offset:16384
	ds_read_b128 v[156:159], v240 offset:17408
	ds_read_b128 v[160:163], v240 offset:18432
	ds_read_b128 v[164:167], v240 offset:19456
	ds_read_b128 v[168:171], v240 offset:20480
	ds_read_b128 v[180:183], v240 offset:21504
	ds_read_b128 v[184:187], v240 offset:22528
	ds_read_b128 v[188:191], v240 offset:23552
	global_load_lds_dwordx4 v[192:193], off
	s_add_i32 m0, s78, 0x2000
	s_add_u32 s78, s84, 0x160000
	v_lshl_add_u64 v[194:195], s[84:85], 0, v[228:229]
	s_addc_u32 s79, s85, 0
	s_add_i32 s94, vcc_hi, s2
	global_load_lds_dwordx4 v[194:195], off
	v_lshl_add_u64 v[196:197], s[78:79], 0, v[216:217]
	s_mov_b32 m0, s94
	v_lshl_add_u64 v[198:199], s[86:87], 0, v[226:227]
	global_load_lds_dwordx4 v[196:197], off
	v_lshl_add_u64 v[196:197], s[78:79], 0, v[228:229]
	s_add_i32 m0, s94, 0x2000
	s_nop 0
	global_load_lds_dwordx4 v[196:197], off
	v_lshl_add_u64 v[196:197], s[86:87], 0, v[224:225]
	s_mov_b32 m0, s29
	s_nop 0
	global_load_lds_dwordx4 v[196:197], off
	s_mov_b32 m0, s34
	s_nop 0
	global_load_lds_dwordx4 v[198:199], off
	s_waitcnt vmcnt(8)
	s_waitcnt lgkmcnt(0)
	s_barrier
	s_waitcnt lgkmcnt(0)
	v_mfma_f32_16x16x32_bf16 v[60:63], v[64:67], v[152:155], 0
	v_mfma_f32_16x16x32_bf16 v[60:63], v[72:75], v[156:159], v[60:63]
	v_mfma_f32_16x16x32_bf16 v[52:55], v[108:111], v[152:155], 0
	v_mfma_f32_16x16x32_bf16 v[52:55], v[116:119], v[156:159], v[52:55]
	v_mfma_f32_16x16x32_bf16 v[56:59], v[88:91], v[152:155], 0
	v_mfma_f32_16x16x32_bf16 v[56:59], v[96:99], v[156:159], v[56:59]
	v_mfma_f32_16x16x32_bf16 v[48:51], v[128:131], v[152:155], 0
	v_mfma_f32_16x16x32_bf16 v[48:51], v[140:143], v[156:159], v[48:51]
	v_mfma_f32_16x16x32_bf16 v[44:47], v[64:67], v[160:163], 0
	v_mfma_f32_16x16x32_bf16 v[44:47], v[72:75], v[164:167], v[44:47]
	v_mfma_f32_16x16x32_bf16 v[36:39], v[108:111], v[160:163], 0
	v_mfma_f32_16x16x32_bf16 v[36:39], v[116:119], v[164:167], v[36:39]
	v_mfma_f32_16x16x32_bf16 v[40:43], v[88:91], v[160:163], 0
	v_mfma_f32_16x16x32_bf16 v[40:43], v[96:99], v[164:167], v[40:43]
	v_mfma_f32_16x16x32_bf16 v[32:35], v[128:131], v[160:163], 0
	v_mfma_f32_16x16x32_bf16 v[32:35], v[140:143], v[164:167], v[32:35]
	v_mfma_f32_16x16x32_bf16 v[28:31], v[64:67], v[168:171], 0
	v_mfma_f32_16x16x32_bf16 v[28:31], v[72:75], v[180:183], v[28:31]
	v_mfma_f32_16x16x32_bf16 v[20:23], v[108:111], v[168:171], 0
	v_mfma_f32_16x16x32_bf16 v[20:23], v[116:119], v[180:183], v[20:23]
	v_mfma_f32_16x16x32_bf16 v[24:27], v[88:91], v[168:171], 0
	v_mfma_f32_16x16x32_bf16 v[24:27], v[96:99], v[180:183], v[24:27]
	v_mfma_f32_16x16x32_bf16 v[16:19], v[128:131], v[168:171], 0
	v_mfma_f32_16x16x32_bf16 v[16:19], v[140:143], v[180:183], v[16:19]
	v_mfma_f32_16x16x32_bf16 v[12:15], v[64:67], v[184:187], 0
	v_mfma_f32_16x16x32_bf16 v[12:15], v[72:75], v[188:191], v[12:15]
	v_mfma_f32_16x16x32_bf16 v[4:7], v[108:111], v[184:187], 0
	v_mfma_f32_16x16x32_bf16 v[4:7], v[116:119], v[188:191], v[4:7]
	v_mfma_f32_16x16x32_bf16 v[8:11], v[88:91], v[184:187], 0
	v_mfma_f32_16x16x32_bf16 v[8:11], v[96:99], v[188:191], v[8:11]
	v_mfma_f32_16x16x32_bf16 v[0:3], v[128:131], v[184:187], 0
	v_mfma_f32_16x16x32_bf16 v[0:3], v[140:143], v[188:191], v[0:3]
	s_barrier
	s_add_i32 s94, 0, 0x18000
	s_add_i32 vcc_hi, 0, 0x1c000
	v_add_u32_e32 v96, s94, v238
	v_add_u32_e32 v140, vcc_hi, v238
	ds_read_b128 v[64:67], v96
	ds_read_b128 v[72:75], v96 offset:1024
	ds_read_b128 v[88:91], v96 offset:2048
	ds_read_b128 v[96:99], v96 offset:3072
	ds_read_b128 v[108:111], v140
	ds_read_b128 v[116:119], v140 offset:1024
	ds_read_b128 v[128:131], v140 offset:2048
	ds_read_b128 v[140:143], v140 offset:3072
	s_add_u32 s78, s86, 0x160000
	s_addc_u32 s79, s87, 0
	s_mov_b32 m0, s35
	v_lshl_add_u64 v[200:201], s[78:79], 0, v[224:225]
	ds_read_b128 v[152:155], v240 offset:32768
	ds_read_b128 v[156:159], v240 offset:33792
	ds_read_b128 v[160:163], v240 offset:34816
	ds_read_b128 v[164:167], v240 offset:35840
	ds_read_b128 v[168:171], v240 offset:36864
	ds_read_b128 v[180:183], v240 offset:37888
	ds_read_b128 v[184:187], v240 offset:38912
	ds_read_b128 v[188:191], v240 offset:39936
	global_load_lds_dwordx4 v[200:201], off
	v_lshl_add_u64 v[200:201], s[78:79], 0, v[226:227]
	s_mov_b32 m0, s38
	s_nop 0
	global_load_lds_dwordx4 v[200:201], off
	s_waitcnt vmcnt(8)
	s_waitcnt lgkmcnt(0)
	s_barrier
	s_waitcnt lgkmcnt(0)
	v_mfma_f32_16x16x32_bf16 v[176:179], v[64:67], v[152:155], v[176:179]
	v_mfma_f32_16x16x32_bf16 v[176:179], v[72:75], v[156:159], v[176:179]
	v_mfma_f32_16x16x32_bf16 v[148:151], v[108:111], v[152:155], v[148:151]
	v_mfma_f32_16x16x32_bf16 v[148:151], v[116:119], v[156:159], v[148:151]
	v_mfma_f32_16x16x32_bf16 v[172:175], v[88:91], v[152:155], v[172:175]
	v_mfma_f32_16x16x32_bf16 v[172:175], v[96:99], v[156:159], v[172:175]
	v_mfma_f32_16x16x32_bf16 v[144:147], v[128:131], v[152:155], v[144:147]
	v_mfma_f32_16x16x32_bf16 v[144:147], v[140:143], v[156:159], v[144:147]
	v_mfma_f32_16x16x32_bf16 v[136:139], v[64:67], v[160:163], v[136:139]
	v_mfma_f32_16x16x32_bf16 v[136:139], v[72:75], v[164:167], v[136:139]
	v_mfma_f32_16x16x32_bf16 v[124:127], v[108:111], v[160:163], v[124:127]
	v_mfma_f32_16x16x32_bf16 v[124:127], v[116:119], v[164:167], v[124:127]
	v_mfma_f32_16x16x32_bf16 v[132:135], v[88:91], v[160:163], v[132:135]
	v_mfma_f32_16x16x32_bf16 v[132:135], v[96:99], v[164:167], v[132:135]
	v_mfma_f32_16x16x32_bf16 v[120:123], v[128:131], v[160:163], v[120:123]
	v_mfma_f32_16x16x32_bf16 v[120:123], v[140:143], v[164:167], v[120:123]
	v_mfma_f32_16x16x32_bf16 v[112:115], v[64:67], v[168:171], v[112:115]
	v_mfma_f32_16x16x32_bf16 v[112:115], v[72:75], v[180:183], v[112:115]
	v_mfma_f32_16x16x32_bf16 v[100:103], v[108:111], v[168:171], v[100:103]
	v_mfma_f32_16x16x32_bf16 v[100:103], v[116:119], v[180:183], v[100:103]
	v_mfma_f32_16x16x32_bf16 v[104:107], v[88:91], v[168:171], v[104:107]
	v_mfma_f32_16x16x32_bf16 v[104:107], v[96:99], v[180:183], v[104:107]
	v_mfma_f32_16x16x32_bf16 v[92:95], v[128:131], v[168:171], v[92:95]
	v_mfma_f32_16x16x32_bf16 v[92:95], v[140:143], v[180:183], v[92:95]
	v_mfma_f32_16x16x32_bf16 v[84:87], v[64:67], v[184:187], v[84:87]
	v_mfma_f32_16x16x32_bf16 v[84:87], v[72:75], v[188:191], v[84:87]
	v_mfma_f32_16x16x32_bf16 v[76:79], v[108:111], v[184:187], v[76:79]
	v_mfma_f32_16x16x32_bf16 v[76:79], v[116:119], v[188:191], v[76:79]
	v_mfma_f32_16x16x32_bf16 v[80:83], v[88:91], v[184:187], v[80:83]
	v_mfma_f32_16x16x32_bf16 v[80:83], v[96:99], v[188:191], v[80:83]
	v_mfma_f32_16x16x32_bf16 v[68:71], v[128:131], v[184:187], v[68:71]
	v_mfma_f32_16x16x32_bf16 v[68:71], v[140:143], v[188:191], v[68:71]
	s_barrier
	s_add_i32 s78, s94, s2
	v_lshl_add_u64 v[192:193], v[192:193], 0, s[30:31]
	s_mov_b32 m0, s78
	ds_read_b128 v[152:155], v240 offset:49152
	ds_read_b128 v[156:159], v240 offset:50176
	ds_read_b128 v[160:163], v240 offset:51200
	ds_read_b128 v[164:167], v240 offset:52224
	ds_read_b128 v[168:171], v240 offset:53248
	ds_read_b128 v[180:183], v240 offset:54272
	ds_read_b128 v[184:187], v240 offset:55296
	ds_read_b128 v[188:191], v240 offset:56320
	global_load_lds_dwordx4 v[192:193], off
	s_add_i32 m0, s78, 0x2000
	s_add_u32 s78, s84, 0x160080
	v_lshl_add_u64 v[192:193], v[194:195], 0, s[30:31]
	s_addc_u32 s79, s85, 0
	s_add_i32 s84, vcc_hi, s2
	global_load_lds_dwordx4 v[192:193], off
	v_lshl_add_u64 v[192:193], s[78:79], 0, v[216:217]
	s_mov_b32 m0, s84
	s_nop 0
	global_load_lds_dwordx4 v[192:193], off
	v_lshl_add_u64 v[192:193], s[78:79], 0, v[228:229]
	s_add_i32 m0, s84, 0x2000
	s_nop 0
	global_load_lds_dwordx4 v[192:193], off
	v_lshl_add_u64 v[192:193], v[196:197], 0, s[30:31]
	s_mov_b32 m0, s60
	s_nop 0
	global_load_lds_dwordx4 v[192:193], off
	v_lshl_add_u64 v[192:193], v[198:199], 0, s[30:31]
	s_mov_b32 m0, s61
	s_nop 0
	global_load_lds_dwordx4 v[192:193], off
	s_waitcnt vmcnt(8)
	s_waitcnt lgkmcnt(0)
	s_barrier
	s_waitcnt lgkmcnt(0)
	v_mfma_f32_16x16x32_bf16 v[60:63], v[64:67], v[152:155], v[60:63]
	v_mfma_f32_16x16x32_bf16 v[60:63], v[72:75], v[156:159], v[60:63]
	v_mfma_f32_16x16x32_bf16 v[52:55], v[108:111], v[152:155], v[52:55]
	v_mfma_f32_16x16x32_bf16 v[52:55], v[116:119], v[156:159], v[52:55]
	v_mfma_f32_16x16x32_bf16 v[56:59], v[88:91], v[152:155], v[56:59]
	v_mfma_f32_16x16x32_bf16 v[56:59], v[96:99], v[156:159], v[56:59]
	v_mfma_f32_16x16x32_bf16 v[48:51], v[128:131], v[152:155], v[48:51]
	v_mfma_f32_16x16x32_bf16 v[48:51], v[140:143], v[156:159], v[48:51]
	v_mfma_f32_16x16x32_bf16 v[44:47], v[64:67], v[160:163], v[44:47]
	v_mfma_f32_16x16x32_bf16 v[44:47], v[72:75], v[164:167], v[44:47]
	v_mfma_f32_16x16x32_bf16 v[36:39], v[108:111], v[160:163], v[36:39]
	v_mfma_f32_16x16x32_bf16 v[36:39], v[116:119], v[164:167], v[36:39]
	v_mfma_f32_16x16x32_bf16 v[40:43], v[88:91], v[160:163], v[40:43]
	v_mfma_f32_16x16x32_bf16 v[40:43], v[96:99], v[164:167], v[40:43]
	v_mfma_f32_16x16x32_bf16 v[32:35], v[128:131], v[160:163], v[32:35]
	v_mfma_f32_16x16x32_bf16 v[32:35], v[140:143], v[164:167], v[32:35]
	v_mfma_f32_16x16x32_bf16 v[28:31], v[64:67], v[168:171], v[28:31]
	v_mfma_f32_16x16x32_bf16 v[28:31], v[72:75], v[180:183], v[28:31]
	v_mfma_f32_16x16x32_bf16 v[20:23], v[108:111], v[168:171], v[20:23]
	v_mfma_f32_16x16x32_bf16 v[20:23], v[116:119], v[180:183], v[20:23]
	v_mfma_f32_16x16x32_bf16 v[24:27], v[88:91], v[168:171], v[24:27]
	v_mfma_f32_16x16x32_bf16 v[24:27], v[96:99], v[180:183], v[24:27]
	v_mfma_f32_16x16x32_bf16 v[16:19], v[128:131], v[168:171], v[16:19]
	v_mfma_f32_16x16x32_bf16 v[16:19], v[140:143], v[180:183], v[16:19]
	v_mfma_f32_16x16x32_bf16 v[12:15], v[64:67], v[184:187], v[12:15]
	v_mfma_f32_16x16x32_bf16 v[12:15], v[72:75], v[188:191], v[12:15]
	v_mfma_f32_16x16x32_bf16 v[4:7], v[108:111], v[184:187], v[4:7]
	v_mfma_f32_16x16x32_bf16 v[4:7], v[116:119], v[188:191], v[4:7]
	v_mfma_f32_16x16x32_bf16 v[8:11], v[88:91], v[184:187], v[8:11]
	v_mfma_f32_16x16x32_bf16 v[8:11], v[96:99], v[188:191], v[8:11]
	v_mfma_f32_16x16x32_bf16 v[0:3], v[128:131], v[184:187], v[0:3]
	v_mfma_f32_16x16x32_bf16 v[0:3], v[140:143], v[188:191], v[0:3]
	s_barrier
	s_add_i32 vcc_lo, vcc_lo, 2
	s_add_u32 s81, s81, 0x100
	s_addc_u32 s96, s96, 0
	s_mov_b64 s[78:79], s[82:83]
.LBB0_1290:
	s_add_u32 s82, s78, 0x100
	s_addc_u32 s83, s79, 0
	s_add_i32 s94, 0, 0x10000
	s_cmpk_eq_i32 vcc_lo, 0x54
	s_cselect_b32 s87, s75, s83
	s_cselect_b32 s86, s74, s82
	s_cselect_b32 s85, s77, s96
	s_cselect_b32 s84, s76, s81
	s_add_i32 vcc_hi, 0, 0x14000
	v_add_u32_e32 v96, s94, v238
	v_add_u32_e32 v140, vcc_hi, v238
	ds_read_b128 v[64:67], v96
	ds_read_b128 v[72:75], v96 offset:1024
	ds_read_b128 v[88:91], v96 offset:2048
	ds_read_b128 v[96:99], v96 offset:3072
	ds_read_b128 v[108:111], v140
	ds_read_b128 v[116:119], v140 offset:1024
	ds_read_b128 v[128:131], v140 offset:2048
	ds_read_b128 v[140:143], v140 offset:3072
	v_lshl_add_u64 v[192:193], s[78:79], 0, v[230:231]
	s_add_i32 m0, s29, 0xc000
	ds_read_b128 v[152:155], v240
	ds_read_b128 v[156:159], v240 offset:1024
	ds_read_b128 v[160:163], v240 offset:2048
	ds_read_b128 v[164:167], v240 offset:3072
	ds_read_b128 v[168:171], v240 offset:4096
	ds_read_b128 v[180:183], v240 offset:5120
	ds_read_b128 v[184:187], v240 offset:6144
	ds_read_b128 v[188:191], v240 offset:7168
	global_load_lds_dwordx4 v[192:193], off
	v_lshl_add_u64 v[192:193], s[78:79], 0, v[232:233]
	s_add_i32 m0, s29, 0xe000
	s_nop 0
	global_load_lds_dwordx4 v[192:193], off
	s_waitcnt vmcnt(8)
	s_waitcnt lgkmcnt(0)
	s_barrier
	s_waitcnt lgkmcnt(0)
	v_mfma_f32_16x16x32_bf16 v[176:179], v[64:67], v[152:155], v[176:179]
	v_mfma_f32_16x16x32_bf16 v[176:179], v[72:75], v[156:159], v[176:179]
	v_mfma_f32_16x16x32_bf16 v[148:151], v[108:111], v[152:155], v[148:151]
	v_mfma_f32_16x16x32_bf16 v[148:151], v[116:119], v[156:159], v[148:151]
	v_mfma_f32_16x16x32_bf16 v[172:175], v[88:91], v[152:155], v[172:175]
	v_mfma_f32_16x16x32_bf16 v[172:175], v[96:99], v[156:159], v[172:175]
	v_mfma_f32_16x16x32_bf16 v[144:147], v[128:131], v[152:155], v[144:147]
	v_mfma_f32_16x16x32_bf16 v[144:147], v[140:143], v[156:159], v[144:147]
	v_mfma_f32_16x16x32_bf16 v[136:139], v[64:67], v[160:163], v[136:139]
	v_mfma_f32_16x16x32_bf16 v[136:139], v[72:75], v[164:167], v[136:139]
	v_mfma_f32_16x16x32_bf16 v[124:127], v[108:111], v[160:163], v[124:127]
	v_mfma_f32_16x16x32_bf16 v[124:127], v[116:119], v[164:167], v[124:127]
	v_mfma_f32_16x16x32_bf16 v[132:135], v[88:91], v[160:163], v[132:135]
	v_mfma_f32_16x16x32_bf16 v[132:135], v[96:99], v[164:167], v[132:135]
	v_mfma_f32_16x16x32_bf16 v[120:123], v[128:131], v[160:163], v[120:123]
	v_mfma_f32_16x16x32_bf16 v[120:123], v[140:143], v[164:167], v[120:123]
	v_mfma_f32_16x16x32_bf16 v[112:115], v[64:67], v[168:171], v[112:115]
	v_mfma_f32_16x16x32_bf16 v[112:115], v[72:75], v[180:183], v[112:115]
	v_mfma_f32_16x16x32_bf16 v[100:103], v[108:111], v[168:171], v[100:103]
	v_mfma_f32_16x16x32_bf16 v[100:103], v[116:119], v[180:183], v[100:103]
	v_mfma_f32_16x16x32_bf16 v[104:107], v[88:91], v[168:171], v[104:107]
	v_mfma_f32_16x16x32_bf16 v[104:107], v[96:99], v[180:183], v[104:107]
	v_mfma_f32_16x16x32_bf16 v[92:95], v[128:131], v[168:171], v[92:95]
	v_mfma_f32_16x16x32_bf16 v[92:95], v[140:143], v[180:183], v[92:95]
	v_mfma_f32_16x16x32_bf16 v[84:87], v[64:67], v[184:187], v[84:87]
	v_mfma_f32_16x16x32_bf16 v[84:87], v[72:75], v[188:191], v[84:87]
	v_mfma_f32_16x16x32_bf16 v[76:79], v[108:111], v[184:187], v[76:79]
	v_mfma_f32_16x16x32_bf16 v[76:79], v[116:119], v[188:191], v[76:79]
	v_mfma_f32_16x16x32_bf16 v[80:83], v[88:91], v[184:187], v[80:83]
	v_mfma_f32_16x16x32_bf16 v[80:83], v[96:99], v[188:191], v[80:83]
	v_mfma_f32_16x16x32_bf16 v[68:71], v[128:131], v[184:187], v[68:71]
	v_mfma_f32_16x16x32_bf16 v[68:71], v[140:143], v[188:191], v[68:71]
	s_barrier
	s_add_i32 s78, s94, s2
	v_lshl_add_u64 v[192:193], s[84:85], 0, v[216:217]
	s_mov_b32 m0, s78
	ds_read_b128 v[152:155], v240 offset:16384
	ds_read_b128 v[156:159], v240 offset:17408
	ds_read_b128 v[160:163], v240 offset:18432
	ds_read_b128 v[164:167], v240 offset:19456
	ds_read_b128 v[168:171], v240 offset:20480
	ds_read_b128 v[180:183], v240 offset:21504
	ds_read_b128 v[184:187], v240 offset:22528
	ds_read_b128 v[188:191], v240 offset:23552
	global_load_lds_dwordx4 v[192:193], off
	s_add_i32 m0, s78, 0x2000
	s_add_u32 s78, s84, 0x160000
	v_lshl_add_u64 v[194:195], s[84:85], 0, v[228:229]
	s_addc_u32 s79, s85, 0
	s_add_i32 s94, vcc_hi, s2
	global_load_lds_dwordx4 v[194:195], off
	v_lshl_add_u64 v[196:197], s[78:79], 0, v[216:217]
	s_mov_b32 m0, s94
	v_lshl_add_u64 v[198:199], s[86:87], 0, v[226:227]
	global_load_lds_dwordx4 v[196:197], off
	v_lshl_add_u64 v[196:197], s[78:79], 0, v[228:229]
	s_add_i32 m0, s94, 0x2000
	s_nop 0
	global_load_lds_dwordx4 v[196:197], off
	v_lshl_add_u64 v[196:197], s[86:87], 0, v[224:225]
	s_mov_b32 m0, s29
	s_nop 0
	global_load_lds_dwordx4 v[196:197], off
	s_mov_b32 m0, s34
	s_nop 0
	global_load_lds_dwordx4 v[198:199], off
	s_waitcnt vmcnt(8)
	s_waitcnt lgkmcnt(0)
	s_barrier
	s_waitcnt lgkmcnt(0)
	v_mfma_f32_16x16x32_bf16 v[60:63], v[64:67], v[152:155], v[60:63]
	v_mfma_f32_16x16x32_bf16 v[60:63], v[72:75], v[156:159], v[60:63]
	v_mfma_f32_16x16x32_bf16 v[52:55], v[108:111], v[152:155], v[52:55]
	v_mfma_f32_16x16x32_bf16 v[52:55], v[116:119], v[156:159], v[52:55]
	v_mfma_f32_16x16x32_bf16 v[56:59], v[88:91], v[152:155], v[56:59]
	v_mfma_f32_16x16x32_bf16 v[56:59], v[96:99], v[156:159], v[56:59]
	v_mfma_f32_16x16x32_bf16 v[48:51], v[128:131], v[152:155], v[48:51]
	v_mfma_f32_16x16x32_bf16 v[48:51], v[140:143], v[156:159], v[48:51]
	v_mfma_f32_16x16x32_bf16 v[44:47], v[64:67], v[160:163], v[44:47]
	v_mfma_f32_16x16x32_bf16 v[44:47], v[72:75], v[164:167], v[44:47]
	v_mfma_f32_16x16x32_bf16 v[36:39], v[108:111], v[160:163], v[36:39]
	v_mfma_f32_16x16x32_bf16 v[36:39], v[116:119], v[164:167], v[36:39]
	v_mfma_f32_16x16x32_bf16 v[40:43], v[88:91], v[160:163], v[40:43]
	v_mfma_f32_16x16x32_bf16 v[40:43], v[96:99], v[164:167], v[40:43]
	v_mfma_f32_16x16x32_bf16 v[32:35], v[128:131], v[160:163], v[32:35]
	v_mfma_f32_16x16x32_bf16 v[32:35], v[140:143], v[164:167], v[32:35]
	v_mfma_f32_16x16x32_bf16 v[28:31], v[64:67], v[168:171], v[28:31]
	v_mfma_f32_16x16x32_bf16 v[28:31], v[72:75], v[180:183], v[28:31]
	v_mfma_f32_16x16x32_bf16 v[20:23], v[108:111], v[168:171], v[20:23]
	v_mfma_f32_16x16x32_bf16 v[20:23], v[116:119], v[180:183], v[20:23]
	v_mfma_f32_16x16x32_bf16 v[24:27], v[88:91], v[168:171], v[24:27]
	v_mfma_f32_16x16x32_bf16 v[24:27], v[96:99], v[180:183], v[24:27]
	v_mfma_f32_16x16x32_bf16 v[16:19], v[128:131], v[168:171], v[16:19]
	v_mfma_f32_16x16x32_bf16 v[16:19], v[140:143], v[180:183], v[16:19]
	v_mfma_f32_16x16x32_bf16 v[12:15], v[64:67], v[184:187], v[12:15]
	v_mfma_f32_16x16x32_bf16 v[12:15], v[72:75], v[188:191], v[12:15]
	v_mfma_f32_16x16x32_bf16 v[4:7], v[108:111], v[184:187], v[4:7]
	v_mfma_f32_16x16x32_bf16 v[4:7], v[116:119], v[188:191], v[4:7]
	v_mfma_f32_16x16x32_bf16 v[8:11], v[88:91], v[184:187], v[8:11]
	v_mfma_f32_16x16x32_bf16 v[8:11], v[96:99], v[188:191], v[8:11]
	v_mfma_f32_16x16x32_bf16 v[0:3], v[128:131], v[184:187], v[0:3]
	v_mfma_f32_16x16x32_bf16 v[0:3], v[140:143], v[188:191], v[0:3]
	s_barrier
	s_add_i32 s94, 0, 0x18000
	s_add_i32 vcc_hi, 0, 0x1c000
	v_add_u32_e32 v96, s94, v238
	v_add_u32_e32 v140, vcc_hi, v238
	ds_read_b128 v[64:67], v96
	ds_read_b128 v[72:75], v96 offset:1024
	ds_read_b128 v[88:91], v96 offset:2048
	ds_read_b128 v[96:99], v96 offset:3072
	ds_read_b128 v[108:111], v140
	ds_read_b128 v[116:119], v140 offset:1024
	ds_read_b128 v[128:131], v140 offset:2048
	ds_read_b128 v[140:143], v140 offset:3072
	s_add_u32 s78, s86, 0x160000
	s_addc_u32 s79, s87, 0
	s_mov_b32 m0, s35
	v_lshl_add_u64 v[200:201], s[78:79], 0, v[224:225]
	ds_read_b128 v[152:155], v240 offset:32768
	ds_read_b128 v[156:159], v240 offset:33792
	ds_read_b128 v[160:163], v240 offset:34816
	ds_read_b128 v[164:167], v240 offset:35840
	ds_read_b128 v[168:171], v240 offset:36864
	ds_read_b128 v[180:183], v240 offset:37888
	ds_read_b128 v[184:187], v240 offset:38912
	ds_read_b128 v[188:191], v240 offset:39936
	global_load_lds_dwordx4 v[200:201], off
	v_lshl_add_u64 v[200:201], s[78:79], 0, v[226:227]
	s_mov_b32 m0, s38
	s_nop 0
	global_load_lds_dwordx4 v[200:201], off
	s_waitcnt vmcnt(8)
	s_waitcnt lgkmcnt(0)
	s_barrier
	s_waitcnt lgkmcnt(0)
	v_mfma_f32_16x16x32_bf16 v[176:179], v[64:67], v[152:155], v[176:179]
	v_mfma_f32_16x16x32_bf16 v[176:179], v[72:75], v[156:159], v[176:179]
	v_mfma_f32_16x16x32_bf16 v[148:151], v[108:111], v[152:155], v[148:151]
	v_mfma_f32_16x16x32_bf16 v[148:151], v[116:119], v[156:159], v[148:151]
	v_mfma_f32_16x16x32_bf16 v[172:175], v[88:91], v[152:155], v[172:175]
	v_mfma_f32_16x16x32_bf16 v[172:175], v[96:99], v[156:159], v[172:175]
	v_mfma_f32_16x16x32_bf16 v[144:147], v[128:131], v[152:155], v[144:147]
	v_mfma_f32_16x16x32_bf16 v[144:147], v[140:143], v[156:159], v[144:147]
	v_mfma_f32_16x16x32_bf16 v[136:139], v[64:67], v[160:163], v[136:139]
	v_mfma_f32_16x16x32_bf16 v[136:139], v[72:75], v[164:167], v[136:139]
	v_mfma_f32_16x16x32_bf16 v[124:127], v[108:111], v[160:163], v[124:127]
	v_mfma_f32_16x16x32_bf16 v[124:127], v[116:119], v[164:167], v[124:127]
	v_mfma_f32_16x16x32_bf16 v[132:135], v[88:91], v[160:163], v[132:135]
	v_mfma_f32_16x16x32_bf16 v[132:135], v[96:99], v[164:167], v[132:135]
	v_mfma_f32_16x16x32_bf16 v[120:123], v[128:131], v[160:163], v[120:123]
	v_mfma_f32_16x16x32_bf16 v[120:123], v[140:143], v[164:167], v[120:123]
	v_mfma_f32_16x16x32_bf16 v[112:115], v[64:67], v[168:171], v[112:115]
	v_mfma_f32_16x16x32_bf16 v[112:115], v[72:75], v[180:183], v[112:115]
	v_mfma_f32_16x16x32_bf16 v[100:103], v[108:111], v[168:171], v[100:103]
	v_mfma_f32_16x16x32_bf16 v[100:103], v[116:119], v[180:183], v[100:103]
	v_mfma_f32_16x16x32_bf16 v[104:107], v[88:91], v[168:171], v[104:107]
	v_mfma_f32_16x16x32_bf16 v[104:107], v[96:99], v[180:183], v[104:107]
	v_mfma_f32_16x16x32_bf16 v[92:95], v[128:131], v[168:171], v[92:95]
	v_mfma_f32_16x16x32_bf16 v[92:95], v[140:143], v[180:183], v[92:95]
	v_mfma_f32_16x16x32_bf16 v[84:87], v[64:67], v[184:187], v[84:87]
	v_mfma_f32_16x16x32_bf16 v[84:87], v[72:75], v[188:191], v[84:87]
	v_mfma_f32_16x16x32_bf16 v[76:79], v[108:111], v[184:187], v[76:79]
	v_mfma_f32_16x16x32_bf16 v[76:79], v[116:119], v[188:191], v[76:79]
	v_mfma_f32_16x16x32_bf16 v[80:83], v[88:91], v[184:187], v[80:83]
	v_mfma_f32_16x16x32_bf16 v[80:83], v[96:99], v[188:191], v[80:83]
	v_mfma_f32_16x16x32_bf16 v[68:71], v[128:131], v[184:187], v[68:71]
	v_mfma_f32_16x16x32_bf16 v[68:71], v[140:143], v[188:191], v[68:71]
	s_barrier
	s_add_i32 s78, s94, s2
	v_lshl_add_u64 v[192:193], v[192:193], 0, s[30:31]
	s_mov_b32 m0, s78
	ds_read_b128 v[152:155], v240 offset:49152
	ds_read_b128 v[156:159], v240 offset:50176
	ds_read_b128 v[160:163], v240 offset:51200
	ds_read_b128 v[164:167], v240 offset:52224
	ds_read_b128 v[168:171], v240 offset:53248
	ds_read_b128 v[180:183], v240 offset:54272
	ds_read_b128 v[184:187], v240 offset:55296
	ds_read_b128 v[188:191], v240 offset:56320
	global_load_lds_dwordx4 v[192:193], off
	s_add_i32 m0, s78, 0x2000
	s_add_u32 s78, s84, 0x160080
	v_lshl_add_u64 v[192:193], v[194:195], 0, s[30:31]
	s_addc_u32 s79, s85, 0
	s_add_i32 s84, vcc_hi, s2
	global_load_lds_dwordx4 v[192:193], off
	v_lshl_add_u64 v[192:193], s[78:79], 0, v[216:217]
	s_mov_b32 m0, s84
	s_nop 0
	global_load_lds_dwordx4 v[192:193], off
	v_lshl_add_u64 v[192:193], s[78:79], 0, v[228:229]
	s_add_i32 m0, s84, 0x2000
	s_nop 0
	global_load_lds_dwordx4 v[192:193], off
	v_lshl_add_u64 v[192:193], v[196:197], 0, s[30:31]
	s_mov_b32 m0, s60
	s_nop 0
	global_load_lds_dwordx4 v[192:193], off
	v_lshl_add_u64 v[192:193], v[198:199], 0, s[30:31]
	s_mov_b32 m0, s61
	s_nop 0
	global_load_lds_dwordx4 v[192:193], off
	s_waitcnt vmcnt(8)
	s_waitcnt lgkmcnt(0)
	s_barrier
	s_waitcnt lgkmcnt(0)
	v_mfma_f32_16x16x32_bf16 v[60:63], v[64:67], v[152:155], v[60:63]
	v_mfma_f32_16x16x32_bf16 v[60:63], v[72:75], v[156:159], v[60:63]
	v_mfma_f32_16x16x32_bf16 v[52:55], v[108:111], v[152:155], v[52:55]
	v_mfma_f32_16x16x32_bf16 v[52:55], v[116:119], v[156:159], v[52:55]
	v_mfma_f32_16x16x32_bf16 v[56:59], v[88:91], v[152:155], v[56:59]
	v_mfma_f32_16x16x32_bf16 v[56:59], v[96:99], v[156:159], v[56:59]
	v_mfma_f32_16x16x32_bf16 v[48:51], v[128:131], v[152:155], v[48:51]
	v_mfma_f32_16x16x32_bf16 v[48:51], v[140:143], v[156:159], v[48:51]
	v_mfma_f32_16x16x32_bf16 v[44:47], v[64:67], v[160:163], v[44:47]
	v_mfma_f32_16x16x32_bf16 v[44:47], v[72:75], v[164:167], v[44:47]
	v_mfma_f32_16x16x32_bf16 v[36:39], v[108:111], v[160:163], v[36:39]
	v_mfma_f32_16x16x32_bf16 v[36:39], v[116:119], v[164:167], v[36:39]
	v_mfma_f32_16x16x32_bf16 v[40:43], v[88:91], v[160:163], v[40:43]
	v_mfma_f32_16x16x32_bf16 v[40:43], v[96:99], v[164:167], v[40:43]
	v_mfma_f32_16x16x32_bf16 v[32:35], v[128:131], v[160:163], v[32:35]
	v_mfma_f32_16x16x32_bf16 v[32:35], v[140:143], v[164:167], v[32:35]
	v_mfma_f32_16x16x32_bf16 v[28:31], v[64:67], v[168:171], v[28:31]
	v_mfma_f32_16x16x32_bf16 v[28:31], v[72:75], v[180:183], v[28:31]
	v_mfma_f32_16x16x32_bf16 v[20:23], v[108:111], v[168:171], v[20:23]
	v_mfma_f32_16x16x32_bf16 v[20:23], v[116:119], v[180:183], v[20:23]
	v_mfma_f32_16x16x32_bf16 v[24:27], v[88:91], v[168:171], v[24:27]
	v_mfma_f32_16x16x32_bf16 v[24:27], v[96:99], v[180:183], v[24:27]
	v_mfma_f32_16x16x32_bf16 v[16:19], v[128:131], v[168:171], v[16:19]
	v_mfma_f32_16x16x32_bf16 v[16:19], v[140:143], v[180:183], v[16:19]
	v_mfma_f32_16x16x32_bf16 v[12:15], v[64:67], v[184:187], v[12:15]
	v_mfma_f32_16x16x32_bf16 v[12:15], v[72:75], v[188:191], v[12:15]
	v_mfma_f32_16x16x32_bf16 v[4:7], v[108:111], v[184:187], v[4:7]
	v_mfma_f32_16x16x32_bf16 v[4:7], v[116:119], v[188:191], v[4:7]
	v_mfma_f32_16x16x32_bf16 v[8:11], v[88:91], v[184:187], v[8:11]
	v_mfma_f32_16x16x32_bf16 v[8:11], v[96:99], v[188:191], v[8:11]
	v_mfma_f32_16x16x32_bf16 v[0:3], v[128:131], v[184:187], v[0:3]
	v_mfma_f32_16x16x32_bf16 v[0:3], v[140:143], v[188:191], v[0:3]
	s_barrier
	s_add_i32 vcc_lo, vcc_lo, 2
	s_add_u32 s81, s81, 0x100
	s_addc_u32 s96, s96, 0
	s_cmpk_gt_u32 vcc_lo, 0x55
	s_mov_b64 s[78:79], s[82:83]
	s_cbranch_scc0 .LBB0_1290
	s_and_b64 vcc, exec, s[70:71]
	s_cbranch_vccz .LBB0_1293
	s_barrier
